# all per-phase s_setprio flips removed from the GEMM K-loops (timing-only experiment)
# speedup vs baseline: 1.0043x; 1.0042x over previous
; #define PG8_STAGE(bufoff, gbase, voff) do { _Pragma("unroll") for (int _i = 0; _i < 2; ++_i) \
;     __builtin_amdgcn_global_load_lds((const unsigned*)((const char*)(gbase) + (voff)[_i]), (PG8_LAS unsigned*)(lds + (bufoff) + ldsw + _i * 8192), 16, 0, 0); } while (0)
; #define PG8_LDA(dst, b, h) do { _Pragma("unroll") for (int m = 0; m < 4; ++m) _Pragma("unroll") for (int k = 0; k < 2; ++k) dst[m][k] = *(const PG8_LAS bf16x8*)(lds + PG8_SA(b, h) + aoff + m * 2048 + k * 1024); } while (0)
; #define PG8_LDB(dst, b, h) do { _Pragma("unroll") for (int n = 0; n < 2; ++n) _Pragma("unroll") for (int k = 0; k < 2; ++k) dst[n][k] = *(const PG8_LAS bf16x8*)(lds + PG8_SB(b, h) + boff + n * 2048 + k * 1024); } while (0)
; #define PG8_MMA(ai, bj, At, Bt) do { __builtin_amdgcn_s_setprio(1); _Pragma("unroll") for (int m = 0; m < 4; ++m) _Pragma("unroll") for (int n = 0; n < 2; ++n) _Pragma("unroll") for (int k = 0; k < 2; ++k) \
;     acc[ai][bj][m][n] = __builtin_amdgcn_mfma_f32_16x16x32_bf16(Bt[n][k], At[m][k], acc[ai][bj][m][n], 0, 0, 0); __builtin_amdgcn_s_setprio(0); } while (0)
; #define PG8_WAIT_L(n) asm volatile("s_waitcnt lgkmcnt(" #n ")" ::: "memory")
; #define PG8_BAR __builtin_amdgcn_s_barrier()
; #define PG8_SCHED __builtin_amdgcn_sched_barrier(0)
; template <class Epi, class Sched>
; __device__ __forceinline__ void gemm_phase(PG8_LAS unsigned char* lds, const int lda, const int ldb, const Sched& S, const Epi& E) {
;     ...
;     for (int t = 0; t < nt; t += 2) {
;       const bool last = (t == nt - 2);
;       const char* a1 = cA + (size_t)(t + 1) * kstep;
;       const char* a2 = last ? nA : cA + (size_t)(t + 2) * kstep; const char* b2 = last ? nB : cB + (size_t)(t + 2) * kstep;
;       const char* a3 = a2 + kstep; const char* b3 = b2 + kstep;
;       PG8_LDB(B0, 0, 0); PG8_SCHED; PG8_LDA(At, 0, 0); PG8_STAGE(PG8_SA(1, 1), a1 + hstepA, voffA);
;       PG8_WAIT_L(8); PG8_BAR; PG8_WAIT_L(0); PG8_MMA(0, 0, At, B0); PG8_BAR; PG8_SCHED;
;       PG8_LDB(B1, 0, 1); PG8_STAGE(PG8_SB(0, 0), b2, voffB);
;       PG8_BAR; PG8_WAIT_L(0); PG8_MMA(0, 1, At, B1); PG8_BAR;
;       PG8_LDA(At, 0, 1); PG8_STAGE(PG8_SA(0, 0), a2, voffA);
;       PG8_BAR; PG8_WAIT_L(0); PG8_MMA(1, 0, At, B0); PG8_BAR; PG8_SCHED;
.LBB0_335:
	s_add_u32 s10, s8, 0xfffc0080
	s_addc_u32 s11, s9, -1
	s_add_i32 s31, 0, 0x10000
	v_add_u32_e32 v156, s31, v131
	ds_read_b128 v[144:147], v156
	ds_read_b128 v[148:151], v156 offset:1024
	ds_read_b128 v[152:155], v156 offset:2048
	ds_read_b128 v[200:203], v156 offset:3072
	s_cmp_eq_u32 s30, 12
	s_cselect_b32 s25, s17, s11
	s_cselect_b32 s24, s26, s10
	s_cselect_b32 s11, s15, s29
	s_cselect_b32 s10, s27, s28
	v_lshl_add_u64 v[156:157], s[8:9], 0, v[140:141]
	s_add_i32 m0, s40, 0xc000
	ds_read_b128 v[204:207], v172
	ds_read_b128 v[208:211], v172 offset:1024
	ds_read_b128 v[212:215], v172 offset:2048
	ds_read_b128 v[216:219], v172 offset:3072
	ds_read_b128 v[220:223], v172 offset:4096
	ds_read_b128 v[224:227], v172 offset:5120
	ds_read_b128 v[228:231], v172 offset:6144
	ds_read_b128 v[232:235], v172 offset:7168
	global_load_lds_dwordx4 v[156:157], off
	v_lshl_add_u64 v[156:157], s[8:9], 0, v[142:143]
	s_add_i32 m0, s40, 0xe000
	s_nop 0
	global_load_lds_dwordx4 v[156:157], off
	s_waitcnt lgkmcnt(8)
	s_barrier
	s_waitcnt lgkmcnt(0)
	v_mfma_f32_16x16x32_bf16 v[126:129], v[144:147], v[204:207], v[126:129]
	v_mfma_f32_16x16x32_bf16 v[122:125], v[152:155], v[204:207], v[122:125]
	v_mfma_f32_16x16x32_bf16 v[110:113], v[144:147], v[212:215], v[110:113]
	v_mfma_f32_16x16x32_bf16 v[106:109], v[152:155], v[212:215], v[106:109]
	v_mfma_f32_16x16x32_bf16 v[94:97], v[144:147], v[220:223], v[94:97]
	v_mfma_f32_16x16x32_bf16 v[90:93], v[152:155], v[220:223], v[90:93]
	v_mfma_f32_16x16x32_bf16 v[78:81], v[144:147], v[228:231], v[78:81]
	v_mfma_f32_16x16x32_bf16 v[74:77], v[152:155], v[228:231], v[74:77]
	v_mfma_f32_16x16x32_bf16 v[126:129], v[148:151], v[208:211], v[126:129]
	v_mfma_f32_16x16x32_bf16 v[122:125], v[200:203], v[208:211], v[122:125]
	v_mfma_f32_16x16x32_bf16 v[110:113], v[148:151], v[216:219], v[110:113]
	v_mfma_f32_16x16x32_bf16 v[106:109], v[200:203], v[216:219], v[106:109]
	v_mfma_f32_16x16x32_bf16 v[94:97], v[148:151], v[224:227], v[94:97]
	v_mfma_f32_16x16x32_bf16 v[90:93], v[200:203], v[224:227], v[90:93]
	v_mfma_f32_16x16x32_bf16 v[78:81], v[148:151], v[232:235], v[78:81]
	v_mfma_f32_16x16x32_bf16 v[74:77], v[200:203], v[232:235], v[74:77]
	s_barrier
	s_add_i32 s33, 0, 0x14000
	v_add_u32_e32 v156, s33, v131
	s_add_i32 s31, s31, s39
	ds_read_b128 v[236:239], v156
	ds_read_b128 v[240:243], v156 offset:1024
	ds_read_b128 v[244:247], v156 offset:2048
	ds_read_b128 v[248:251], v156 offset:3072
	v_lshl_add_u64 v[156:157], s[10:11], 0, v[134:135]
	s_mov_b32 m0, s31
	v_lshl_add_u64 v[174:175], s[10:11], 0, v[132:133]
	global_load_lds_dwordx4 v[156:157], off
	s_add_i32 m0, s31, 0x2000
	s_nop 0
	global_load_lds_dwordx4 v[174:175], off
	s_barrier
	s_waitcnt lgkmcnt(0)
	v_mfma_f32_16x16x32_bf16 v[118:121], v[236:239], v[204:207], v[118:121]
	v_mfma_f32_16x16x32_bf16 v[114:117], v[244:247], v[204:207], v[114:117]
	v_mfma_f32_16x16x32_bf16 v[102:105], v[236:239], v[212:215], v[102:105]
	v_mfma_f32_16x16x32_bf16 v[98:101], v[244:247], v[212:215], v[98:101]
	v_mfma_f32_16x16x32_bf16 v[86:89], v[236:239], v[220:223], v[86:89]
	v_mfma_f32_16x16x32_bf16 v[82:85], v[244:247], v[220:223], v[82:85]
	v_mfma_f32_16x16x32_bf16 v[70:73], v[236:239], v[228:231], v[70:73]
	v_mfma_f32_16x16x32_bf16 v[66:69], v[244:247], v[228:231], v[66:69]
	v_mfma_f32_16x16x32_bf16 v[118:121], v[240:243], v[208:211], v[118:121]
	v_mfma_f32_16x16x32_bf16 v[114:117], v[248:251], v[208:211], v[114:117]
	v_mfma_f32_16x16x32_bf16 v[102:105], v[240:243], v[216:219], v[102:105]
	v_mfma_f32_16x16x32_bf16 v[98:101], v[248:251], v[216:219], v[98:101]
	v_mfma_f32_16x16x32_bf16 v[86:89], v[240:243], v[224:227], v[86:89]
	v_mfma_f32_16x16x32_bf16 v[82:85], v[248:251], v[224:227], v[82:85]
	v_mfma_f32_16x16x32_bf16 v[70:73], v[240:243], v[232:235], v[70:73]
	v_mfma_f32_16x16x32_bf16 v[66:69], v[248:251], v[232:235], v[66:69]
	s_mov_b32 m0, s40
	v_lshl_add_u64 v[182:183], s[24:25], 0, v[134:135]
	s_barrier
	ds_read_b128 v[204:207], v172 offset:16384
	ds_read_b128 v[208:211], v172 offset:17408
	ds_read_b128 v[212:215], v172 offset:18432
	ds_read_b128 v[216:219], v172 offset:19456
	ds_read_b128 v[220:223], v172 offset:20480
	ds_read_b128 v[224:227], v172 offset:21504
	ds_read_b128 v[228:231], v172 offset:22528
	ds_read_b128 v[232:235], v172 offset:23552
	global_load_lds_dwordx4 v[182:183], off
	v_lshl_add_u64 v[184:185], s[24:25], 0, v[132:133]
	s_mov_b32 m0, s41
	s_nop 0
	global_load_lds_dwordx4 v[184:185], off
	s_barrier
	s_waitcnt lgkmcnt(0)
	v_mfma_f32_16x16x32_bf16 v[62:65], v[144:147], v[204:207], v[62:65]
	v_mfma_f32_16x16x32_bf16 v[58:61], v[152:155], v[204:207], v[58:61]
	v_mfma_f32_16x16x32_bf16 v[46:49], v[144:147], v[212:215], v[46:49]
	v_mfma_f32_16x16x32_bf16 v[42:45], v[152:155], v[212:215], v[42:45]
	v_mfma_f32_16x16x32_bf16 v[30:33], v[144:147], v[220:223], v[30:33]
	v_mfma_f32_16x16x32_bf16 v[26:29], v[152:155], v[220:223], v[26:29]
	v_mfma_f32_16x16x32_bf16 v[14:17], v[144:147], v[228:231], v[14:17]
	v_mfma_f32_16x16x32_bf16 v[10:13], v[152:155], v[228:231], v[10:13]
	v_mfma_f32_16x16x32_bf16 v[62:65], v[148:151], v[208:211], v[62:65]
	v_mfma_f32_16x16x32_bf16 v[58:61], v[200:203], v[208:211], v[58:61]
	v_mfma_f32_16x16x32_bf16 v[46:49], v[148:151], v[216:219], v[46:49]
	v_mfma_f32_16x16x32_bf16 v[42:45], v[200:203], v[216:219], v[42:45]
	v_mfma_f32_16x16x32_bf16 v[30:33], v[148:151], v[224:227], v[30:33]
	v_mfma_f32_16x16x32_bf16 v[26:29], v[200:203], v[224:227], v[26:29]
	v_mfma_f32_16x16x32_bf16 v[14:17], v[148:151], v[232:235], v[14:17]
	v_mfma_f32_16x16x32_bf16 v[10:13], v[200:203], v[232:235], v[10:13]
	s_barrier
; #define PG8_STAGE(bufoff, gbase, voff) do { _Pragma("unroll") for (int _i = 0; _i < 2; ++_i) \
;     __builtin_amdgcn_global_load_lds((const unsigned*)((const char*)(gbase) + (voff)[_i]), (PG8_LAS unsigned*)(lds + (bufoff) + ldsw + _i * 8192), 16, 0, 0); } while (0)
; #define PG8_LDA(dst, b, h) do { _Pragma("unroll") for (int m = 0; m < 4; ++m) _Pragma("unroll") for (int k = 0; k < 2; ++k) dst[m][k] = *(const PG8_LAS bf16x8*)(lds + PG8_SA(b, h) + aoff + m * 2048 + k * 1024); } while (0)
; #define PG8_LDB(dst, b, h) do { _Pragma("unroll") for (int n = 0; n < 2; ++n) _Pragma("unroll") for (int k = 0; k < 2; ++k) dst[n][k] = *(const PG8_LAS bf16x8*)(lds + PG8_SB(b, h) + boff + n * 2048 + k * 1024); } while (0)
; #define PG8_MMA(ai, bj, At, Bt) do { __builtin_amdgcn_s_setprio(1); _Pragma("unroll") for (int m = 0; m < 4; ++m) _Pragma("unroll") for (int n = 0; n < 2; ++n) _Pragma("unroll") for (int k = 0; k < 2; ++k) \
;     acc[ai][bj][m][n] = __builtin_amdgcn_mfma_f32_16x16x32_bf16(Bt[n][k], At[m][k], acc[ai][bj][m][n], 0, 0, 0); __builtin_amdgcn_s_setprio(0); } while (0)
; #define PG8_WAIT_V(n) asm volatile("s_waitcnt vmcnt(" #n ")" ::: "memory")
; #define PG8_WAIT_L(n) asm volatile("s_waitcnt lgkmcnt(" #n ")" ::: "memory")
; #define PG8_BAR __builtin_amdgcn_s_barrier()
; #define PG8_SCHED __builtin_amdgcn_sched_barrier(0)
; template <class Epi, class Sched>
; __device__ __forceinline__ void gemm_phase(PG8_LAS unsigned char* lds, const int lda, const int ldb, const Sched& S, const Epi& E) {
;     ...
;       PG8_STAGE(PG8_SB(0, 1), b2 + hstepB, voffB);
;       PG8_WAIT_V(6); PG8_BAR; PG8_MMA(1, 1, At, B1); PG8_BAR;
;       PG8_LDB(B0, 1, 0); PG8_SCHED; PG8_LDA(At, 1, 0); PG8_STAGE(PG8_SA(0, 1), a2 + hstepA, voffA);
;       PG8_WAIT_L(8); PG8_BAR; PG8_WAIT_L(0); PG8_MMA(0, 0, At, B0); PG8_BAR; PG8_SCHED;
;       PG8_LDB(B1, 1, 1); PG8_STAGE(PG8_SB(1, 0), b3, voffB);
;       PG8_BAR; PG8_WAIT_L(0); PG8_MMA(0, 1, At, B1); PG8_BAR;
;       PG8_LDA(At, 1, 1); PG8_STAGE(PG8_SA(1, 0), a3, voffA);
	s_add_u32 s34, s10, 0x40000
	s_addc_u32 s35, s11, 0
	s_add_i32 s31, s33, s39
	v_lshl_add_u64 v[144:145], s[34:35], 0, v[134:135]
	s_mov_b32 m0, s31
	s_nop 0
	global_load_lds_dwordx4 v[144:145], off
	v_lshl_add_u64 v[144:145], s[34:35], 0, v[132:133]
	s_add_i32 m0, s31, 0x2000
	s_nop 0
	global_load_lds_dwordx4 v[144:145], off
	s_waitcnt vmcnt(6)
	s_barrier
	v_mfma_f32_16x16x32_bf16 v[54:57], v[236:239], v[204:207], v[54:57]
	v_mfma_f32_16x16x32_bf16 v[50:53], v[244:247], v[204:207], v[50:53]
	v_mfma_f32_16x16x32_bf16 v[38:41], v[236:239], v[212:215], v[38:41]
	v_mfma_f32_16x16x32_bf16 v[34:37], v[244:247], v[212:215], v[34:37]
	v_mfma_f32_16x16x32_bf16 v[22:25], v[236:239], v[220:223], v[22:25]
	v_mfma_f32_16x16x32_bf16 v[18:21], v[244:247], v[220:223], v[18:21]
	v_mfma_f32_16x16x32_bf16 v[6:9], v[236:239], v[228:231], v[6:9]
	v_mfma_f32_16x16x32_bf16 v[2:5], v[244:247], v[228:231], v[2:5]
	v_mfma_f32_16x16x32_bf16 v[54:57], v[240:243], v[208:211], v[54:57]
	v_mfma_f32_16x16x32_bf16 v[50:53], v[248:251], v[208:211], v[50:53]
	v_mfma_f32_16x16x32_bf16 v[38:41], v[240:243], v[216:219], v[38:41]
	v_mfma_f32_16x16x32_bf16 v[34:37], v[248:251], v[216:219], v[34:37]
	v_mfma_f32_16x16x32_bf16 v[22:25], v[240:243], v[224:227], v[22:25]
	v_mfma_f32_16x16x32_bf16 v[18:21], v[248:251], v[224:227], v[18:21]
	v_mfma_f32_16x16x32_bf16 v[6:9], v[240:243], v[232:235], v[6:9]
	v_mfma_f32_16x16x32_bf16 v[2:5], v[248:251], v[232:235], v[2:5]
	s_add_i32 s31, 0, 0x18000
	v_add_u32_e32 v173, s31, v131
	s_barrier
	ds_read_b128 v[144:147], v173
	ds_read_b128 v[148:151], v173 offset:1024
	ds_read_b128 v[152:155], v173 offset:2048
	ds_read_b128 v[200:203], v173 offset:3072
	s_add_u32 s24, s24, 0x40000
	s_addc_u32 s25, s25, 0
	s_mov_b32 m0, s42
	v_lshl_add_u64 v[236:237], s[24:25], 0, v[134:135]
	ds_read_b128 v[204:207], v172 offset:32768
	ds_read_b128 v[208:211], v172 offset:33792
	ds_read_b128 v[212:215], v172 offset:34816
	ds_read_b128 v[216:219], v172 offset:35840
	ds_read_b128 v[220:223], v172 offset:36864
	ds_read_b128 v[224:227], v172 offset:37888
	ds_read_b128 v[228:231], v172 offset:38912
	ds_read_b128 v[232:235], v172 offset:39936
	global_load_lds_dwordx4 v[236:237], off
	v_lshl_add_u64 v[236:237], s[24:25], 0, v[132:133]
	s_mov_b32 m0, s43
	s_nop 0
	global_load_lds_dwordx4 v[236:237], off
	s_waitcnt lgkmcnt(8)
	s_barrier
	s_waitcnt lgkmcnt(0)
	v_mfma_f32_16x16x32_bf16 v[126:129], v[144:147], v[204:207], v[126:129]
	v_mfma_f32_16x16x32_bf16 v[122:125], v[152:155], v[204:207], v[122:125]
	v_mfma_f32_16x16x32_bf16 v[110:113], v[144:147], v[212:215], v[110:113]
	v_mfma_f32_16x16x32_bf16 v[106:109], v[152:155], v[212:215], v[106:109]
	v_mfma_f32_16x16x32_bf16 v[94:97], v[144:147], v[220:223], v[94:97]
	v_mfma_f32_16x16x32_bf16 v[90:93], v[152:155], v[220:223], v[90:93]
	v_mfma_f32_16x16x32_bf16 v[78:81], v[144:147], v[228:231], v[78:81]
	v_mfma_f32_16x16x32_bf16 v[74:77], v[152:155], v[228:231], v[74:77]
	v_mfma_f32_16x16x32_bf16 v[126:129], v[148:151], v[208:211], v[126:129]
	v_mfma_f32_16x16x32_bf16 v[122:125], v[200:203], v[208:211], v[122:125]
	v_mfma_f32_16x16x32_bf16 v[110:113], v[148:151], v[216:219], v[110:113]
	v_mfma_f32_16x16x32_bf16 v[106:109], v[200:203], v[216:219], v[106:109]
	v_mfma_f32_16x16x32_bf16 v[94:97], v[148:151], v[224:227], v[94:97]
	v_mfma_f32_16x16x32_bf16 v[90:93], v[200:203], v[224:227], v[90:93]
	v_mfma_f32_16x16x32_bf16 v[78:81], v[148:151], v[232:235], v[78:81]
	v_mfma_f32_16x16x32_bf16 v[74:77], v[200:203], v[232:235], v[74:77]
	s_barrier
	s_add_i32 s24, 0, 0x1c000
	s_add_i32 s25, s31, s39
	v_add_u32_e32 v173, s24, v131
	v_lshl_add_u64 v[156:157], v[156:157], 0, s[86:87]
	s_mov_b32 m0, s25
	ds_read_b128 v[236:239], v173
	ds_read_b128 v[240:243], v173 offset:1024
	ds_read_b128 v[244:247], v173 offset:2048
	ds_read_b128 v[248:251], v173 offset:3072
	global_load_lds_dwordx4 v[156:157], off
	v_lshl_add_u64 v[156:157], v[174:175], 0, s[86:87]
	s_add_i32 m0, s25, 0x2000
	s_nop 0
	global_load_lds_dwordx4 v[156:157], off
	s_barrier
	s_waitcnt lgkmcnt(0)
	v_mfma_f32_16x16x32_bf16 v[118:121], v[236:239], v[204:207], v[118:121]
	v_mfma_f32_16x16x32_bf16 v[114:117], v[244:247], v[204:207], v[114:117]
	v_mfma_f32_16x16x32_bf16 v[102:105], v[236:239], v[212:215], v[102:105]
	v_mfma_f32_16x16x32_bf16 v[98:101], v[244:247], v[212:215], v[98:101]
	v_mfma_f32_16x16x32_bf16 v[86:89], v[236:239], v[220:223], v[86:89]
	v_mfma_f32_16x16x32_bf16 v[82:85], v[244:247], v[220:223], v[82:85]
	v_mfma_f32_16x16x32_bf16 v[70:73], v[236:239], v[228:231], v[70:73]
	v_mfma_f32_16x16x32_bf16 v[66:69], v[244:247], v[228:231], v[66:69]
	v_mfma_f32_16x16x32_bf16 v[118:121], v[240:243], v[208:211], v[118:121]
	v_mfma_f32_16x16x32_bf16 v[114:117], v[248:251], v[208:211], v[114:117]
	v_mfma_f32_16x16x32_bf16 v[102:105], v[240:243], v[216:219], v[102:105]
	v_mfma_f32_16x16x32_bf16 v[98:101], v[248:251], v[216:219], v[98:101]
	v_mfma_f32_16x16x32_bf16 v[86:89], v[240:243], v[224:227], v[86:89]
	v_mfma_f32_16x16x32_bf16 v[82:85], v[248:251], v[224:227], v[82:85]
	v_mfma_f32_16x16x32_bf16 v[70:73], v[240:243], v[232:235], v[70:73]
	v_mfma_f32_16x16x32_bf16 v[66:69], v[248:251], v[232:235], v[66:69]
	s_mov_b32 m0, s45
	v_lshl_add_u64 v[156:157], v[182:183], 0, s[86:87]
	s_barrier
	ds_read_b128 v[204:207], v172 offset:49152
	ds_read_b128 v[208:211], v172 offset:50176
	ds_read_b128 v[212:215], v172 offset:51200
	ds_read_b128 v[216:219], v172 offset:52224
	ds_read_b128 v[220:223], v172 offset:53248
	ds_read_b128 v[224:227], v172 offset:54272
	ds_read_b128 v[228:231], v172 offset:55296
	ds_read_b128 v[232:235], v172 offset:56320
	global_load_lds_dwordx4 v[156:157], off
	v_lshl_add_u64 v[156:157], v[184:185], 0, s[86:87]
	s_mov_b32 m0, s46
	s_nop 0
	global_load_lds_dwordx4 v[156:157], off
	s_barrier
; #define PG8_STAGE(bufoff, gbase, voff) do { _Pragma("unroll") for (int _i = 0; _i < 2; ++_i) \
;     __builtin_amdgcn_global_load_lds((const unsigned*)((const char*)(gbase) + (voff)[_i]), (PG8_LAS unsigned*)(lds + (bufoff) + ldsw + _i * 8192), 16, 0, 0); } while (0)
; template <class Epi, class Sched>
; __device__ __forceinline__ void gemm_phase(PG8_LAS unsigned char* lds, const int lda, const int ldb, const Sched& S, const Epi& E) {
;     ...
;       PG8_BAR; PG8_WAIT_L(0); PG8_MMA(1, 0, At, B0); PG8_BAR; PG8_SCHED;
;       PG8_STAGE(PG8_SB(1, 1), b3 + hstepB, voffB);
;       PG8_WAIT_V(6); PG8_BAR; PG8_MMA(1, 1, At, B1); PG8_BAR;
;     }
;   __device__ __forceinline__ void operator()(const f32x4 (&acc)[2][2][4][2], const Unit& u, int wr, int wc, int fr, int fq) const {
; #pragma unroll
;     for (int ai = 0; ai < 2; ++ai)
; #pragma unroll
;       for (int m = 0; m < 4; ++m) {
;         const int r = u.pm * 256 + ai * 128 + wr * 64 + m * 16 + fr;
; #pragma unroll
;         for (int bj = 0; bj < 2; ++bj)
; #pragma unroll
;           for (int n = 0; n < 2; ++n) {
;             const f32x4 v = acc[ai][bj][m][n];
;             const int c = u.pn * 256 + bj * 128 + wc * 32 + n * 16 + 4 * fq;
;             if (u.pn < 7) {
;               uint2 w; w.x = pack2(v[0], v[1]); w.y = pack2(v[2], v[3]);
;               *reinterpret_cast<uint2*>(PB + (size_t)r * PBW + c) = w;
;             } else {
;               const int nn = c - 1792, part = nn >> 8, ch = nn & 255;
;               if (u.pn == 7 && bj == 0 && wc == 1 && n == 1) {
;                 *reinterpret_cast<float4*>(AB + (size_t)r * 16 + 4 * fq) = make_float4(v[0], v[1], v[2], v[3]);
;               } else {
;                 u16* d; int cstride;
;                 if (r < ML) { const int b = r >> 11, tt = r & 2047; d = FT + ((size_t)(b * 256)) * 4096 + part * 2048 + tt; cstride = 4096; }
;                 else { const int rc = r - ML, b = rc >> 8, tt = rc & 255; d = FTC + ((size_t)(b * 256)) * 512 + part * 256 + tt; cstride = 512; }
; #pragma unroll
;                 for (int e = 0; e < 4; ++e) d[(size_t)(ch + e) * cstride] = f2bf(v[e]);
;                 if (u.pn == 7 && bj == 0 && wc == 0) {
; #pragma unroll
;                   for (int e = 0; e < 4; ++e) {
;                     const int kc = n * 16 + 4 * fq + e;
;                     if (kc >= 1 && kc <= 16) d[(size_t)(64 - kc) * cstride] = f2bf(v[e]);
	s_waitcnt lgkmcnt(0)
	v_mfma_f32_16x16x32_bf16 v[62:65], v[144:147], v[204:207], v[62:65]
	v_mfma_f32_16x16x32_bf16 v[58:61], v[152:155], v[204:207], v[58:61]
	v_mfma_f32_16x16x32_bf16 v[46:49], v[144:147], v[212:215], v[46:49]
	v_mfma_f32_16x16x32_bf16 v[42:45], v[152:155], v[212:215], v[42:45]
	v_mfma_f32_16x16x32_bf16 v[30:33], v[144:147], v[220:223], v[30:33]
	v_mfma_f32_16x16x32_bf16 v[26:29], v[152:155], v[220:223], v[26:29]
	v_mfma_f32_16x16x32_bf16 v[14:17], v[144:147], v[228:231], v[14:17]
	v_mfma_f32_16x16x32_bf16 v[10:13], v[152:155], v[228:231], v[10:13]
	v_mfma_f32_16x16x32_bf16 v[62:65], v[148:151], v[208:211], v[62:65]
	v_mfma_f32_16x16x32_bf16 v[58:61], v[200:203], v[208:211], v[58:61]
	v_mfma_f32_16x16x32_bf16 v[46:49], v[148:151], v[216:219], v[46:49]
	v_mfma_f32_16x16x32_bf16 v[42:45], v[200:203], v[216:219], v[42:45]
	v_mfma_f32_16x16x32_bf16 v[30:33], v[148:151], v[224:227], v[30:33]
	v_mfma_f32_16x16x32_bf16 v[26:29], v[200:203], v[224:227], v[26:29]
	v_mfma_f32_16x16x32_bf16 v[14:17], v[148:151], v[232:235], v[14:17]
	v_mfma_f32_16x16x32_bf16 v[10:13], v[200:203], v[232:235], v[10:13]
	s_barrier
	s_add_u32 s10, s10, 0x40080
	s_addc_u32 s11, s11, 0
	s_add_i32 s24, s24, s39
	v_lshl_add_u64 v[144:145], s[10:11], 0, v[134:135]
	s_mov_b32 m0, s24
	s_nop 0
	global_load_lds_dwordx4 v[144:145], off
	v_lshl_add_u64 v[144:145], s[10:11], 0, v[132:133]
	s_add_i32 m0, s24, 0x2000
	s_nop 0
	global_load_lds_dwordx4 v[144:145], off
	s_waitcnt vmcnt(6)
	s_barrier
	v_mfma_f32_16x16x32_bf16 v[54:57], v[236:239], v[204:207], v[54:57]
	v_mfma_f32_16x16x32_bf16 v[50:53], v[244:247], v[204:207], v[50:53]
	v_mfma_f32_16x16x32_bf16 v[38:41], v[236:239], v[212:215], v[38:41]
	v_mfma_f32_16x16x32_bf16 v[34:37], v[244:247], v[212:215], v[34:37]
	v_mfma_f32_16x16x32_bf16 v[22:25], v[236:239], v[220:223], v[22:25]
	v_mfma_f32_16x16x32_bf16 v[18:21], v[244:247], v[220:223], v[18:21]
	v_mfma_f32_16x16x32_bf16 v[6:9], v[236:239], v[228:231], v[6:9]
	v_mfma_f32_16x16x32_bf16 v[2:5], v[244:247], v[228:231], v[2:5]
	v_mfma_f32_16x16x32_bf16 v[54:57], v[240:243], v[208:211], v[54:57]
	v_mfma_f32_16x16x32_bf16 v[50:53], v[248:251], v[208:211], v[50:53]
	v_mfma_f32_16x16x32_bf16 v[38:41], v[240:243], v[216:219], v[38:41]
	v_mfma_f32_16x16x32_bf16 v[34:37], v[248:251], v[216:219], v[34:37]
	v_mfma_f32_16x16x32_bf16 v[22:25], v[240:243], v[224:227], v[22:25]
	v_mfma_f32_16x16x32_bf16 v[18:21], v[248:251], v[224:227], v[18:21]
	v_mfma_f32_16x16x32_bf16 v[6:9], v[240:243], v[232:235], v[6:9]
	v_mfma_f32_16x16x32_bf16 v[2:5], v[248:251], v[232:235], v[2:5]
	s_add_i32 s30, s30, 2
	s_add_u32 s8, s8, 0x100
	s_addc_u32 s9, s9, 0
	s_add_u32 s28, s28, 0x100
	s_addc_u32 s29, s29, 0
	s_cmp_gt_u32 s30, 13
	s_barrier
	s_cbranch_scc0 .LBB0_335
	s_lshl_b32 s15, s2, 8
	s_add_i32 s15, s15, s44
	v_or_b32_e32 v152, s15, v1
	s_mov_b32 s2, 0xffff
	v_cmp_lt_i32_e64 s[10:11], s2, v152
	s_and_b32 s2, s15, 0xffffff00
	s_add_i32 s2, s2, 0xffff0000
	s_lshl_b64 s[28:29], s[2:3], 10
	s_ashr_i32 s2, s15, 3
	s_and_b32 s8, s2, 0xffffff00
	s_ashr_i32 s9, s8, 31
	s_lshl_b64 s[26:27], s[8:9], 13
	s_lshl_b32 s24, s48, 8
	s_cmp_gt_i32 s48, 6
	s_cselect_b64 s[30:31], -1, 0
	v_bitop3_b32 v146, s15, v186, v1 bitop3:0xc8
	v_bitop3_b32 v148, s15, v187, v1 bitop3:0xc8
	s_mov_b64 s[8:9], -1
	s_and_b64 vcc, exec, s[30:31]
	s_cbranch_vccz .LBB0_346
	s_and_saveexec_b64 s[8:9], s[10:11]
	s_xor_b64 s[8:9], exec, s[8:9]
	s_add_u32 s34, s54, s28
	s_addc_u32 s35, s55, s29
	s_or_saveexec_b64 s[8:9], s[8:9]
	s_add_i32 s2, s24, 0xfffff900
	v_mov_b64_e32 v[144:145], 0x200
	v_mov_b32_e32 v150, s2
	v_mov_b64_e32 v[154:155], s[34:35]
	v_mov_b64_e32 v[156:157], v[146:147]
	s_xor_b64 exec, exec, s[8:9]
	s_add_u32 s34, s69, s26
	s_addc_u32 s35, s52, s27
	s_lshl_b32 s2, s2, 3
	v_mov_b64_e32 v[144:145], 0x1000
	v_mov_b32_e32 v150, s2
	v_mov_b64_e32 v[154:155], s[34:35]
	v_mov_b64_e32 v[156:157], v[148:149]
	s_or_b64 exec, exec, s[8:9]
	v_ashrrev_i32_e32 v151, 31, v150
	v_lshl_add_u64 v[150:151], v[150:151], 1, v[154:155]
	v_lshlrev_b32_e32 v154, 1, v156
	v_mov_b32_e32 v155, v0
	v_mul_u32_u24_e32 v145, v144, v136
	v_lshl_add_u64 v[150:151], v[150:151], 0, v[154:155]
	v_lshlrev_b32_e32 v154, 1, v145
	v_cvt_pk_bf16_f32 v149, v126, s0
	v_lshl_add_u64 v[154:155], v[150:151], 0, v[154:155]
	v_mul_u32_u24_e32 v147, v144, v166
	global_store_short v[154:155], v149, off
	v_lshlrev_b32_e32 v154, 1, v147
	v_mov_b32_e32 v155, v0
	v_cvt_pk_bf16_f32 v145, v127, s0
	v_lshl_add_u64 v[154:155], v[150:151], 0, v[154:155]
	v_mul_u32_u24_e32 v153, v144, v167
	global_store_short v[154:155], v145, off
	v_lshlrev_b32_e32 v154, 1, v153
	v_mov_b32_e32 v155, v0
	s_cmp_lg_u32 s48, 7
	v_cvt_pk_bf16_f32 v147, v128, s0
	v_lshl_add_u64 v[154:155], v[150:151], 0, v[154:155]
	s_cselect_b64 s[8:9], -1, 0
	global_store_short v[154:155], v147, off
	v_mul_u32_u24_e32 v154, v144, v168
	s_xor_b64 s[34:35], s[12:13], -1
	v_lshlrev_b32_e32 v154, 1, v154
	v_mov_b32_e32 v155, v0
	s_or_b64 s[8:9], s[34:35], s[8:9]
	v_cvt_pk_bf16_f32 v153, v129, s0
	v_lshl_add_u64 v[154:155], v[150:151], 0, v[154:155]
	s_and_b64 vcc, exec, s[8:9]
	global_store_short v[154:155], v153, off
	s_cbranch_vccnz .LBB0_345
	s_and_saveexec_b64 s[8:9], s[4:5]
	s_cbranch_execz .LBB0_344
	v_mul_u32_u24_e32 v154, v144, v158
	v_lshlrev_b32_e32 v154, 1, v154
	v_mov_b32_e32 v155, v0
	v_lshl_add_u64 v[154:155], v[150:151], 0, v[154:155]
	global_store_short v[154:155], v149, off

; #define PG8_STAGE(bufoff, gbase, voff) do { _Pragma("unroll") for (int _i = 0; _i < 2; ++_i) \
;     __builtin_amdgcn_global_load_lds((const unsigned*)((const char*)(gbase) + (voff)[_i]), (PG8_LAS unsigned*)(lds + (bufoff) + ldsw + _i * 8192), 16, 0, 0); } while (0)
; #define PG8_LDA(dst, b, h) do { _Pragma("unroll") for (int m = 0; m < 4; ++m) _Pragma("unroll") for (int k = 0; k < 2; ++k) dst[m][k] = *(const PG8_LAS bf16x8*)(lds + PG8_SA(b, h) + aoff + m * 2048 + k * 1024); } while (0)
; #define PG8_LDB(dst, b, h) do { _Pragma("unroll") for (int n = 0; n < 2; ++n) _Pragma("unroll") for (int k = 0; k < 2; ++k) dst[n][k] = *(const PG8_LAS bf16x8*)(lds + PG8_SB(b, h) + boff + n * 2048 + k * 1024); } while (0)
; #define PG8_MMA(ai, bj, At, Bt) do { __builtin_amdgcn_s_setprio(1); _Pragma("unroll") for (int m = 0; m < 4; ++m) _Pragma("unroll") for (int n = 0; n < 2; ++n) _Pragma("unroll") for (int k = 0; k < 2; ++k) \
;     acc[ai][bj][m][n] = __builtin_amdgcn_mfma_f32_16x16x32_bf16(Bt[n][k], At[m][k], acc[ai][bj][m][n], 0, 0, 0); __builtin_amdgcn_s_setprio(0); } while (0)
; #define PG8_WAIT_L(n) asm volatile("s_waitcnt lgkmcnt(" #n ")" ::: "memory")
; #define PG8_BAR __builtin_amdgcn_s_barrier()
; #define PG8_SCHED __builtin_amdgcn_sched_barrier(0)
; template <class Epi, class Sched>
; __device__ __forceinline__ void gemm_phase(PG8_LAS unsigned char* lds, const int lda, const int ldb, const Sched& S, const Epi& E) {
;     ...
;     for (int t = 0; t < nt; t += 2) {
;       const bool last = (t == nt - 2);
;       const char* a1 = cA + (size_t)(t + 1) * kstep;
;       const char* a2 = last ? nA : cA + (size_t)(t + 2) * kstep; const char* b2 = last ? nB : cB + (size_t)(t + 2) * kstep;
;       const char* a3 = a2 + kstep; const char* b3 = b2 + kstep;
;       PG8_LDB(B0, 0, 0); PG8_SCHED; PG8_LDA(At, 0, 0); PG8_STAGE(PG8_SA(1, 1), a1 + hstepA, voffA);
;       PG8_WAIT_L(8); PG8_BAR; PG8_WAIT_L(0); PG8_MMA(0, 0, At, B0); PG8_BAR; PG8_SCHED;
;       PG8_LDB(B1, 0, 1); PG8_STAGE(PG8_SB(0, 0), b2, voffB);
;       PG8_BAR; PG8_WAIT_L(0); PG8_MMA(0, 1, At, B1); PG8_BAR;
;       PG8_LDA(At, 0, 1); PG8_STAGE(PG8_SA(0, 0), a2, voffA);
;       PG8_BAR; PG8_WAIT_L(0); PG8_MMA(1, 0, At, B0); PG8_BAR; PG8_SCHED;
.LBB0_685:
	s_add_u32 s12, s10, 0xfffc0080
	s_addc_u32 s13, s11, -1
	s_add_i32 s31, 0, 0x10000
	v_add_u32_e32 v156, s31, v131
	ds_read_b128 v[144:147], v156
	ds_read_b128 v[148:151], v156 offset:1024
	ds_read_b128 v[152:155], v156 offset:2048
	ds_read_b128 v[200:203], v156 offset:3072
	s_cmp_eq_u32 s30, 12
	s_cselect_b32 s25, s19, s13
	s_cselect_b32 s24, s26, s12
	s_cselect_b32 s13, s17, s29
	s_cselect_b32 s12, s27, s28
	v_lshl_add_u64 v[156:157], s[10:11], 0, v[140:141]
	s_add_i32 m0, s40, 0xc000
	ds_read_b128 v[204:207], v172
	ds_read_b128 v[208:211], v172 offset:1024
	ds_read_b128 v[212:215], v172 offset:2048
	ds_read_b128 v[216:219], v172 offset:3072
	ds_read_b128 v[220:223], v172 offset:4096
	ds_read_b128 v[224:227], v172 offset:5120
	ds_read_b128 v[228:231], v172 offset:6144
	ds_read_b128 v[232:235], v172 offset:7168
	global_load_lds_dwordx4 v[156:157], off
	v_lshl_add_u64 v[156:157], s[10:11], 0, v[142:143]
	s_add_i32 m0, s40, 0xe000
	s_nop 0
	global_load_lds_dwordx4 v[156:157], off
	s_waitcnt lgkmcnt(8)
	s_barrier
	s_waitcnt lgkmcnt(0)
	v_mfma_f32_16x16x32_bf16 v[126:129], v[144:147], v[204:207], v[126:129]
	v_mfma_f32_16x16x32_bf16 v[122:125], v[152:155], v[204:207], v[122:125]
	v_mfma_f32_16x16x32_bf16 v[110:113], v[144:147], v[212:215], v[110:113]
	v_mfma_f32_16x16x32_bf16 v[106:109], v[152:155], v[212:215], v[106:109]
	v_mfma_f32_16x16x32_bf16 v[94:97], v[144:147], v[220:223], v[94:97]
	v_mfma_f32_16x16x32_bf16 v[90:93], v[152:155], v[220:223], v[90:93]
	v_mfma_f32_16x16x32_bf16 v[78:81], v[144:147], v[228:231], v[78:81]
	v_mfma_f32_16x16x32_bf16 v[74:77], v[152:155], v[228:231], v[74:77]
	v_mfma_f32_16x16x32_bf16 v[126:129], v[148:151], v[208:211], v[126:129]
	v_mfma_f32_16x16x32_bf16 v[122:125], v[200:203], v[208:211], v[122:125]
	v_mfma_f32_16x16x32_bf16 v[110:113], v[148:151], v[216:219], v[110:113]
	v_mfma_f32_16x16x32_bf16 v[106:109], v[200:203], v[216:219], v[106:109]
	v_mfma_f32_16x16x32_bf16 v[94:97], v[148:151], v[224:227], v[94:97]
	v_mfma_f32_16x16x32_bf16 v[90:93], v[200:203], v[224:227], v[90:93]
	v_mfma_f32_16x16x32_bf16 v[78:81], v[148:151], v[232:235], v[78:81]
	v_mfma_f32_16x16x32_bf16 v[74:77], v[200:203], v[232:235], v[74:77]
	s_barrier
	s_add_i32 s33, 0, 0x14000
	v_add_u32_e32 v156, s33, v131
	s_add_i32 s31, s31, s39
	ds_read_b128 v[236:239], v156
	ds_read_b128 v[240:243], v156 offset:1024
	ds_read_b128 v[244:247], v156 offset:2048
	ds_read_b128 v[248:251], v156 offset:3072
	v_lshl_add_u64 v[156:157], s[12:13], 0, v[134:135]
	s_mov_b32 m0, s31
	v_lshl_add_u64 v[174:175], s[12:13], 0, v[132:133]
	global_load_lds_dwordx4 v[156:157], off
	s_add_i32 m0, s31, 0x2000
	s_nop 0
	global_load_lds_dwordx4 v[174:175], off
	s_barrier
	s_waitcnt lgkmcnt(0)
	v_mfma_f32_16x16x32_bf16 v[118:121], v[236:239], v[204:207], v[118:121]
	v_mfma_f32_16x16x32_bf16 v[114:117], v[244:247], v[204:207], v[114:117]
	v_mfma_f32_16x16x32_bf16 v[102:105], v[236:239], v[212:215], v[102:105]
	v_mfma_f32_16x16x32_bf16 v[98:101], v[244:247], v[212:215], v[98:101]
	v_mfma_f32_16x16x32_bf16 v[86:89], v[236:239], v[220:223], v[86:89]
	v_mfma_f32_16x16x32_bf16 v[82:85], v[244:247], v[220:223], v[82:85]
	v_mfma_f32_16x16x32_bf16 v[70:73], v[236:239], v[228:231], v[70:73]
	v_mfma_f32_16x16x32_bf16 v[66:69], v[244:247], v[228:231], v[66:69]
	v_mfma_f32_16x16x32_bf16 v[118:121], v[240:243], v[208:211], v[118:121]
	v_mfma_f32_16x16x32_bf16 v[114:117], v[248:251], v[208:211], v[114:117]
	v_mfma_f32_16x16x32_bf16 v[102:105], v[240:243], v[216:219], v[102:105]
	v_mfma_f32_16x16x32_bf16 v[98:101], v[248:251], v[216:219], v[98:101]
	v_mfma_f32_16x16x32_bf16 v[86:89], v[240:243], v[224:227], v[86:89]
	v_mfma_f32_16x16x32_bf16 v[82:85], v[248:251], v[224:227], v[82:85]
	v_mfma_f32_16x16x32_bf16 v[70:73], v[240:243], v[232:235], v[70:73]
	v_mfma_f32_16x16x32_bf16 v[66:69], v[248:251], v[232:235], v[66:69]
	s_mov_b32 m0, s40
	v_lshl_add_u64 v[182:183], s[24:25], 0, v[134:135]
	s_barrier
	ds_read_b128 v[204:207], v172 offset:16384
	ds_read_b128 v[208:211], v172 offset:17408
	ds_read_b128 v[212:215], v172 offset:18432
	ds_read_b128 v[216:219], v172 offset:19456
	ds_read_b128 v[220:223], v172 offset:20480
	ds_read_b128 v[224:227], v172 offset:21504
	ds_read_b128 v[228:231], v172 offset:22528
	ds_read_b128 v[232:235], v172 offset:23552
	global_load_lds_dwordx4 v[182:183], off
	v_lshl_add_u64 v[184:185], s[24:25], 0, v[132:133]
	s_mov_b32 m0, s41
	s_nop 0
	global_load_lds_dwordx4 v[184:185], off
	s_barrier
	s_waitcnt lgkmcnt(0)
	v_mfma_f32_16x16x32_bf16 v[62:65], v[144:147], v[204:207], v[62:65]
	v_mfma_f32_16x16x32_bf16 v[58:61], v[152:155], v[204:207], v[58:61]
	v_mfma_f32_16x16x32_bf16 v[46:49], v[144:147], v[212:215], v[46:49]
	v_mfma_f32_16x16x32_bf16 v[42:45], v[152:155], v[212:215], v[42:45]
	v_mfma_f32_16x16x32_bf16 v[30:33], v[144:147], v[220:223], v[30:33]
	v_mfma_f32_16x16x32_bf16 v[26:29], v[152:155], v[220:223], v[26:29]
	v_mfma_f32_16x16x32_bf16 v[14:17], v[144:147], v[228:231], v[14:17]
	v_mfma_f32_16x16x32_bf16 v[10:13], v[152:155], v[228:231], v[10:13]
	v_mfma_f32_16x16x32_bf16 v[62:65], v[148:151], v[208:211], v[62:65]
	v_mfma_f32_16x16x32_bf16 v[58:61], v[200:203], v[208:211], v[58:61]
	v_mfma_f32_16x16x32_bf16 v[46:49], v[148:151], v[216:219], v[46:49]
	v_mfma_f32_16x16x32_bf16 v[42:45], v[200:203], v[216:219], v[42:45]
	v_mfma_f32_16x16x32_bf16 v[30:33], v[148:151], v[224:227], v[30:33]
	v_mfma_f32_16x16x32_bf16 v[26:29], v[200:203], v[224:227], v[26:29]
	v_mfma_f32_16x16x32_bf16 v[14:17], v[148:151], v[232:235], v[14:17]
	v_mfma_f32_16x16x32_bf16 v[10:13], v[200:203], v[232:235], v[10:13]
	s_barrier
; #define PG8_STAGE(bufoff, gbase, voff) do { _Pragma("unroll") for (int _i = 0; _i < 2; ++_i) \
;     __builtin_amdgcn_global_load_lds((const unsigned*)((const char*)(gbase) + (voff)[_i]), (PG8_LAS unsigned*)(lds + (bufoff) + ldsw + _i * 8192), 16, 0, 0); } while (0)
; #define PG8_LDA(dst, b, h) do { _Pragma("unroll") for (int m = 0; m < 4; ++m) _Pragma("unroll") for (int k = 0; k < 2; ++k) dst[m][k] = *(const PG8_LAS bf16x8*)(lds + PG8_SA(b, h) + aoff + m * 2048 + k * 1024); } while (0)
; #define PG8_LDB(dst, b, h) do { _Pragma("unroll") for (int n = 0; n < 2; ++n) _Pragma("unroll") for (int k = 0; k < 2; ++k) dst[n][k] = *(const PG8_LAS bf16x8*)(lds + PG8_SB(b, h) + boff + n * 2048 + k * 1024); } while (0)
; #define PG8_MMA(ai, bj, At, Bt) do { __builtin_amdgcn_s_setprio(1); _Pragma("unroll") for (int m = 0; m < 4; ++m) _Pragma("unroll") for (int n = 0; n < 2; ++n) _Pragma("unroll") for (int k = 0; k < 2; ++k) \
;     acc[ai][bj][m][n] = __builtin_amdgcn_mfma_f32_16x16x32_bf16(Bt[n][k], At[m][k], acc[ai][bj][m][n], 0, 0, 0); __builtin_amdgcn_s_setprio(0); } while (0)
; #define PG8_WAIT_V(n) asm volatile("s_waitcnt vmcnt(" #n ")" ::: "memory")
; #define PG8_WAIT_L(n) asm volatile("s_waitcnt lgkmcnt(" #n ")" ::: "memory")
; #define PG8_BAR __builtin_amdgcn_s_barrier()
; #define PG8_SCHED __builtin_amdgcn_sched_barrier(0)
; template <class Epi, class Sched>
; __device__ __forceinline__ void gemm_phase(PG8_LAS unsigned char* lds, const int lda, const int ldb, const Sched& S, const Epi& E) {
;     ...
;       PG8_STAGE(PG8_SB(0, 1), b2 + hstepB, voffB);
;       PG8_WAIT_V(6); PG8_BAR; PG8_MMA(1, 1, At, B1); PG8_BAR;
;       PG8_LDB(B0, 1, 0); PG8_SCHED; PG8_LDA(At, 1, 0); PG8_STAGE(PG8_SA(0, 1), a2 + hstepA, voffA);
;       PG8_WAIT_L(8); PG8_BAR; PG8_WAIT_L(0); PG8_MMA(0, 0, At, B0); PG8_BAR; PG8_SCHED;
;       PG8_LDB(B1, 1, 1); PG8_STAGE(PG8_SB(1, 0), b3, voffB);
;       PG8_BAR; PG8_WAIT_L(0); PG8_MMA(0, 1, At, B1); PG8_BAR;
;       PG8_LDA(At, 1, 1); PG8_STAGE(PG8_SA(1, 0), a3, voffA);
	s_add_u32 s34, s12, 0x40000
	s_addc_u32 s35, s13, 0
	s_add_i32 s31, s33, s39
	v_lshl_add_u64 v[144:145], s[34:35], 0, v[134:135]
	s_mov_b32 m0, s31
	s_nop 0
	global_load_lds_dwordx4 v[144:145], off
	v_lshl_add_u64 v[144:145], s[34:35], 0, v[132:133]
	s_add_i32 m0, s31, 0x2000
	s_nop 0
	global_load_lds_dwordx4 v[144:145], off
	s_waitcnt vmcnt(6)
	s_barrier
	v_mfma_f32_16x16x32_bf16 v[54:57], v[236:239], v[204:207], v[54:57]
	v_mfma_f32_16x16x32_bf16 v[50:53], v[244:247], v[204:207], v[50:53]
	v_mfma_f32_16x16x32_bf16 v[38:41], v[236:239], v[212:215], v[38:41]
	v_mfma_f32_16x16x32_bf16 v[34:37], v[244:247], v[212:215], v[34:37]
	v_mfma_f32_16x16x32_bf16 v[22:25], v[236:239], v[220:223], v[22:25]
	v_mfma_f32_16x16x32_bf16 v[18:21], v[244:247], v[220:223], v[18:21]
	v_mfma_f32_16x16x32_bf16 v[6:9], v[236:239], v[228:231], v[6:9]
	v_mfma_f32_16x16x32_bf16 v[2:5], v[244:247], v[228:231], v[2:5]
	v_mfma_f32_16x16x32_bf16 v[54:57], v[240:243], v[208:211], v[54:57]
	v_mfma_f32_16x16x32_bf16 v[50:53], v[248:251], v[208:211], v[50:53]
	v_mfma_f32_16x16x32_bf16 v[38:41], v[240:243], v[216:219], v[38:41]
	v_mfma_f32_16x16x32_bf16 v[34:37], v[248:251], v[216:219], v[34:37]
	v_mfma_f32_16x16x32_bf16 v[22:25], v[240:243], v[224:227], v[22:25]
	v_mfma_f32_16x16x32_bf16 v[18:21], v[248:251], v[224:227], v[18:21]
	v_mfma_f32_16x16x32_bf16 v[6:9], v[240:243], v[232:235], v[6:9]
	v_mfma_f32_16x16x32_bf16 v[2:5], v[248:251], v[232:235], v[2:5]
	s_add_i32 s31, 0, 0x18000
	v_add_u32_e32 v173, s31, v131
	s_barrier
	ds_read_b128 v[144:147], v173
	ds_read_b128 v[148:151], v173 offset:1024
	ds_read_b128 v[152:155], v173 offset:2048
	ds_read_b128 v[200:203], v173 offset:3072
	s_add_u32 s24, s24, 0x40000
	s_addc_u32 s25, s25, 0
	s_mov_b32 m0, s42
	v_lshl_add_u64 v[236:237], s[24:25], 0, v[134:135]
	ds_read_b128 v[204:207], v172 offset:32768
	ds_read_b128 v[208:211], v172 offset:33792
	ds_read_b128 v[212:215], v172 offset:34816
	ds_read_b128 v[216:219], v172 offset:35840
	ds_read_b128 v[220:223], v172 offset:36864
	ds_read_b128 v[224:227], v172 offset:37888
	ds_read_b128 v[228:231], v172 offset:38912
	ds_read_b128 v[232:235], v172 offset:39936
	global_load_lds_dwordx4 v[236:237], off
	v_lshl_add_u64 v[236:237], s[24:25], 0, v[132:133]
	s_mov_b32 m0, s43
	s_nop 0
	global_load_lds_dwordx4 v[236:237], off
	s_waitcnt lgkmcnt(8)
	s_barrier
	s_waitcnt lgkmcnt(0)
	v_mfma_f32_16x16x32_bf16 v[126:129], v[144:147], v[204:207], v[126:129]
	v_mfma_f32_16x16x32_bf16 v[122:125], v[152:155], v[204:207], v[122:125]
	v_mfma_f32_16x16x32_bf16 v[110:113], v[144:147], v[212:215], v[110:113]
	v_mfma_f32_16x16x32_bf16 v[106:109], v[152:155], v[212:215], v[106:109]
	v_mfma_f32_16x16x32_bf16 v[94:97], v[144:147], v[220:223], v[94:97]
	v_mfma_f32_16x16x32_bf16 v[90:93], v[152:155], v[220:223], v[90:93]
	v_mfma_f32_16x16x32_bf16 v[78:81], v[144:147], v[228:231], v[78:81]
	v_mfma_f32_16x16x32_bf16 v[74:77], v[152:155], v[228:231], v[74:77]
	v_mfma_f32_16x16x32_bf16 v[126:129], v[148:151], v[208:211], v[126:129]
	v_mfma_f32_16x16x32_bf16 v[122:125], v[200:203], v[208:211], v[122:125]
	v_mfma_f32_16x16x32_bf16 v[110:113], v[148:151], v[216:219], v[110:113]
	v_mfma_f32_16x16x32_bf16 v[106:109], v[200:203], v[216:219], v[106:109]
	v_mfma_f32_16x16x32_bf16 v[94:97], v[148:151], v[224:227], v[94:97]
	v_mfma_f32_16x16x32_bf16 v[90:93], v[200:203], v[224:227], v[90:93]
	v_mfma_f32_16x16x32_bf16 v[78:81], v[148:151], v[232:235], v[78:81]
	v_mfma_f32_16x16x32_bf16 v[74:77], v[200:203], v[232:235], v[74:77]
	s_barrier
	s_add_i32 s24, 0, 0x1c000
	s_add_i32 s25, s31, s39
	v_add_u32_e32 v173, s24, v131
	v_lshl_add_u64 v[156:157], v[156:157], 0, s[86:87]
	s_mov_b32 m0, s25
	ds_read_b128 v[236:239], v173
	ds_read_b128 v[240:243], v173 offset:1024
	ds_read_b128 v[244:247], v173 offset:2048
	ds_read_b128 v[248:251], v173 offset:3072
	global_load_lds_dwordx4 v[156:157], off
	v_lshl_add_u64 v[156:157], v[174:175], 0, s[86:87]
	s_add_i32 m0, s25, 0x2000
	s_nop 0
	global_load_lds_dwordx4 v[156:157], off
	s_barrier
	s_waitcnt lgkmcnt(0)
	v_mfma_f32_16x16x32_bf16 v[118:121], v[236:239], v[204:207], v[118:121]
	v_mfma_f32_16x16x32_bf16 v[114:117], v[244:247], v[204:207], v[114:117]
	v_mfma_f32_16x16x32_bf16 v[102:105], v[236:239], v[212:215], v[102:105]
	v_mfma_f32_16x16x32_bf16 v[98:101], v[244:247], v[212:215], v[98:101]
	v_mfma_f32_16x16x32_bf16 v[86:89], v[236:239], v[220:223], v[86:89]
	v_mfma_f32_16x16x32_bf16 v[82:85], v[244:247], v[220:223], v[82:85]
	v_mfma_f32_16x16x32_bf16 v[70:73], v[236:239], v[228:231], v[70:73]
	v_mfma_f32_16x16x32_bf16 v[66:69], v[244:247], v[228:231], v[66:69]
	v_mfma_f32_16x16x32_bf16 v[118:121], v[240:243], v[208:211], v[118:121]
	v_mfma_f32_16x16x32_bf16 v[114:117], v[248:251], v[208:211], v[114:117]
	v_mfma_f32_16x16x32_bf16 v[102:105], v[240:243], v[216:219], v[102:105]
	v_mfma_f32_16x16x32_bf16 v[98:101], v[248:251], v[216:219], v[98:101]
	v_mfma_f32_16x16x32_bf16 v[86:89], v[240:243], v[224:227], v[86:89]
	v_mfma_f32_16x16x32_bf16 v[82:85], v[248:251], v[224:227], v[82:85]
	v_mfma_f32_16x16x32_bf16 v[70:73], v[240:243], v[232:235], v[70:73]
	v_mfma_f32_16x16x32_bf16 v[66:69], v[248:251], v[232:235], v[66:69]
	s_mov_b32 m0, s45
	v_lshl_add_u64 v[156:157], v[182:183], 0, s[86:87]
	s_barrier
	ds_read_b128 v[204:207], v172 offset:49152
	ds_read_b128 v[208:211], v172 offset:50176
	ds_read_b128 v[212:215], v172 offset:51200
	ds_read_b128 v[216:219], v172 offset:52224
	ds_read_b128 v[220:223], v172 offset:53248
	ds_read_b128 v[224:227], v172 offset:54272
	ds_read_b128 v[228:231], v172 offset:55296
	ds_read_b128 v[232:235], v172 offset:56320
	global_load_lds_dwordx4 v[156:157], off
	v_lshl_add_u64 v[156:157], v[184:185], 0, s[86:87]
	s_mov_b32 m0, s46
	s_nop 0
	global_load_lds_dwordx4 v[156:157], off
	s_barrier
; #define PG8_STAGE(bufoff, gbase, voff) do { _Pragma("unroll") for (int _i = 0; _i < 2; ++_i) \
;     __builtin_amdgcn_global_load_lds((const unsigned*)((const char*)(gbase) + (voff)[_i]), (PG8_LAS unsigned*)(lds + (bufoff) + ldsw + _i * 8192), 16, 0, 0); } while (0)
; #define PG8_WAIT_V(n) asm volatile("s_waitcnt vmcnt(" #n ")" ::: "memory")
; #define PG8_WAIT_L(n) asm volatile("s_waitcnt lgkmcnt(" #n ")" ::: "memory")
; #define PG8_BAR __builtin_amdgcn_s_barrier()
; #define PG8_SCHED __builtin_amdgcn_sched_barrier(0)
; template <class Epi, class Sched>
; __device__ __forceinline__ void gemm_phase(PG8_LAS unsigned char* lds, const int lda, const int ldb, const Sched& S, const Epi& E) {
;     ...
;       PG8_BAR; PG8_WAIT_L(0); PG8_MMA(1, 0, At, B0); PG8_BAR; PG8_SCHED;
;       PG8_STAGE(PG8_SB(1, 1), b3 + hstepB, voffB);
;       PG8_WAIT_V(6); PG8_BAR; PG8_MMA(1, 1, At, B1); PG8_BAR;
;     }
;   __device__ __forceinline__ void operator()(const f32x4 (&acc)[2][2][4][2], const Unit& u, int wr, int wc, int fr, int fq) const {
; #pragma unroll
;     for (int ai = 0; ai < 2; ++ai)
; #pragma unroll
;       for (int m = 0; m < 4; ++m) {
;         const int r = u.pm * 256 + ai * 128 + wr * 64 + m * 16 + fr;
; #pragma unroll
;         for (int bj = 0; bj < 2; ++bj)
; #pragma unroll
;           for (int n = 0; n < 2; ++n) {
;             const f32x4 v = acc[ai][bj][m][n];
;             const int c = u.pn * 256 + bj * 128 + wc * 32 + n * 16 + 4 * fq;
;             if (u.pn < 7) {
;               uint2 w; w.x = pack2(v[0], v[1]); w.y = pack2(v[2], v[3]);
;               *reinterpret_cast<uint2*>(PB + (size_t)r * PBW + c) = w;
;             } else {
;               const int nn = c - 1792, part = nn >> 8, ch = nn & 255;
;               if (u.pn == 7 && bj == 0 && wc == 1 && n == 1) {
;                 *reinterpret_cast<float4*>(AB + (size_t)r * 16 + 4 * fq) = make_float4(v[0], v[1], v[2], v[3]);
;               } else {
;                 u16* d; int cstride;
;                 if (r < ML) { const int b = r >> 11, tt = r & 2047; d = FT + ((size_t)(b * 256)) * 4096 + part * 2048 + tt; cstride = 4096; }
;                 else { const int rc = r - ML, b = rc >> 8, tt = rc & 255; d = FTC + ((size_t)(b * 256)) * 512 + part * 256 + tt; cstride = 512; }
; #pragma unroll
;                 for (int e = 0; e < 4; ++e) d[(size_t)(ch + e) * cstride] = f2bf(v[e]);
	s_waitcnt lgkmcnt(0)
	v_mfma_f32_16x16x32_bf16 v[62:65], v[144:147], v[204:207], v[62:65]
	v_mfma_f32_16x16x32_bf16 v[58:61], v[152:155], v[204:207], v[58:61]
	v_mfma_f32_16x16x32_bf16 v[46:49], v[144:147], v[212:215], v[46:49]
	v_mfma_f32_16x16x32_bf16 v[42:45], v[152:155], v[212:215], v[42:45]
	v_mfma_f32_16x16x32_bf16 v[30:33], v[144:147], v[220:223], v[30:33]
	v_mfma_f32_16x16x32_bf16 v[26:29], v[152:155], v[220:223], v[26:29]
	v_mfma_f32_16x16x32_bf16 v[14:17], v[144:147], v[228:231], v[14:17]
	v_mfma_f32_16x16x32_bf16 v[10:13], v[152:155], v[228:231], v[10:13]
	v_mfma_f32_16x16x32_bf16 v[62:65], v[148:151], v[208:211], v[62:65]
	v_mfma_f32_16x16x32_bf16 v[58:61], v[200:203], v[208:211], v[58:61]
	v_mfma_f32_16x16x32_bf16 v[46:49], v[148:151], v[216:219], v[46:49]
	v_mfma_f32_16x16x32_bf16 v[42:45], v[200:203], v[216:219], v[42:45]
	v_mfma_f32_16x16x32_bf16 v[30:33], v[148:151], v[224:227], v[30:33]
	v_mfma_f32_16x16x32_bf16 v[26:29], v[200:203], v[224:227], v[26:29]
	v_mfma_f32_16x16x32_bf16 v[14:17], v[148:151], v[232:235], v[14:17]
	v_mfma_f32_16x16x32_bf16 v[10:13], v[200:203], v[232:235], v[10:13]
	s_barrier
	s_add_u32 s12, s12, 0x40080
	s_addc_u32 s13, s13, 0
	s_add_i32 s24, s24, s39
	v_lshl_add_u64 v[144:145], s[12:13], 0, v[134:135]
	s_mov_b32 m0, s24
	s_nop 0
	global_load_lds_dwordx4 v[144:145], off
	v_lshl_add_u64 v[144:145], s[12:13], 0, v[132:133]
	s_add_i32 m0, s24, 0x2000
	s_nop 0
	global_load_lds_dwordx4 v[144:145], off
	s_waitcnt vmcnt(6)
	s_barrier
	v_mfma_f32_16x16x32_bf16 v[54:57], v[236:239], v[204:207], v[54:57]
	v_mfma_f32_16x16x32_bf16 v[50:53], v[244:247], v[204:207], v[50:53]
	v_mfma_f32_16x16x32_bf16 v[38:41], v[236:239], v[212:215], v[38:41]
	v_mfma_f32_16x16x32_bf16 v[34:37], v[244:247], v[212:215], v[34:37]
	v_mfma_f32_16x16x32_bf16 v[22:25], v[236:239], v[220:223], v[22:25]
	v_mfma_f32_16x16x32_bf16 v[18:21], v[244:247], v[220:223], v[18:21]
	v_mfma_f32_16x16x32_bf16 v[6:9], v[236:239], v[228:231], v[6:9]
	v_mfma_f32_16x16x32_bf16 v[2:5], v[244:247], v[228:231], v[2:5]
	v_mfma_f32_16x16x32_bf16 v[54:57], v[240:243], v[208:211], v[54:57]
	v_mfma_f32_16x16x32_bf16 v[50:53], v[248:251], v[208:211], v[50:53]
	v_mfma_f32_16x16x32_bf16 v[38:41], v[240:243], v[216:219], v[38:41]
	v_mfma_f32_16x16x32_bf16 v[34:37], v[248:251], v[216:219], v[34:37]
	v_mfma_f32_16x16x32_bf16 v[22:25], v[240:243], v[224:227], v[22:25]
	v_mfma_f32_16x16x32_bf16 v[18:21], v[248:251], v[224:227], v[18:21]
	v_mfma_f32_16x16x32_bf16 v[6:9], v[240:243], v[232:235], v[6:9]
	v_mfma_f32_16x16x32_bf16 v[2:5], v[248:251], v[232:235], v[2:5]
	s_add_i32 s30, s30, 2
	s_add_u32 s10, s10, 0x100
	s_addc_u32 s11, s11, 0
	s_add_u32 s28, s28, 0x100
	s_addc_u32 s29, s29, 0
	s_cmp_gt_u32 s30, 13
	s_barrier
	s_cbranch_scc0 .LBB0_685
	s_lshl_b32 s17, s2, 8
	s_add_i32 s17, s17, s44
	v_or_b32_e32 v152, s17, v1
	s_mov_b32 s2, 0xffff
	v_cmp_lt_i32_e64 s[12:13], s2, v152
	s_and_b32 s2, s17, 0xffffff00
	s_add_i32 s2, s2, 0xffff0000
	s_lshl_b64 s[28:29], s[2:3], 10
	s_ashr_i32 s2, s17, 3
	s_and_b32 s10, s2, 0xffffff00
	s_ashr_i32 s11, s10, 31
	s_lshl_b64 s[26:27], s[10:11], 13
	s_lshl_b32 s24, s48, 8
	s_cmp_gt_i32 s48, 6
	s_cselect_b64 s[30:31], -1, 0
	v_bitop3_b32 v146, s17, v186, v1 bitop3:0xc8
	v_bitop3_b32 v148, s17, v187, v1 bitop3:0xc8
	s_mov_b64 s[10:11], -1
	s_and_b64 vcc, exec, s[30:31]
	s_cbranch_vccz .LBB0_696
	s_and_saveexec_b64 s[10:11], s[12:13]
	s_xor_b64 s[10:11], exec, s[10:11]
	s_add_u32 s34, s54, s28
	s_addc_u32 s35, s55, s29
	s_or_saveexec_b64 s[10:11], s[10:11]
	s_add_i32 s2, s24, 0xfffff900
	v_mov_b64_e32 v[144:145], 0x200
	v_mov_b32_e32 v150, s2
	v_mov_b64_e32 v[154:155], s[34:35]
	v_mov_b64_e32 v[156:157], v[146:147]
	s_xor_b64 exec, exec, s[10:11]
	s_add_u32 s34, s69, s26
	s_addc_u32 s35, s52, s27
	s_lshl_b32 s2, s2, 3
	v_mov_b64_e32 v[144:145], 0x1000
	v_mov_b32_e32 v150, s2
	v_mov_b64_e32 v[154:155], s[34:35]
	v_mov_b64_e32 v[156:157], v[148:149]
	s_or_b64 exec, exec, s[10:11]
	v_ashrrev_i32_e32 v151, 31, v150
	v_lshl_add_u64 v[150:151], v[150:151], 1, v[154:155]
	v_lshlrev_b32_e32 v154, 1, v156
	v_mov_b32_e32 v155, v0
	v_mul_u32_u24_e32 v145, v144, v136
	v_lshl_add_u64 v[150:151], v[150:151], 0, v[154:155]
	v_lshlrev_b32_e32 v154, 1, v145
	v_cvt_pk_bf16_f32 v149, v126, s0
	v_lshl_add_u64 v[154:155], v[150:151], 0, v[154:155]
	v_mul_u32_u24_e32 v147, v144, v166
	global_store_short v[154:155], v149, off
	v_lshlrev_b32_e32 v154, 1, v147
	v_mov_b32_e32 v155, v0
	v_cvt_pk_bf16_f32 v145, v127, s0
	v_lshl_add_u64 v[154:155], v[150:151], 0, v[154:155]
	v_mul_u32_u24_e32 v153, v144, v167
	global_store_short v[154:155], v145, off
	v_lshlrev_b32_e32 v154, 1, v153
	v_mov_b32_e32 v155, v0
	s_cmp_lg_u32 s48, 7
	v_cvt_pk_bf16_f32 v147, v128, s0
	v_lshl_add_u64 v[154:155], v[150:151], 0, v[154:155]
	s_cselect_b64 s[10:11], -1, 0
	global_store_short v[154:155], v147, off
	v_mul_u32_u24_e32 v154, v144, v168
	s_xor_b64 s[34:35], s[14:15], -1
	v_lshlrev_b32_e32 v154, 1, v154
	v_mov_b32_e32 v155, v0
	s_or_b64 s[10:11], s[34:35], s[10:11]
	v_cvt_pk_bf16_f32 v153, v129, s0
	v_lshl_add_u64 v[154:155], v[150:151], 0, v[154:155]
	s_and_b64 vcc, exec, s[10:11]
	global_store_short v[154:155], v153, off
	s_cbranch_vccnz .LBB0_695
	s_and_saveexec_b64 s[10:11], s[4:5]
	s_cbranch_execz .LBB0_694
	v_mul_u32_u24_e32 v154, v144, v158
	v_lshlrev_b32_e32 v154, 1, v154
	v_mov_b32_e32 v155, v0
	v_lshl_add_u64 v[154:155], v[150:151], 0, v[154:155]
	global_store_short v[154:155], v149, off

; #define PG8_STAGE(bufoff, gbase, voff) do { _Pragma("unroll") for (int _i = 0; _i < 2; ++_i) \
;     __builtin_amdgcn_global_load_lds((const unsigned*)((const char*)(gbase) + (voff)[_i]), (PG8_LAS unsigned*)(lds + (bufoff) + ldsw + _i * 8192), 16, 0, 0); } while (0)
; #define PG8_LDA(dst, b, h) do { _Pragma("unroll") for (int m = 0; m < 4; ++m) _Pragma("unroll") for (int k = 0; k < 2; ++k) dst[m][k] = *(const PG8_LAS bf16x8*)(lds + PG8_SA(b, h) + aoff + m * 2048 + k * 1024); } while (0)
; #define PG8_LDB(dst, b, h) do { _Pragma("unroll") for (int n = 0; n < 2; ++n) _Pragma("unroll") for (int k = 0; k < 2; ++k) dst[n][k] = *(const PG8_LAS bf16x8*)(lds + PG8_SB(b, h) + boff + n * 2048 + k * 1024); } while (0)
; #define PG8_MMA(ai, bj, At, Bt) do { __builtin_amdgcn_s_setprio(1); _Pragma("unroll") for (int m = 0; m < 4; ++m) _Pragma("unroll") for (int n = 0; n < 2; ++n) _Pragma("unroll") for (int k = 0; k < 2; ++k) \
;     acc[ai][bj][m][n] = __builtin_amdgcn_mfma_f32_16x16x32_bf16(Bt[n][k], At[m][k], acc[ai][bj][m][n], 0, 0, 0); __builtin_amdgcn_s_setprio(0); } while (0)
; #define PG8_WAIT_L(n) asm volatile("s_waitcnt lgkmcnt(" #n ")" ::: "memory")
; #define PG8_BAR __builtin_amdgcn_s_barrier()
; #define PG8_SCHED __builtin_amdgcn_sched_barrier(0)
; template <class Epi, class Sched>
; __device__ __forceinline__ void gemm_phase(PG8_LAS unsigned char* lds, const int lda, const int ldb, const Sched& S, const Epi& E) {
;     ...
;     for (int t = 0; t < nt; t += 2) {
;       const bool last = (t == nt - 2);
;       const char* a1 = cA + (size_t)(t + 1) * kstep;
;       const char* a2 = last ? nA : cA + (size_t)(t + 2) * kstep; const char* b2 = last ? nB : cB + (size_t)(t + 2) * kstep;
;       const char* a3 = a2 + kstep; const char* b3 = b2 + kstep;
;       PG8_LDB(B0, 0, 0); PG8_SCHED; PG8_LDA(At, 0, 0); PG8_STAGE(PG8_SA(1, 1), a1 + hstepA, voffA);
;       PG8_WAIT_L(8); PG8_BAR; PG8_WAIT_L(0); PG8_MMA(0, 0, At, B0); PG8_BAR; PG8_SCHED;
;       PG8_LDB(B1, 0, 1); PG8_STAGE(PG8_SB(0, 0), b2, voffB);
;       PG8_BAR; PG8_WAIT_L(0); PG8_MMA(0, 1, At, B1); PG8_BAR;
;       PG8_LDA(At, 0, 1); PG8_STAGE(PG8_SA(0, 0), a2, voffA);
;       PG8_BAR; PG8_WAIT_L(0); PG8_MMA(1, 0, At, B0); PG8_BAR; PG8_SCHED;
.LBB0_1088:
	s_add_u32 s16, s14, 0xfff00080
	s_addc_u32 s17, s15, -1
	s_add_i32 s33, 0, 0x10000
	v_add_u32_e32 v145, s33, v1
	ds_read_b128 v[152:155], v145
	ds_read_b128 v[156:159], v145 offset:1024
	ds_read_b128 v[160:163], v145 offset:2048
	ds_read_b128 v[164:167], v145 offset:3072
	s_cmp_eq_u32 s34, 60
	s_cselect_b32 s19, s7, s17
	s_cselect_b32 s18, s13, s16
	s_cselect_b32 s17, s1, s31
	s_cselect_b32 s16, s29, s30
	v_lshl_add_u64 v[182:183], s[14:15], 0, v[140:141]
	s_add_i32 m0, s21, 0xc000
	ds_read_b128 v[168:171], v131
	ds_read_b128 v[172:175], v131 offset:1024
	ds_read_b128 v[200:203], v131 offset:2048
	ds_read_b128 v[204:207], v131 offset:3072
	ds_read_b128 v[208:211], v131 offset:4096
	ds_read_b128 v[212:215], v131 offset:5120
	ds_read_b128 v[216:219], v131 offset:6144
	ds_read_b128 v[220:223], v131 offset:7168
	global_load_lds_dwordx4 v[182:183], off
	v_lshl_add_u64 v[182:183], s[14:15], 0, v[142:143]
	s_add_i32 m0, s21, 0xe000
	s_nop 0
	global_load_lds_dwordx4 v[182:183], off
	s_waitcnt lgkmcnt(8)
	s_barrier
	s_waitcnt lgkmcnt(0)
	v_mfma_f32_16x16x32_bf16 v[126:129], v[152:155], v[168:171], v[126:129]
	v_mfma_f32_16x16x32_bf16 v[122:125], v[160:163], v[168:171], v[122:125]
	v_mfma_f32_16x16x32_bf16 v[118:121], v[152:155], v[200:203], v[118:121]
	v_mfma_f32_16x16x32_bf16 v[114:117], v[160:163], v[200:203], v[114:117]
	v_mfma_f32_16x16x32_bf16 v[102:105], v[152:155], v[208:211], v[102:105]
	v_mfma_f32_16x16x32_bf16 v[98:101], v[160:163], v[208:211], v[98:101]
	v_mfma_f32_16x16x32_bf16 v[86:89], v[152:155], v[216:219], v[86:89]
	v_mfma_f32_16x16x32_bf16 v[82:85], v[160:163], v[216:219], v[82:85]
	v_mfma_f32_16x16x32_bf16 v[126:129], v[156:159], v[172:175], v[126:129]
	v_mfma_f32_16x16x32_bf16 v[122:125], v[164:167], v[172:175], v[122:125]
	v_mfma_f32_16x16x32_bf16 v[118:121], v[156:159], v[204:207], v[118:121]
	v_mfma_f32_16x16x32_bf16 v[114:117], v[164:167], v[204:207], v[114:117]
	v_mfma_f32_16x16x32_bf16 v[102:105], v[156:159], v[212:215], v[102:105]
	v_mfma_f32_16x16x32_bf16 v[98:101], v[164:167], v[212:215], v[98:101]
	v_mfma_f32_16x16x32_bf16 v[86:89], v[156:159], v[220:223], v[86:89]
	v_mfma_f32_16x16x32_bf16 v[82:85], v[164:167], v[220:223], v[82:85]
	s_barrier
	s_add_i32 s35, 0, 0x14000
	s_add_i32 s33, s33, s20
	v_add_u32_e32 v145, s35, v1
	v_lshl_add_u64 v[182:183], s[16:17], 0, v[134:135]
	s_mov_b32 m0, s33
	ds_read_b128 v[224:227], v145
	ds_read_b128 v[228:231], v145 offset:1024
	ds_read_b128 v[232:235], v145 offset:2048
	ds_read_b128 v[236:239], v145 offset:3072
	global_load_lds_dwordx4 v[182:183], off
	v_lshl_add_u64 v[184:185], s[16:17], 0, v[132:133]
	s_add_i32 m0, s33, 0x2000
	s_nop 0
	global_load_lds_dwordx4 v[184:185], off
	s_barrier
	s_waitcnt lgkmcnt(0)
	v_mfma_f32_16x16x32_bf16 v[110:113], v[224:227], v[168:171], v[110:113]
	v_mfma_f32_16x16x32_bf16 v[106:109], v[232:235], v[168:171], v[106:109]
	v_mfma_f32_16x16x32_bf16 v[94:97], v[224:227], v[200:203], v[94:97]
	v_mfma_f32_16x16x32_bf16 v[90:93], v[232:235], v[200:203], v[90:93]
	v_mfma_f32_16x16x32_bf16 v[78:81], v[224:227], v[208:211], v[78:81]
	v_mfma_f32_16x16x32_bf16 v[74:77], v[232:235], v[208:211], v[74:77]
	v_mfma_f32_16x16x32_bf16 v[70:73], v[224:227], v[216:219], v[70:73]
	v_mfma_f32_16x16x32_bf16 v[66:69], v[232:235], v[216:219], v[66:69]
	v_mfma_f32_16x16x32_bf16 v[110:113], v[228:231], v[172:175], v[110:113]
	v_mfma_f32_16x16x32_bf16 v[106:109], v[236:239], v[172:175], v[106:109]
	v_mfma_f32_16x16x32_bf16 v[94:97], v[228:231], v[204:207], v[94:97]
	v_mfma_f32_16x16x32_bf16 v[90:93], v[236:239], v[204:207], v[90:93]
	v_mfma_f32_16x16x32_bf16 v[78:81], v[228:231], v[212:215], v[78:81]
	v_mfma_f32_16x16x32_bf16 v[74:77], v[236:239], v[212:215], v[74:77]
	v_mfma_f32_16x16x32_bf16 v[70:73], v[228:231], v[220:223], v[70:73]
	v_mfma_f32_16x16x32_bf16 v[66:69], v[236:239], v[220:223], v[66:69]
	s_mov_b32 m0, s21
	v_lshl_add_u64 v[240:241], s[18:19], 0, v[134:135]
	s_barrier
	ds_read_b128 v[168:171], v131 offset:16384
	ds_read_b128 v[172:175], v131 offset:17408
	ds_read_b128 v[200:203], v131 offset:18432
	ds_read_b128 v[204:207], v131 offset:19456
	ds_read_b128 v[208:211], v131 offset:20480
	ds_read_b128 v[212:215], v131 offset:21504
	ds_read_b128 v[216:219], v131 offset:22528
	ds_read_b128 v[220:223], v131 offset:23552
	global_load_lds_dwordx4 v[240:241], off
	v_lshl_add_u64 v[242:243], s[18:19], 0, v[132:133]
	s_mov_b32 m0, s22
	s_nop 0
	global_load_lds_dwordx4 v[242:243], off
	s_barrier
	s_waitcnt lgkmcnt(0)
	v_mfma_f32_16x16x32_bf16 v[62:65], v[152:155], v[168:171], v[62:65]
	v_mfma_f32_16x16x32_bf16 v[58:61], v[160:163], v[168:171], v[58:61]
	v_mfma_f32_16x16x32_bf16 v[54:57], v[152:155], v[200:203], v[54:57]
	v_mfma_f32_16x16x32_bf16 v[46:49], v[160:163], v[200:203], v[46:49]
	v_mfma_f32_16x16x32_bf16 v[38:41], v[152:155], v[208:211], v[38:41]
	v_mfma_f32_16x16x32_bf16 v[34:37], v[160:163], v[208:211], v[34:37]
	v_mfma_f32_16x16x32_bf16 v[22:25], v[152:155], v[216:219], v[22:25]
	v_mfma_f32_16x16x32_bf16 v[18:21], v[160:163], v[216:219], v[18:21]
	v_mfma_f32_16x16x32_bf16 v[62:65], v[156:159], v[172:175], v[62:65]
	v_mfma_f32_16x16x32_bf16 v[58:61], v[164:167], v[172:175], v[58:61]
	v_mfma_f32_16x16x32_bf16 v[54:57], v[156:159], v[204:207], v[54:57]
	v_mfma_f32_16x16x32_bf16 v[46:49], v[164:167], v[204:207], v[46:49]
	v_mfma_f32_16x16x32_bf16 v[38:41], v[156:159], v[212:215], v[38:41]
	v_mfma_f32_16x16x32_bf16 v[34:37], v[164:167], v[212:215], v[34:37]
	v_mfma_f32_16x16x32_bf16 v[22:25], v[156:159], v[220:223], v[22:25]
	v_mfma_f32_16x16x32_bf16 v[18:21], v[164:167], v[220:223], v[18:21]
	s_barrier
; #define PG8_STAGE(bufoff, gbase, voff) do { _Pragma("unroll") for (int _i = 0; _i < 2; ++_i) \
;     __builtin_amdgcn_global_load_lds((const unsigned*)((const char*)(gbase) + (voff)[_i]), (PG8_LAS unsigned*)(lds + (bufoff) + ldsw + _i * 8192), 16, 0, 0); } while (0)
; #define PG8_LDA(dst, b, h) do { _Pragma("unroll") for (int m = 0; m < 4; ++m) _Pragma("unroll") for (int k = 0; k < 2; ++k) dst[m][k] = *(const PG8_LAS bf16x8*)(lds + PG8_SA(b, h) + aoff + m * 2048 + k * 1024); } while (0)
; #define PG8_LDB(dst, b, h) do { _Pragma("unroll") for (int n = 0; n < 2; ++n) _Pragma("unroll") for (int k = 0; k < 2; ++k) dst[n][k] = *(const PG8_LAS bf16x8*)(lds + PG8_SB(b, h) + boff + n * 2048 + k * 1024); } while (0)
; #define PG8_MMA(ai, bj, At, Bt) do { __builtin_amdgcn_s_setprio(1); _Pragma("unroll") for (int m = 0; m < 4; ++m) _Pragma("unroll") for (int n = 0; n < 2; ++n) _Pragma("unroll") for (int k = 0; k < 2; ++k) \
;     acc[ai][bj][m][n] = __builtin_amdgcn_mfma_f32_16x16x32_bf16(Bt[n][k], At[m][k], acc[ai][bj][m][n], 0, 0, 0); __builtin_amdgcn_s_setprio(0); } while (0)
; #define PG8_WAIT_V(n) asm volatile("s_waitcnt vmcnt(" #n ")" ::: "memory")
; #define PG8_WAIT_L(n) asm volatile("s_waitcnt lgkmcnt(" #n ")" ::: "memory")
; #define PG8_BAR __builtin_amdgcn_s_barrier()
; #define PG8_SCHED __builtin_amdgcn_sched_barrier(0)
; template <class Epi, class Sched>
; __device__ __forceinline__ void gemm_phase(PG8_LAS unsigned char* lds, const int lda, const int ldb, const Sched& S, const Epi& E) {
;     ...
;       PG8_STAGE(PG8_SB(0, 1), b2 + hstepB, voffB);
;       PG8_WAIT_V(6); PG8_BAR; PG8_MMA(1, 1, At, B1); PG8_BAR;
;       PG8_LDB(B0, 1, 0); PG8_SCHED; PG8_LDA(At, 1, 0); PG8_STAGE(PG8_SA(0, 1), a2 + hstepA, voffA);
;       PG8_WAIT_L(8); PG8_BAR; PG8_WAIT_L(0); PG8_MMA(0, 0, At, B0); PG8_BAR; PG8_SCHED;
;       PG8_LDB(B1, 1, 1); PG8_STAGE(PG8_SB(1, 0), b3, voffB);
;       PG8_BAR; PG8_WAIT_L(0); PG8_MMA(0, 1, At, B1); PG8_BAR;
;       PG8_LDA(At, 1, 1); PG8_STAGE(PG8_SA(1, 0), a3, voffA);
	s_add_u32 s36, s16, 0x100000
	s_addc_u32 s37, s17, 0
	s_add_i32 s33, s35, s20
	v_lshl_add_u64 v[152:153], s[36:37], 0, v[134:135]
	s_mov_b32 m0, s33
	s_nop 0
	global_load_lds_dwordx4 v[152:153], off
	v_lshl_add_u64 v[152:153], s[36:37], 0, v[132:133]
	s_add_i32 m0, s33, 0x2000
	s_nop 0
	global_load_lds_dwordx4 v[152:153], off
	s_waitcnt vmcnt(6)
	s_barrier
	v_mfma_f32_16x16x32_bf16 v[50:53], v[224:227], v[168:171], v[50:53]
	v_mfma_f32_16x16x32_bf16 v[42:45], v[232:235], v[168:171], v[42:45]
	v_mfma_f32_16x16x32_bf16 v[30:33], v[224:227], v[200:203], v[30:33]
	v_mfma_f32_16x16x32_bf16 v[26:29], v[232:235], v[200:203], v[26:29]
	v_mfma_f32_16x16x32_bf16 v[14:17], v[224:227], v[208:211], v[14:17]
	v_mfma_f32_16x16x32_bf16 v[10:13], v[232:235], v[208:211], v[10:13]
	v_mfma_f32_16x16x32_bf16 v[6:9], v[224:227], v[216:219], v[6:9]
	v_mfma_f32_16x16x32_bf16 v[2:5], v[232:235], v[216:219], v[2:5]
	v_mfma_f32_16x16x32_bf16 v[50:53], v[228:231], v[172:175], v[50:53]
	v_mfma_f32_16x16x32_bf16 v[42:45], v[236:239], v[172:175], v[42:45]
	v_mfma_f32_16x16x32_bf16 v[30:33], v[228:231], v[204:207], v[30:33]
	v_mfma_f32_16x16x32_bf16 v[26:29], v[236:239], v[204:207], v[26:29]
	v_mfma_f32_16x16x32_bf16 v[14:17], v[228:231], v[212:215], v[14:17]
	v_mfma_f32_16x16x32_bf16 v[10:13], v[236:239], v[212:215], v[10:13]
	v_mfma_f32_16x16x32_bf16 v[6:9], v[228:231], v[220:223], v[6:9]
	v_mfma_f32_16x16x32_bf16 v[2:5], v[236:239], v[220:223], v[2:5]
	s_add_i32 s33, 0, 0x18000
	v_add_u32_e32 v145, s33, v1
	s_barrier
	ds_read_b128 v[152:155], v145
	ds_read_b128 v[156:159], v145 offset:1024
	ds_read_b128 v[160:163], v145 offset:2048
	ds_read_b128 v[164:167], v145 offset:3072
	s_add_u32 s18, s18, 0x100000
	s_addc_u32 s19, s19, 0
	s_mov_b32 m0, s23
	v_lshl_add_u64 v[224:225], s[18:19], 0, v[134:135]
	ds_read_b128 v[168:171], v131 offset:32768
	ds_read_b128 v[172:175], v131 offset:33792
	ds_read_b128 v[200:203], v131 offset:34816
	ds_read_b128 v[204:207], v131 offset:35840
	ds_read_b128 v[208:211], v131 offset:36864
	ds_read_b128 v[212:215], v131 offset:37888
	ds_read_b128 v[216:219], v131 offset:38912
	ds_read_b128 v[220:223], v131 offset:39936
	global_load_lds_dwordx4 v[224:225], off
	v_lshl_add_u64 v[224:225], s[18:19], 0, v[132:133]
	s_mov_b32 m0, s24
	s_nop 0
	global_load_lds_dwordx4 v[224:225], off
	s_waitcnt lgkmcnt(8)
	s_barrier
	s_waitcnt lgkmcnt(0)
	v_mfma_f32_16x16x32_bf16 v[126:129], v[152:155], v[168:171], v[126:129]
	v_mfma_f32_16x16x32_bf16 v[122:125], v[160:163], v[168:171], v[122:125]
	v_mfma_f32_16x16x32_bf16 v[118:121], v[152:155], v[200:203], v[118:121]
	v_mfma_f32_16x16x32_bf16 v[114:117], v[160:163], v[200:203], v[114:117]
	v_mfma_f32_16x16x32_bf16 v[102:105], v[152:155], v[208:211], v[102:105]
	v_mfma_f32_16x16x32_bf16 v[98:101], v[160:163], v[208:211], v[98:101]
	v_mfma_f32_16x16x32_bf16 v[86:89], v[152:155], v[216:219], v[86:89]
	v_mfma_f32_16x16x32_bf16 v[82:85], v[160:163], v[216:219], v[82:85]
	v_mfma_f32_16x16x32_bf16 v[126:129], v[156:159], v[172:175], v[126:129]
	v_mfma_f32_16x16x32_bf16 v[122:125], v[164:167], v[172:175], v[122:125]
	v_mfma_f32_16x16x32_bf16 v[118:121], v[156:159], v[204:207], v[118:121]
	v_mfma_f32_16x16x32_bf16 v[114:117], v[164:167], v[204:207], v[114:117]
	v_mfma_f32_16x16x32_bf16 v[102:105], v[156:159], v[212:215], v[102:105]
	v_mfma_f32_16x16x32_bf16 v[98:101], v[164:167], v[212:215], v[98:101]
	v_mfma_f32_16x16x32_bf16 v[86:89], v[156:159], v[220:223], v[86:89]
	v_mfma_f32_16x16x32_bf16 v[82:85], v[164:167], v[220:223], v[82:85]
	s_barrier
	s_add_i32 s18, 0, 0x1c000
	s_add_i32 s19, s33, s20
	v_add_u32_e32 v145, s18, v1
	v_lshl_add_u64 v[182:183], v[182:183], 0, s[86:87]
	s_mov_b32 m0, s19
	ds_read_b128 v[224:227], v145
	ds_read_b128 v[228:231], v145 offset:1024
	ds_read_b128 v[232:235], v145 offset:2048
	ds_read_b128 v[236:239], v145 offset:3072
	global_load_lds_dwordx4 v[182:183], off
	v_lshl_add_u64 v[182:183], v[184:185], 0, s[86:87]
	s_add_i32 m0, s19, 0x2000
	s_nop 0
	global_load_lds_dwordx4 v[182:183], off
	s_barrier
	s_waitcnt lgkmcnt(0)
	v_mfma_f32_16x16x32_bf16 v[110:113], v[224:227], v[168:171], v[110:113]
	v_mfma_f32_16x16x32_bf16 v[106:109], v[232:235], v[168:171], v[106:109]
	v_mfma_f32_16x16x32_bf16 v[94:97], v[224:227], v[200:203], v[94:97]
	v_mfma_f32_16x16x32_bf16 v[90:93], v[232:235], v[200:203], v[90:93]
	v_mfma_f32_16x16x32_bf16 v[78:81], v[224:227], v[208:211], v[78:81]
	v_mfma_f32_16x16x32_bf16 v[74:77], v[232:235], v[208:211], v[74:77]
	v_mfma_f32_16x16x32_bf16 v[70:73], v[224:227], v[216:219], v[70:73]
	v_mfma_f32_16x16x32_bf16 v[66:69], v[232:235], v[216:219], v[66:69]
	v_mfma_f32_16x16x32_bf16 v[110:113], v[228:231], v[172:175], v[110:113]
	v_mfma_f32_16x16x32_bf16 v[106:109], v[236:239], v[172:175], v[106:109]
	v_mfma_f32_16x16x32_bf16 v[94:97], v[228:231], v[204:207], v[94:97]
	v_mfma_f32_16x16x32_bf16 v[90:93], v[236:239], v[204:207], v[90:93]
	v_mfma_f32_16x16x32_bf16 v[78:81], v[228:231], v[212:215], v[78:81]
	v_mfma_f32_16x16x32_bf16 v[74:77], v[236:239], v[212:215], v[74:77]
	v_mfma_f32_16x16x32_bf16 v[70:73], v[228:231], v[220:223], v[70:73]
	v_mfma_f32_16x16x32_bf16 v[66:69], v[236:239], v[220:223], v[66:69]
	s_mov_b32 m0, s25
	v_lshl_add_u64 v[182:183], v[240:241], 0, s[86:87]
	s_barrier
	ds_read_b128 v[168:171], v131 offset:49152
	ds_read_b128 v[172:175], v131 offset:50176
	ds_read_b128 v[200:203], v131 offset:51200
	ds_read_b128 v[204:207], v131 offset:52224
	ds_read_b128 v[208:211], v131 offset:53248
	ds_read_b128 v[212:215], v131 offset:54272
	ds_read_b128 v[216:219], v131 offset:55296
	ds_read_b128 v[220:223], v131 offset:56320
	global_load_lds_dwordx4 v[182:183], off
	v_lshl_add_u64 v[182:183], v[242:243], 0, s[86:87]
	s_mov_b32 m0, s26
	s_nop 0
	global_load_lds_dwordx4 v[182:183], off
	s_barrier
; #define PG8_STAGE(bufoff, gbase, voff) do { _Pragma("unroll") for (int _i = 0; _i < 2; ++_i) \
;     __builtin_amdgcn_global_load_lds((const unsigned*)((const char*)(gbase) + (voff)[_i]), (PG8_LAS unsigned*)(lds + (bufoff) + ldsw + _i * 8192), 16, 0, 0); } while (0)
; #define PG8_MMA(ai, bj, At, Bt) do { __builtin_amdgcn_s_setprio(1); _Pragma("unroll") for (int m = 0; m < 4; ++m) _Pragma("unroll") for (int n = 0; n < 2; ++n) _Pragma("unroll") for (int k = 0; k < 2; ++k) \
;     acc[ai][bj][m][n] = __builtin_amdgcn_mfma_f32_16x16x32_bf16(Bt[n][k], At[m][k], acc[ai][bj][m][n], 0, 0, 0); __builtin_amdgcn_s_setprio(0); } while (0)
; #define PG8_WAIT_V(n) asm volatile("s_waitcnt vmcnt(" #n ")" ::: "memory")
; #define PG8_WAIT_L(n) asm volatile("s_waitcnt lgkmcnt(" #n ")" ::: "memory")
; #define PG8_BAR __builtin_amdgcn_s_barrier()
; #define PG8_SCHED __builtin_amdgcn_sched_barrier(0)
; template <class Epi, class Sched>
; __device__ __forceinline__ void gemm_phase(PG8_LAS unsigned char* lds, const int lda, const int ldb, const Sched& S, const Epi& E) {
;     ...
;       PG8_BAR; PG8_WAIT_L(0); PG8_MMA(1, 0, At, B0); PG8_BAR; PG8_SCHED;
;       PG8_STAGE(PG8_SB(1, 1), b3 + hstepB, voffB);
;       PG8_WAIT_V(6); PG8_BAR; PG8_MMA(1, 1, At, B1); PG8_BAR;
;     }
	s_waitcnt lgkmcnt(0)
	v_mfma_f32_16x16x32_bf16 v[62:65], v[152:155], v[168:171], v[62:65]
	v_mfma_f32_16x16x32_bf16 v[58:61], v[160:163], v[168:171], v[58:61]
	v_mfma_f32_16x16x32_bf16 v[54:57], v[152:155], v[200:203], v[54:57]
	v_mfma_f32_16x16x32_bf16 v[46:49], v[160:163], v[200:203], v[46:49]
	v_mfma_f32_16x16x32_bf16 v[38:41], v[152:155], v[208:211], v[38:41]
	v_mfma_f32_16x16x32_bf16 v[34:37], v[160:163], v[208:211], v[34:37]
	v_mfma_f32_16x16x32_bf16 v[22:25], v[152:155], v[216:219], v[22:25]
	v_mfma_f32_16x16x32_bf16 v[18:21], v[160:163], v[216:219], v[18:21]
	v_mfma_f32_16x16x32_bf16 v[62:65], v[156:159], v[172:175], v[62:65]
	v_mfma_f32_16x16x32_bf16 v[58:61], v[164:167], v[172:175], v[58:61]
	v_mfma_f32_16x16x32_bf16 v[54:57], v[156:159], v[204:207], v[54:57]
	v_mfma_f32_16x16x32_bf16 v[46:49], v[164:167], v[204:207], v[46:49]
	v_mfma_f32_16x16x32_bf16 v[38:41], v[156:159], v[212:215], v[38:41]
	v_mfma_f32_16x16x32_bf16 v[34:37], v[164:167], v[212:215], v[34:37]
	v_mfma_f32_16x16x32_bf16 v[22:25], v[156:159], v[220:223], v[22:25]
	v_mfma_f32_16x16x32_bf16 v[18:21], v[164:167], v[220:223], v[18:21]
	s_barrier
	s_add_u32 s16, s16, 0x100080
	s_addc_u32 s17, s17, 0
	s_add_i32 s18, s18, s20
	v_lshl_add_u64 v[152:153], s[16:17], 0, v[134:135]
	s_mov_b32 m0, s18
	s_nop 0
	global_load_lds_dwordx4 v[152:153], off
	v_lshl_add_u64 v[152:153], s[16:17], 0, v[132:133]
	s_add_i32 m0, s18, 0x2000
	s_nop 0
	global_load_lds_dwordx4 v[152:153], off
	s_waitcnt vmcnt(6)
	s_barrier
	v_mfma_f32_16x16x32_bf16 v[50:53], v[224:227], v[168:171], v[50:53]
	v_mfma_f32_16x16x32_bf16 v[42:45], v[232:235], v[168:171], v[42:45]
	v_mfma_f32_16x16x32_bf16 v[30:33], v[224:227], v[200:203], v[30:33]
	v_mfma_f32_16x16x32_bf16 v[26:29], v[232:235], v[200:203], v[26:29]
	v_mfma_f32_16x16x32_bf16 v[14:17], v[224:227], v[208:211], v[14:17]
	v_mfma_f32_16x16x32_bf16 v[10:13], v[232:235], v[208:211], v[10:13]
	v_mfma_f32_16x16x32_bf16 v[6:9], v[224:227], v[216:219], v[6:9]
	v_mfma_f32_16x16x32_bf16 v[2:5], v[232:235], v[216:219], v[2:5]
	v_mfma_f32_16x16x32_bf16 v[50:53], v[228:231], v[172:175], v[50:53]
	v_mfma_f32_16x16x32_bf16 v[42:45], v[236:239], v[172:175], v[42:45]
	v_mfma_f32_16x16x32_bf16 v[30:33], v[228:231], v[204:207], v[30:33]
	v_mfma_f32_16x16x32_bf16 v[26:29], v[236:239], v[204:207], v[26:29]
	v_mfma_f32_16x16x32_bf16 v[14:17], v[228:231], v[212:215], v[14:17]
	v_mfma_f32_16x16x32_bf16 v[10:13], v[236:239], v[212:215], v[10:13]
	v_mfma_f32_16x16x32_bf16 v[6:9], v[228:231], v[220:223], v[6:9]
	v_mfma_f32_16x16x32_bf16 v[2:5], v[236:239], v[220:223], v[2:5]
	s_add_i32 s34, s34, 2
	s_add_u32 s14, s14, 0x100
	s_addc_u32 s15, s15, 0
	s_add_u32 s30, s30, 0x100
	s_addc_u32 s31, s31, 0
	s_cmp_gt_u32 s34, 61
	s_barrier
	s_cbranch_scc0 .LBB0_1088
; #define PG8_WAIT_V(n) asm volatile("s_waitcnt vmcnt(" #n ")" ::: "memory")
; #define PG8_BAR __builtin_amdgcn_s_barrier()
; template <class Epi, class Sched>
; __device__ __forceinline__ void gemm_phase(PG8_LAS unsigned char* lds, const int lda, const int ldb, const Sched& S, const Epi& E) {
;     ...
;   PG8_WAIT_V(0);
;   if (wr == 0) PG8_BAR;
;   PG8_BAR;
;   __device__ __forceinline__ void operator()(const f32x4 (&acc)[2][2][4][2], const Unit& u, int wr, int wc, int fr, int fq) const {
; #pragma unroll
;     for (int ai = 0; ai < 2; ++ai)
; #pragma unroll
;       for (int m = 0; m < 4; ++m) {
;         const size_t r = (size_t)rowbase + (size_t)u.pn * rows_per_b + u.pm * 256 + ai * 128 + wr * 64 + m * 16 + fr;
; #pragma unroll
;         for (int bj = 0; bj < 2; ++bj)
; #pragma unroll
;           for (int n = 0; n < 2; ++n) {
;             const f32x4 v = acc[ai][bj][m][n];
;             const int c = 256 + bj * 128 + wc * 32 + n * 16 + 4 * fq;
;             uint2 w; w.x = pack2(v[0], v[1]); w.y = pack2(v[2], v[3]);
;             *reinterpret_cast<uint2*>(Y + r * 1024 + c) = w;
;           }
;       }
;   }
	s_lshl_b32 s14, s28, 8
	s_ashr_i32 s15, s14, 31
	s_ashr_i32 s13, s12, 31
	v_lshl_add_u64 v[152:153], v[136:137], 0, s[14:15]
	s_lshl_b64 s[12:13], s[12:13], 22
	v_lshlrev_b64 v[152:153], 11, v[152:153]
	v_lshl_add_u64 v[152:153], v[152:153], 0, s[12:13]
	v_readlane_b32 s12, v253, 54
	v_readlane_b32 s13, v253, 55
	v_mov_b32_e32 v145, v0
	v_cvt_pk_bf16_f32 v109, v108, v109
	v_lshl_add_u64 v[154:155], s[12:13], 0, v[152:153]
	v_lshl_add_u64 v[156:157], v[154:155], 0, v[144:145]
	v_cvt_pk_bf16_f32 v108, v106, v107
	v_or_b32_e32 v106, 0x8000, v152
	v_mov_b32_e32 v107, v153
	s_mov_b64 s[12:13], 0x40000
	v_cvt_pk_bf16_f32 v129, v128, v129
	v_cvt_pk_bf16_f32 v128, v126, v127
	v_cvt_pk_bf16_f32 v125, v124, v125
	v_cvt_pk_bf16_f32 v124, v122, v123
	v_cvt_pk_bf16_f32 v113, v112, v113
	v_cvt_pk_bf16_f32 v112, v110, v111
	global_store_dwordx2 v[156:157], v[108:109], off offset:800
	v_lshl_add_u64 v[106:107], v[138:139], 0, v[106:107]
	v_cvt_pk_bf16_f32 v109, v120, v121
	v_cvt_pk_bf16_f32 v108, v118, v119
	v_cvt_pk_bf16_f32 v93, v92, v93
	v_cvt_pk_bf16_f32 v92, v90, v91
	v_or_b32_e32 v90, 0x10000, v152
	v_mov_b32_e32 v91, v153
	v_cvt_pk_bf16_f32 v69, v68, v69
	v_cvt_pk_bf16_f32 v68, v66, v67
	v_lshl_add_u64 v[66:67], v[154:155], 0, s[12:13]
	s_mov_b64 s[12:13], 0x48000
	global_store_dwordx2 v[156:157], v[128:129], off offset:512
	global_store_dwordx2 v[156:157], v[124:125], off offset:544
	global_store_dwordx2 v[156:157], v[112:113], off offset:768
	global_store_dwordx2 v[106:107], v[108:109], off offset:512
	v_cvt_pk_bf16_f32 v109, v116, v117
	v_cvt_pk_bf16_f32 v108, v114, v115
	v_cvt_pk_bf16_f32 v97, v96, v97
	v_cvt_pk_bf16_f32 v96, v94, v95
	global_store_dwordx2 v[106:107], v[92:93], off offset:800
	v_lshl_add_u64 v[90:91], v[138:139], 0, v[90:91]
	v_cvt_pk_bf16_f32 v93, v104, v105
	v_cvt_pk_bf16_f32 v92, v102, v103
	v_cvt_pk_bf16_f32 v77, v76, v77
	v_cvt_pk_bf16_f32 v76, v74, v75
	v_or_b32_e32 v152, 0x18000, v152
	v_cvt_pk_bf16_f32 v45, v44, v45
	v_cvt_pk_bf16_f32 v44, v42, v43
	v_lshl_add_u64 v[42:43], v[154:155], 0, s[12:13]
	s_mov_b64 s[12:13], 0x50000
	global_store_dwordx2 v[106:107], v[108:109], off offset:544
	global_store_dwordx2 v[106:107], v[96:97], off offset:768
	global_store_dwordx2 v[90:91], v[92:93], off offset:512
	v_cvt_pk_bf16_f32 v93, v100, v101
	v_cvt_pk_bf16_f32 v92, v98, v99
	v_cvt_pk_bf16_f32 v81, v80, v81
	v_cvt_pk_bf16_f32 v80, v78, v79
	global_store_dwordx2 v[90:91], v[76:77], off offset:800
	v_lshl_add_u64 v[74:75], v[138:139], 0, v[152:153]
	v_cvt_pk_bf16_f32 v77, v88, v89
	v_cvt_pk_bf16_f32 v76, v86, v87
	v_mov_b32_e32 v151, v0
	v_cvt_pk_bf16_f32 v29, v28, v29
	v_cvt_pk_bf16_f32 v28, v26, v27
	v_lshl_add_u64 v[26:27], v[154:155], 0, s[12:13]
	s_mov_b64 s[12:13], 0x58000
	global_store_dwordx2 v[90:91], v[92:93], off offset:544
	global_store_dwordx2 v[90:91], v[80:81], off offset:768
	global_store_dwordx2 v[74:75], v[76:77], off offset:512
	v_cvt_pk_bf16_f32 v77, v84, v85
	v_cvt_pk_bf16_f32 v76, v82, v83
	v_cvt_pk_bf16_f32 v73, v72, v73
	v_cvt_pk_bf16_f32 v72, v70, v71
	v_cvt_pk_bf16_f32 v53, v52, v53
	v_cvt_pk_bf16_f32 v52, v50, v51
	v_lshl_add_u64 v[50:51], v[66:67], 0, v[150:151]
	v_cvt_pk_bf16_f32 v33, v32, v33
	v_cvt_pk_bf16_f32 v32, v30, v31
	v_lshl_add_u64 v[30:31], v[42:43], 0, v[150:151]
	v_cvt_pk_bf16_f32 v17, v16, v17
	v_cvt_pk_bf16_f32 v16, v14, v15
	v_lshl_add_u64 v[14:15], v[26:27], 0, v[150:151]
	v_cvt_pk_bf16_f32 v13, v12, v13
	v_cvt_pk_bf16_f32 v12, v10, v11
	v_lshl_add_u64 v[10:11], v[154:155], 0, s[12:13]
	global_store_dwordx2 v[74:75], v[76:77], off offset:544
	global_store_dwordx2 v[74:75], v[72:73], off offset:768
	global_store_dwordx2 v[74:75], v[68:69], off offset:800
	v_mov_b32_e32 v147, v0
	global_store_dwordx2 v[50:51], v[44:45], off offset:512
	v_lshl_add_u64 v[44:45], v[42:43], 0, v[144:145]
	v_cvt_pk_bf16_f32 v51, v56, v57
	v_cvt_pk_bf16_f32 v50, v54, v55
	global_store_dwordx2 v[30:31], v[28:29], off offset:512
	v_lshl_add_u64 v[28:29], v[26:27], 0, v[144:145]
	v_cvt_pk_bf16_f32 v31, v40, v41
	v_cvt_pk_bf16_f32 v30, v38, v39
	global_store_dwordx2 v[14:15], v[12:13], off offset:512
	v_lshl_add_u64 v[12:13], v[10:11], 0, v[144:145]
	v_cvt_pk_bf16_f32 v15, v24, v25
	v_cvt_pk_bf16_f32 v14, v22, v23
	v_mov_b32_e32 v149, v0
	global_store_dwordx2 v[44:45], v[50:51], off offset:512
	v_lshl_add_u64 v[44:45], v[42:43], 0, v[146:147]
	v_cvt_pk_bf16_f32 v49, v48, v49
	v_cvt_pk_bf16_f32 v48, v46, v47
	global_store_dwordx2 v[28:29], v[30:31], off offset:512
	v_lshl_add_u64 v[28:29], v[26:27], 0, v[146:147]
	v_cvt_pk_bf16_f32 v31, v36, v37
	v_cvt_pk_bf16_f32 v30, v34, v35
	global_store_dwordx2 v[12:13], v[14:15], off offset:512
	v_lshl_add_u64 v[12:13], v[10:11], 0, v[146:147]
	v_cvt_pk_bf16_f32 v15, v20, v21
	v_cvt_pk_bf16_f32 v14, v18, v19
	v_lshl_add_u64 v[68:69], v[66:67], 0, v[144:145]
	v_cvt_pk_bf16_f32 v65, v64, v65
	v_cvt_pk_bf16_f32 v64, v62, v63
	v_lshl_add_u64 v[62:63], v[66:67], 0, v[146:147]
	v_cvt_pk_bf16_f32 v61, v60, v61
	v_cvt_pk_bf16_f32 v60, v58, v59
	v_lshl_add_u64 v[58:59], v[66:67], 0, v[148:149]
	global_store_dwordx2 v[44:45], v[48:49], off offset:512
	v_lshl_add_u64 v[44:45], v[42:43], 0, v[148:149]
	global_store_dwordx2 v[28:29], v[30:31], off offset:512
	v_lshl_add_u64 v[28:29], v[26:27], 0, v[148:149]
	global_store_dwordx2 v[12:13], v[14:15], off offset:512
	v_lshl_add_u64 v[12:13], v[10:11], 0, v[148:149]
	v_cvt_pk_bf16_f32 v9, v8, v9
	v_cvt_pk_bf16_f32 v8, v6, v7
	v_lshl_add_u64 v[6:7], v[10:11], 0, v[150:151]
	v_cvt_pk_bf16_f32 v5, v4, v5
	v_cvt_pk_bf16_f32 v4, v2, v3
	s_and_b64 vcc, exec, s[4:5]
	s_mov_b32 s12, s0
	s_mov_b32 s28, s6
	s_mov_b64 s[16:17], s[10:11]
	s_mov_b64 s[14:15], s[8:9]
	global_store_dwordx2 v[68:69], v[64:65], off offset:512
	global_store_dwordx2 v[62:63], v[60:61], off offset:512
	global_store_dwordx2 v[58:59], v[52:53], off offset:512
	global_store_dwordx2 v[44:45], v[32:33], off offset:512
	global_store_dwordx2 v[28:29], v[16:17], off offset:512
	global_store_dwordx2 v[12:13], v[8:9], off offset:512
	global_store_dwordx2 v[6:7], v[4:5], off offset:512
	s_cbranch_vccz .LBB0_1081
	s_waitcnt vmcnt(0)
	s_cmpk_gt_u32 s2, 0xff
	s_movk_i32 s21, 0x210
	s_mov_b32 s26, 0x2aaaaaab
	s_movk_i32 s27, 0xff40
	s_cbranch_scc1 .LBB0_1092
	s_barrier

; #define PG8_STAGE(bufoff, gbase, voff) do { _Pragma("unroll") for (int _i = 0; _i < 2; ++_i) \
;     __builtin_amdgcn_global_load_lds((const unsigned*)((const char*)(gbase) + (voff)[_i]), (PG8_LAS unsigned*)(lds + (bufoff) + ldsw + _i * 8192), 16, 0, 0); } while (0)
; #define PG8_LDA(dst, b, h) do { _Pragma("unroll") for (int m = 0; m < 4; ++m) _Pragma("unroll") for (int k = 0; k < 2; ++k) dst[m][k] = *(const PG8_LAS bf16x8*)(lds + PG8_SA(b, h) + aoff + m * 2048 + k * 1024); } while (0)
; #define PG8_LDB(dst, b, h) do { _Pragma("unroll") for (int n = 0; n < 2; ++n) _Pragma("unroll") for (int k = 0; k < 2; ++k) dst[n][k] = *(const PG8_LAS bf16x8*)(lds + PG8_SB(b, h) + boff + n * 2048 + k * 1024); } while (0)
; #define PG8_MMA(ai, bj, At, Bt) do { __builtin_amdgcn_s_setprio(1); _Pragma("unroll") for (int m = 0; m < 4; ++m) _Pragma("unroll") for (int n = 0; n < 2; ++n) _Pragma("unroll") for (int k = 0; k < 2; ++k) \
;     acc[ai][bj][m][n] = __builtin_amdgcn_mfma_f32_16x16x32_bf16(Bt[n][k], At[m][k], acc[ai][bj][m][n], 0, 0, 0); __builtin_amdgcn_s_setprio(0); } while (0)
; #define PG8_WAIT_L(n) asm volatile("s_waitcnt lgkmcnt(" #n ")" ::: "memory")
; #define PG8_BAR __builtin_amdgcn_s_barrier()
; #define PG8_SCHED __builtin_amdgcn_sched_barrier(0)
; template <class Epi, class Sched>
; __device__ __forceinline__ void gemm_phase(PG8_LAS unsigned char* lds, const int lda, const int ldb, const Sched& S, const Epi& E) {
;     ...
;     for (int t = 0; t < nt; t += 2) {
;       const bool last = (t == nt - 2);
;       const char* a1 = cA + (size_t)(t + 1) * kstep;
;       const char* a2 = last ? nA : cA + (size_t)(t + 2) * kstep; const char* b2 = last ? nB : cB + (size_t)(t + 2) * kstep;
;       const char* a3 = a2 + kstep; const char* b3 = b2 + kstep;
;       PG8_LDB(B0, 0, 0); PG8_SCHED; PG8_LDA(At, 0, 0); PG8_STAGE(PG8_SA(1, 1), a1 + hstepA, voffA);
;       PG8_WAIT_L(8); PG8_BAR; PG8_WAIT_L(0); PG8_MMA(0, 0, At, B0); PG8_BAR; PG8_SCHED;
;       PG8_LDB(B1, 0, 1); PG8_STAGE(PG8_SB(0, 0), b2, voffB);
;       PG8_BAR; PG8_WAIT_L(0); PG8_MMA(0, 1, At, B1); PG8_BAR;
;       PG8_LDA(At, 0, 1); PG8_STAGE(PG8_SA(0, 0), a2, voffA);
;       PG8_BAR; PG8_WAIT_L(0); PG8_MMA(1, 0, At, B0); PG8_BAR; PG8_SCHED;
.LBB0_1412:
	s_add_i32 s33, s18, 2
	s_add_u32 s19, s14, 0xfffc0080
	s_addc_u32 s20, s15, -1
	s_add_i32 s44, 0, 0x10000
	v_add_u32_e32 v152, s44, v131
	ds_read_b128 v[140:143], v152
	ds_read_b128 v[144:147], v152 offset:1024
	ds_read_b128 v[148:151], v152 offset:2048
	ds_read_b128 v[152:155], v152 offset:3072
	s_cmp_eq_u32 s11, s18
	s_cselect_b32 s18, s12, s22
	s_cselect_b32 s21, s7, s20
	s_cselect_b32 s20, s6, s19
	s_cselect_b32 s19, s13, s23
	v_lshl_add_u64 v[182:183], s[14:15], 0, v[136:137]
	s_add_i32 m0, s17, 0xc000
	ds_read_b128 v[156:159], v201
	ds_read_b128 v[160:163], v201 offset:1024
	ds_read_b128 v[164:167], v201 offset:2048
	ds_read_b128 v[168:171], v201 offset:3072
	ds_read_b128 v[172:175], v201 offset:4096
	ds_read_b128 v[202:205], v201 offset:5120
	ds_read_b128 v[206:209], v201 offset:6144
	ds_read_b128 v[210:213], v201 offset:7168
	global_load_lds_dwordx4 v[182:183], off
	v_lshl_add_u64 v[182:183], s[14:15], 0, v[138:139]
	s_add_i32 m0, s17, 0xe000
	s_nop 0
	global_load_lds_dwordx4 v[182:183], off
	s_waitcnt lgkmcnt(8)
	s_barrier
	s_waitcnt lgkmcnt(0)
	v_mfma_f32_16x16x32_bf16 v[126:129], v[140:143], v[156:159], v[126:129]
	v_mfma_f32_16x16x32_bf16 v[122:125], v[148:151], v[156:159], v[122:125]
	v_mfma_f32_16x16x32_bf16 v[118:121], v[140:143], v[164:167], v[118:121]
	v_mfma_f32_16x16x32_bf16 v[114:117], v[148:151], v[164:167], v[114:117]
	v_mfma_f32_16x16x32_bf16 v[110:113], v[140:143], v[172:175], v[110:113]
	v_mfma_f32_16x16x32_bf16 v[106:109], v[148:151], v[172:175], v[106:109]
	v_mfma_f32_16x16x32_bf16 v[102:105], v[140:143], v[206:209], v[102:105]
	v_mfma_f32_16x16x32_bf16 v[98:101], v[148:151], v[206:209], v[98:101]
	v_mfma_f32_16x16x32_bf16 v[126:129], v[144:147], v[160:163], v[126:129]
	v_mfma_f32_16x16x32_bf16 v[122:125], v[152:155], v[160:163], v[122:125]
	v_mfma_f32_16x16x32_bf16 v[118:121], v[144:147], v[168:171], v[118:121]
	v_mfma_f32_16x16x32_bf16 v[114:117], v[152:155], v[168:171], v[114:117]
	v_mfma_f32_16x16x32_bf16 v[110:113], v[144:147], v[202:205], v[110:113]
	v_mfma_f32_16x16x32_bf16 v[106:109], v[152:155], v[202:205], v[106:109]
	v_mfma_f32_16x16x32_bf16 v[102:105], v[144:147], v[210:213], v[102:105]
	v_mfma_f32_16x16x32_bf16 v[98:101], v[152:155], v[210:213], v[98:101]
	s_barrier
	s_add_i32 s46, 0, 0x14000
	v_add_u32_e32 v182, s46, v131
	s_add_i32 s44, s44, s29
	ds_read_b128 v[214:217], v182
	ds_read_b128 v[218:221], v182 offset:1024
	ds_read_b128 v[222:225], v182 offset:2048
	ds_read_b128 v[226:229], v182 offset:3072
	v_lshl_add_u64 v[182:183], s[18:19], 0, v[134:135]
	s_mov_b32 m0, s44
	v_lshl_add_u64 v[184:185], s[18:19], 0, v[132:133]
	global_load_lds_dwordx4 v[182:183], off
	s_add_i32 m0, s44, 0x2000
	s_nop 0
	global_load_lds_dwordx4 v[184:185], off
	s_barrier
	s_waitcnt lgkmcnt(0)
	v_mfma_f32_16x16x32_bf16 v[94:97], v[214:217], v[156:159], v[94:97]
	v_mfma_f32_16x16x32_bf16 v[90:93], v[222:225], v[156:159], v[90:93]
	v_mfma_f32_16x16x32_bf16 v[86:89], v[214:217], v[164:167], v[86:89]
	v_mfma_f32_16x16x32_bf16 v[82:85], v[222:225], v[164:167], v[82:85]
	v_mfma_f32_16x16x32_bf16 v[78:81], v[214:217], v[172:175], v[78:81]
	v_mfma_f32_16x16x32_bf16 v[74:77], v[222:225], v[172:175], v[74:77]
	v_mfma_f32_16x16x32_bf16 v[70:73], v[214:217], v[206:209], v[70:73]
	v_mfma_f32_16x16x32_bf16 v[66:69], v[222:225], v[206:209], v[66:69]
	v_mfma_f32_16x16x32_bf16 v[94:97], v[218:221], v[160:163], v[94:97]
	v_mfma_f32_16x16x32_bf16 v[90:93], v[226:229], v[160:163], v[90:93]
	v_mfma_f32_16x16x32_bf16 v[86:89], v[218:221], v[168:171], v[86:89]
	v_mfma_f32_16x16x32_bf16 v[82:85], v[226:229], v[168:171], v[82:85]
	v_mfma_f32_16x16x32_bf16 v[78:81], v[218:221], v[202:205], v[78:81]
	v_mfma_f32_16x16x32_bf16 v[74:77], v[226:229], v[202:205], v[74:77]
	v_mfma_f32_16x16x32_bf16 v[70:73], v[218:221], v[210:213], v[70:73]
	v_mfma_f32_16x16x32_bf16 v[66:69], v[226:229], v[210:213], v[66:69]
	s_mov_b32 m0, s17
	v_lshl_add_u64 v[230:231], s[20:21], 0, v[134:135]
	s_barrier
	ds_read_b128 v[156:159], v201 offset:16384
	ds_read_b128 v[160:163], v201 offset:17408
	ds_read_b128 v[164:167], v201 offset:18432
	ds_read_b128 v[168:171], v201 offset:19456
	ds_read_b128 v[172:175], v201 offset:20480
	ds_read_b128 v[202:205], v201 offset:21504
	ds_read_b128 v[206:209], v201 offset:22528
	ds_read_b128 v[210:213], v201 offset:23552
	global_load_lds_dwordx4 v[230:231], off
	v_lshl_add_u64 v[232:233], s[20:21], 0, v[132:133]
	s_mov_b32 m0, s34
	s_nop 0
	global_load_lds_dwordx4 v[232:233], off
	s_barrier
	s_waitcnt lgkmcnt(0)
	v_mfma_f32_16x16x32_bf16 v[62:65], v[140:143], v[156:159], v[62:65]
	v_mfma_f32_16x16x32_bf16 v[58:61], v[148:151], v[156:159], v[58:61]
	v_mfma_f32_16x16x32_bf16 v[54:57], v[140:143], v[164:167], v[54:57]
	v_mfma_f32_16x16x32_bf16 v[50:53], v[148:151], v[164:167], v[50:53]
	v_mfma_f32_16x16x32_bf16 v[46:49], v[140:143], v[172:175], v[46:49]
	v_mfma_f32_16x16x32_bf16 v[42:45], v[148:151], v[172:175], v[42:45]
	v_mfma_f32_16x16x32_bf16 v[38:41], v[140:143], v[206:209], v[38:41]
	v_mfma_f32_16x16x32_bf16 v[34:37], v[148:151], v[206:209], v[34:37]
	v_mfma_f32_16x16x32_bf16 v[62:65], v[144:147], v[160:163], v[62:65]
	v_mfma_f32_16x16x32_bf16 v[58:61], v[152:155], v[160:163], v[58:61]
	v_mfma_f32_16x16x32_bf16 v[54:57], v[144:147], v[168:171], v[54:57]
	v_mfma_f32_16x16x32_bf16 v[50:53], v[152:155], v[168:171], v[50:53]
	v_mfma_f32_16x16x32_bf16 v[46:49], v[144:147], v[202:205], v[46:49]
	v_mfma_f32_16x16x32_bf16 v[42:45], v[152:155], v[202:205], v[42:45]
	v_mfma_f32_16x16x32_bf16 v[38:41], v[144:147], v[210:213], v[38:41]
	v_mfma_f32_16x16x32_bf16 v[34:37], v[152:155], v[210:213], v[34:37]
	s_barrier
; #define PG8_STAGE(bufoff, gbase, voff) do { _Pragma("unroll") for (int _i = 0; _i < 2; ++_i) \
;     __builtin_amdgcn_global_load_lds((const unsigned*)((const char*)(gbase) + (voff)[_i]), (PG8_LAS unsigned*)(lds + (bufoff) + ldsw + _i * 8192), 16, 0, 0); } while (0)
; #define PG8_LDA(dst, b, h) do { _Pragma("unroll") for (int m = 0; m < 4; ++m) _Pragma("unroll") for (int k = 0; k < 2; ++k) dst[m][k] = *(const PG8_LAS bf16x8*)(lds + PG8_SA(b, h) + aoff + m * 2048 + k * 1024); } while (0)
; #define PG8_LDB(dst, b, h) do { _Pragma("unroll") for (int n = 0; n < 2; ++n) _Pragma("unroll") for (int k = 0; k < 2; ++k) dst[n][k] = *(const PG8_LAS bf16x8*)(lds + PG8_SB(b, h) + boff + n * 2048 + k * 1024); } while (0)
; #define PG8_MMA(ai, bj, At, Bt) do { __builtin_amdgcn_s_setprio(1); _Pragma("unroll") for (int m = 0; m < 4; ++m) _Pragma("unroll") for (int n = 0; n < 2; ++n) _Pragma("unroll") for (int k = 0; k < 2; ++k) \
;     acc[ai][bj][m][n] = __builtin_amdgcn_mfma_f32_16x16x32_bf16(Bt[n][k], At[m][k], acc[ai][bj][m][n], 0, 0, 0); __builtin_amdgcn_s_setprio(0); } while (0)
; #define PG8_WAIT_V(n) asm volatile("s_waitcnt vmcnt(" #n ")" ::: "memory")
; #define PG8_WAIT_L(n) asm volatile("s_waitcnt lgkmcnt(" #n ")" ::: "memory")
; #define PG8_BAR __builtin_amdgcn_s_barrier()
; #define PG8_SCHED __builtin_amdgcn_sched_barrier(0)
; template <class Epi, class Sched>
; __device__ __forceinline__ void gemm_phase(PG8_LAS unsigned char* lds, const int lda, const int ldb, const Sched& S, const Epi& E) {
;     ...
;       PG8_STAGE(PG8_SB(0, 1), b2 + hstepB, voffB);
;       PG8_WAIT_V(6); PG8_BAR; PG8_MMA(1, 1, At, B1); PG8_BAR;
;       PG8_LDB(B0, 1, 0); PG8_SCHED; PG8_LDA(At, 1, 0); PG8_STAGE(PG8_SA(0, 1), a2 + hstepA, voffA);
;       PG8_WAIT_L(8); PG8_BAR; PG8_WAIT_L(0); PG8_MMA(0, 0, At, B0); PG8_BAR; PG8_SCHED;
;       PG8_LDB(B1, 1, 1); PG8_STAGE(PG8_SB(1, 0), b3, voffB);
;       PG8_BAR; PG8_WAIT_L(0); PG8_MMA(0, 1, At, B1); PG8_BAR;
;       PG8_LDA(At, 1, 1); PG8_STAGE(PG8_SA(1, 0), a3, voffA);
	s_add_u32 s44, s18, 0x40000
	s_addc_u32 s45, s19, 0
	s_add_i32 s46, s46, s29
	v_lshl_add_u64 v[140:141], s[44:45], 0, v[134:135]
	s_mov_b32 m0, s46
	s_nop 0
	global_load_lds_dwordx4 v[140:141], off
	v_lshl_add_u64 v[140:141], s[44:45], 0, v[132:133]
	s_add_i32 m0, s46, 0x2000
	s_nop 0
	global_load_lds_dwordx4 v[140:141], off
	s_waitcnt vmcnt(6)
	s_barrier
	v_mfma_f32_16x16x32_bf16 v[30:33], v[214:217], v[156:159], v[30:33]
	v_mfma_f32_16x16x32_bf16 v[26:29], v[222:225], v[156:159], v[26:29]
	v_mfma_f32_16x16x32_bf16 v[22:25], v[214:217], v[164:167], v[22:25]
	v_mfma_f32_16x16x32_bf16 v[18:21], v[222:225], v[164:167], v[18:21]
	v_mfma_f32_16x16x32_bf16 v[14:17], v[214:217], v[172:175], v[14:17]
	v_mfma_f32_16x16x32_bf16 v[10:13], v[222:225], v[172:175], v[10:13]
	v_mfma_f32_16x16x32_bf16 v[6:9], v[214:217], v[206:209], v[6:9]
	v_mfma_f32_16x16x32_bf16 v[2:5], v[222:225], v[206:209], v[2:5]
	v_mfma_f32_16x16x32_bf16 v[30:33], v[218:221], v[160:163], v[30:33]
	v_mfma_f32_16x16x32_bf16 v[26:29], v[226:229], v[160:163], v[26:29]
	v_mfma_f32_16x16x32_bf16 v[22:25], v[218:221], v[168:171], v[22:25]
	v_mfma_f32_16x16x32_bf16 v[18:21], v[226:229], v[168:171], v[18:21]
	v_mfma_f32_16x16x32_bf16 v[14:17], v[218:221], v[202:205], v[14:17]
	v_mfma_f32_16x16x32_bf16 v[10:13], v[226:229], v[202:205], v[10:13]
	v_mfma_f32_16x16x32_bf16 v[6:9], v[218:221], v[210:213], v[6:9]
	v_mfma_f32_16x16x32_bf16 v[2:5], v[226:229], v[210:213], v[2:5]
	s_add_i32 s44, 0, 0x18000
	v_add_u32_e32 v152, s44, v131
	s_barrier
	ds_read_b128 v[140:143], v152
	ds_read_b128 v[144:147], v152 offset:1024
	ds_read_b128 v[148:151], v152 offset:2048
	ds_read_b128 v[152:155], v152 offset:3072
	s_add_u32 s20, s20, 0x40000
	s_addc_u32 s21, s21, 0
	s_mov_b32 m0, s35
	v_lshl_add_u64 v[214:215], s[20:21], 0, v[134:135]
	ds_read_b128 v[156:159], v201 offset:32768
	ds_read_b128 v[160:163], v201 offset:33792
	ds_read_b128 v[164:167], v201 offset:34816
	ds_read_b128 v[168:171], v201 offset:35840
	ds_read_b128 v[172:175], v201 offset:36864
	ds_read_b128 v[202:205], v201 offset:37888
	ds_read_b128 v[206:209], v201 offset:38912
	ds_read_b128 v[210:213], v201 offset:39936
	global_load_lds_dwordx4 v[214:215], off
	v_lshl_add_u64 v[214:215], s[20:21], 0, v[132:133]
	s_mov_b32 m0, s36
	s_nop 0
	global_load_lds_dwordx4 v[214:215], off
	s_waitcnt lgkmcnt(8)
	s_barrier
	s_waitcnt lgkmcnt(0)
	v_mfma_f32_16x16x32_bf16 v[126:129], v[140:143], v[156:159], v[126:129]
	v_mfma_f32_16x16x32_bf16 v[122:125], v[148:151], v[156:159], v[122:125]
	v_mfma_f32_16x16x32_bf16 v[118:121], v[140:143], v[164:167], v[118:121]
	v_mfma_f32_16x16x32_bf16 v[114:117], v[148:151], v[164:167], v[114:117]
	v_mfma_f32_16x16x32_bf16 v[110:113], v[140:143], v[172:175], v[110:113]
	v_mfma_f32_16x16x32_bf16 v[106:109], v[148:151], v[172:175], v[106:109]
	v_mfma_f32_16x16x32_bf16 v[102:105], v[140:143], v[206:209], v[102:105]
	v_mfma_f32_16x16x32_bf16 v[98:101], v[148:151], v[206:209], v[98:101]
	v_mfma_f32_16x16x32_bf16 v[126:129], v[144:147], v[160:163], v[126:129]
	v_mfma_f32_16x16x32_bf16 v[122:125], v[152:155], v[160:163], v[122:125]
	v_mfma_f32_16x16x32_bf16 v[118:121], v[144:147], v[168:171], v[118:121]
	v_mfma_f32_16x16x32_bf16 v[114:117], v[152:155], v[168:171], v[114:117]
	v_mfma_f32_16x16x32_bf16 v[110:113], v[144:147], v[202:205], v[110:113]
	v_mfma_f32_16x16x32_bf16 v[106:109], v[152:155], v[202:205], v[106:109]
	v_mfma_f32_16x16x32_bf16 v[102:105], v[144:147], v[210:213], v[102:105]
	v_mfma_f32_16x16x32_bf16 v[98:101], v[152:155], v[210:213], v[98:101]
	s_barrier
	s_add_i32 s20, 0, 0x1c000
	s_add_i32 s21, s44, s29
	v_add_u32_e32 v226, s20, v131
	v_lshl_add_u64 v[182:183], v[182:183], 0, s[86:87]
	s_mov_b32 m0, s21
	ds_read_b128 v[214:217], v226
	ds_read_b128 v[218:221], v226 offset:1024
	ds_read_b128 v[222:225], v226 offset:2048
	ds_read_b128 v[226:229], v226 offset:3072
	global_load_lds_dwordx4 v[182:183], off
	v_lshl_add_u64 v[182:183], v[184:185], 0, s[86:87]
	s_add_i32 m0, s21, 0x2000
	s_nop 0
	global_load_lds_dwordx4 v[182:183], off
	s_barrier
; __device__ __forceinline__ int tid_l() { int t = threadIdx.x; asm volatile("" : "+v"(t)); return t; }
; #define PG8_STAGE(bufoff, gbase, voff) do { _Pragma("unroll") for (int _i = 0; _i < 2; ++_i) \
;     __builtin_amdgcn_global_load_lds((const unsigned*)((const char*)(gbase) + (voff)[_i]), (PG8_LAS unsigned*)(lds + (bufoff) + ldsw + _i * 8192), 16, 0, 0); } while (0)
; #define PG8_MMA(ai, bj, At, Bt) do { __builtin_amdgcn_s_setprio(1); _Pragma("unroll") for (int m = 0; m < 4; ++m) _Pragma("unroll") for (int n = 0; n < 2; ++n) _Pragma("unroll") for (int k = 0; k < 2; ++k) \
;     acc[ai][bj][m][n] = __builtin_amdgcn_mfma_f32_16x16x32_bf16(Bt[n][k], At[m][k], acc[ai][bj][m][n], 0, 0, 0); __builtin_amdgcn_s_setprio(0); } while (0)
; #define PG8_WAIT_V(n) asm volatile("s_waitcnt vmcnt(" #n ")" ::: "memory")
; #define PG8_WAIT_L(n) asm volatile("s_waitcnt lgkmcnt(" #n ")" ::: "memory")
; #define PG8_BAR __builtin_amdgcn_s_barrier()
; #define PG8_SCHED __builtin_amdgcn_sched_barrier(0)
; template <class Epi, class Sched>
; __device__ __forceinline__ void gemm_phase(PG8_LAS unsigned char* lds, const int lda, const int ldb, const Sched& S, const Epi& E) {
;     ...
;       PG8_BAR; PG8_WAIT_L(0); PG8_MMA(1, 0, At, B0); PG8_BAR; PG8_SCHED;
;       PG8_STAGE(PG8_SB(1, 1), b3 + hstepB, voffB);
;       PG8_WAIT_V(6); PG8_BAR; PG8_MMA(1, 1, At, B1); PG8_BAR;
;     }
;   __device__ __forceinline__ void operator()(const f32x4 (&acc)[2][2][4][2], const Unit& u, int wr, int wc, int fr, int fq) const {
;     const int s = u.pn & 7, dq = u.pn >> 3;
;     const int tid = tid_l();
;     if (s < 4) {
	s_waitcnt lgkmcnt(0)
	v_mfma_f32_16x16x32_bf16 v[94:97], v[214:217], v[156:159], v[94:97]
	v_mfma_f32_16x16x32_bf16 v[90:93], v[222:225], v[156:159], v[90:93]
	v_mfma_f32_16x16x32_bf16 v[86:89], v[214:217], v[164:167], v[86:89]
	v_mfma_f32_16x16x32_bf16 v[82:85], v[222:225], v[164:167], v[82:85]
	v_mfma_f32_16x16x32_bf16 v[78:81], v[214:217], v[172:175], v[78:81]
	v_mfma_f32_16x16x32_bf16 v[74:77], v[222:225], v[172:175], v[74:77]
	v_mfma_f32_16x16x32_bf16 v[70:73], v[214:217], v[206:209], v[70:73]
	v_mfma_f32_16x16x32_bf16 v[66:69], v[222:225], v[206:209], v[66:69]
	v_mfma_f32_16x16x32_bf16 v[94:97], v[218:221], v[160:163], v[94:97]
	v_mfma_f32_16x16x32_bf16 v[90:93], v[226:229], v[160:163], v[90:93]
	v_mfma_f32_16x16x32_bf16 v[86:89], v[218:221], v[168:171], v[86:89]
	v_mfma_f32_16x16x32_bf16 v[82:85], v[226:229], v[168:171], v[82:85]
	v_mfma_f32_16x16x32_bf16 v[78:81], v[218:221], v[202:205], v[78:81]
	v_mfma_f32_16x16x32_bf16 v[74:77], v[226:229], v[202:205], v[74:77]
	v_mfma_f32_16x16x32_bf16 v[70:73], v[218:221], v[210:213], v[70:73]
	v_mfma_f32_16x16x32_bf16 v[66:69], v[226:229], v[210:213], v[66:69]
	s_mov_b32 m0, s39
	v_lshl_add_u64 v[182:183], v[230:231], 0, s[86:87]
	s_barrier
	ds_read_b128 v[156:159], v201 offset:49152
	ds_read_b128 v[160:163], v201 offset:50176
	ds_read_b128 v[164:167], v201 offset:51200
	ds_read_b128 v[168:171], v201 offset:52224
	ds_read_b128 v[172:175], v201 offset:53248
	ds_read_b128 v[202:205], v201 offset:54272
	ds_read_b128 v[206:209], v201 offset:55296
	ds_read_b128 v[210:213], v201 offset:56320
	global_load_lds_dwordx4 v[182:183], off
	v_lshl_add_u64 v[182:183], v[232:233], 0, s[86:87]
	s_mov_b32 m0, s40
	s_nop 0
	global_load_lds_dwordx4 v[182:183], off
	s_barrier
	s_waitcnt lgkmcnt(0)
	v_mfma_f32_16x16x32_bf16 v[62:65], v[140:143], v[156:159], v[62:65]
	v_mfma_f32_16x16x32_bf16 v[58:61], v[148:151], v[156:159], v[58:61]
	v_mfma_f32_16x16x32_bf16 v[54:57], v[140:143], v[164:167], v[54:57]
	v_mfma_f32_16x16x32_bf16 v[50:53], v[148:151], v[164:167], v[50:53]
	v_mfma_f32_16x16x32_bf16 v[46:49], v[140:143], v[172:175], v[46:49]
	v_mfma_f32_16x16x32_bf16 v[42:45], v[148:151], v[172:175], v[42:45]
	v_mfma_f32_16x16x32_bf16 v[38:41], v[140:143], v[206:209], v[38:41]
	v_mfma_f32_16x16x32_bf16 v[34:37], v[148:151], v[206:209], v[34:37]
	v_mfma_f32_16x16x32_bf16 v[62:65], v[144:147], v[160:163], v[62:65]
	v_mfma_f32_16x16x32_bf16 v[58:61], v[152:155], v[160:163], v[58:61]
	v_mfma_f32_16x16x32_bf16 v[54:57], v[144:147], v[168:171], v[54:57]
	v_mfma_f32_16x16x32_bf16 v[50:53], v[152:155], v[168:171], v[50:53]
	v_mfma_f32_16x16x32_bf16 v[46:49], v[144:147], v[202:205], v[46:49]
	v_mfma_f32_16x16x32_bf16 v[42:45], v[152:155], v[202:205], v[42:45]
	v_mfma_f32_16x16x32_bf16 v[38:41], v[144:147], v[210:213], v[38:41]
	v_mfma_f32_16x16x32_bf16 v[34:37], v[152:155], v[210:213], v[34:37]
	s_barrier
	s_add_u32 s18, s18, 0x40080
	s_addc_u32 s19, s19, 0
	s_add_i32 s20, s20, s29
	v_lshl_add_u64 v[140:141], s[18:19], 0, v[134:135]
	s_mov_b32 m0, s20
	s_nop 0
	global_load_lds_dwordx4 v[140:141], off
	v_lshl_add_u64 v[140:141], s[18:19], 0, v[132:133]
	s_add_i32 m0, s20, 0x2000
	s_nop 0
	global_load_lds_dwordx4 v[140:141], off
	s_waitcnt vmcnt(6)
	s_barrier
	v_mfma_f32_16x16x32_bf16 v[30:33], v[214:217], v[156:159], v[30:33]
	v_mfma_f32_16x16x32_bf16 v[26:29], v[222:225], v[156:159], v[26:29]
	v_mfma_f32_16x16x32_bf16 v[22:25], v[214:217], v[164:167], v[22:25]
	v_mfma_f32_16x16x32_bf16 v[18:21], v[222:225], v[164:167], v[18:21]
	v_mfma_f32_16x16x32_bf16 v[14:17], v[214:217], v[172:175], v[14:17]
	v_mfma_f32_16x16x32_bf16 v[10:13], v[222:225], v[172:175], v[10:13]
	v_mfma_f32_16x16x32_bf16 v[6:9], v[214:217], v[206:209], v[6:9]
	v_mfma_f32_16x16x32_bf16 v[2:5], v[222:225], v[206:209], v[2:5]
	v_mfma_f32_16x16x32_bf16 v[30:33], v[218:221], v[160:163], v[30:33]
	v_mfma_f32_16x16x32_bf16 v[26:29], v[226:229], v[160:163], v[26:29]
	v_mfma_f32_16x16x32_bf16 v[22:25], v[218:221], v[168:171], v[22:25]
	v_mfma_f32_16x16x32_bf16 v[18:21], v[226:229], v[168:171], v[18:21]
	v_mfma_f32_16x16x32_bf16 v[14:17], v[218:221], v[202:205], v[14:17]
	v_mfma_f32_16x16x32_bf16 v[10:13], v[226:229], v[202:205], v[10:13]
	v_mfma_f32_16x16x32_bf16 v[6:9], v[218:221], v[210:213], v[6:9]
	v_mfma_f32_16x16x32_bf16 v[2:5], v[226:229], v[210:213], v[2:5]
	s_add_u32 s14, s14, 0x100
	s_addc_u32 s15, s15, 0
	s_add_u32 s22, s22, 0x100
	s_addc_u32 s23, s23, 0
	s_cmp_ge_u32 s33, s43
	s_mov_b32 s18, s33
	s_barrier
	s_cbranch_scc0 .LBB0_1412
	s_and_b32 s11, s2, 7
	v_mov_b32_e32 v140, v176
	s_mov_b64 s[14:15], -1
	s_cmp_gt_u32 s11, 3
	v_ashrrev_i32_e32 v141, 31, v140
	s_cbranch_scc1 .LBB0_1416
	s_andn2_b64 vcc, exec, s[14:15]
	s_cbranch_vccz .LBB0_1417

; #define PG8_STAGE(bufoff, gbase, voff) do { _Pragma("unroll") for (int _i = 0; _i < 2; ++_i) \
;     __builtin_amdgcn_global_load_lds((const unsigned*)((const char*)(gbase) + (voff)[_i]), (PG8_LAS unsigned*)(lds + (bufoff) + ldsw + _i * 8192), 16, 0, 0); } while (0)
; #define PG8_LDA(dst, b, h) do { _Pragma("unroll") for (int m = 0; m < 4; ++m) _Pragma("unroll") for (int k = 0; k < 2; ++k) dst[m][k] = *(const PG8_LAS bf16x8*)(lds + PG8_SA(b, h) + aoff + m * 2048 + k * 1024); } while (0)
; #define PG8_LDB(dst, b, h) do { _Pragma("unroll") for (int n = 0; n < 2; ++n) _Pragma("unroll") for (int k = 0; k < 2; ++k) dst[n][k] = *(const PG8_LAS bf16x8*)(lds + PG8_SB(b, h) + boff + n * 2048 + k * 1024); } while (0)
; #define PG8_MMA(ai, bj, At, Bt) do { __builtin_amdgcn_s_setprio(1); _Pragma("unroll") for (int m = 0; m < 4; ++m) _Pragma("unroll") for (int n = 0; n < 2; ++n) _Pragma("unroll") for (int k = 0; k < 2; ++k) \
;     acc[ai][bj][m][n] = __builtin_amdgcn_mfma_f32_16x16x32_bf16(Bt[n][k], At[m][k], acc[ai][bj][m][n], 0, 0, 0); __builtin_amdgcn_s_setprio(0); } while (0)
; #define PG8_WAIT_L(n) asm volatile("s_waitcnt lgkmcnt(" #n ")" ::: "memory")
; #define PG8_BAR __builtin_amdgcn_s_barrier()
; #define PG8_SCHED __builtin_amdgcn_sched_barrier(0)
; template <class Epi, class Sched>
; __device__ __forceinline__ void gemm_phase(PG8_LAS unsigned char* lds, const int lda, const int ldb, const Sched& S, const Epi& E) {
;     ...
;     for (int t = 0; t < nt; t += 2) {
;       const bool last = (t == nt - 2);
;       const char* a1 = cA + (size_t)(t + 1) * kstep;
;       const char* a2 = last ? nA : cA + (size_t)(t + 2) * kstep; const char* b2 = last ? nB : cB + (size_t)(t + 2) * kstep;
;       const char* a3 = a2 + kstep; const char* b3 = b2 + kstep;
;       PG8_LDB(B0, 0, 0); PG8_SCHED; PG8_LDA(At, 0, 0); PG8_STAGE(PG8_SA(1, 1), a1 + hstepA, voffA);
;       PG8_WAIT_L(8); PG8_BAR; PG8_WAIT_L(0); PG8_MMA(0, 0, At, B0); PG8_BAR; PG8_SCHED;
;       PG8_LDB(B1, 0, 1); PG8_STAGE(PG8_SB(0, 0), b2, voffB);
;       PG8_BAR; PG8_WAIT_L(0); PG8_MMA(0, 1, At, B1); PG8_BAR;
;       PG8_LDA(At, 0, 1); PG8_STAGE(PG8_SA(0, 0), a2, voffA);
;       PG8_BAR; PG8_WAIT_L(0); PG8_MMA(1, 0, At, B0); PG8_BAR; PG8_SCHED;
.LBB0_1482:
	s_add_u32 s20, s18, 0x100
	s_addc_u32 s21, s19, 0
	s_add_i32 s33, 0, 0x10000
	v_add_u32_e32 v154, s33, v131
	ds_read_b128 v[140:143], v154
	ds_read_b128 v[146:149], v154 offset:1024
	ds_read_b128 v[150:153], v154 offset:2048
	ds_read_b128 v[154:157], v154 offset:3072
	s_cmp_eq_u32 s54, 12
	s_cselect_b32 s25, s11, s21
	s_cselect_b32 s24, s50, s20
	s_cselect_b32 s23, s1, s53
	s_cselect_b32 s22, s51, s52
	v_lshl_add_u64 v[174:175], s[18:19], 0, v[136:137]
	s_add_i32 m0, s17, 0xc000
	ds_read_b128 v[158:161], v145
	ds_read_b128 v[162:165], v145 offset:1024
	ds_read_b128 v[166:169], v145 offset:2048
	ds_read_b128 v[170:173], v145 offset:3072
	ds_read_b128 v[200:203], v145 offset:4096
	ds_read_b128 v[204:207], v145 offset:5120
	ds_read_b128 v[208:211], v145 offset:6144
	ds_read_b128 v[212:215], v145 offset:7168
	global_load_lds_dwordx4 v[174:175], off
	v_lshl_add_u64 v[174:175], s[18:19], 0, v[138:139]
	s_add_i32 m0, s17, 0xe000
	s_nop 0
	global_load_lds_dwordx4 v[174:175], off
	s_waitcnt lgkmcnt(8)
	s_barrier
	s_waitcnt lgkmcnt(0)
	v_mfma_f32_16x16x32_bf16 v[126:129], v[140:143], v[158:161], v[126:129]
	v_mfma_f32_16x16x32_bf16 v[122:125], v[150:153], v[158:161], v[122:125]
	v_mfma_f32_16x16x32_bf16 v[110:113], v[140:143], v[166:169], v[110:113]
	v_mfma_f32_16x16x32_bf16 v[106:109], v[150:153], v[166:169], v[106:109]
	v_mfma_f32_16x16x32_bf16 v[94:97], v[140:143], v[200:203], v[94:97]
	v_mfma_f32_16x16x32_bf16 v[90:93], v[150:153], v[200:203], v[90:93]
	v_mfma_f32_16x16x32_bf16 v[78:81], v[140:143], v[208:211], v[78:81]
	v_mfma_f32_16x16x32_bf16 v[74:77], v[150:153], v[208:211], v[74:77]
	v_mfma_f32_16x16x32_bf16 v[126:129], v[146:149], v[162:165], v[126:129]
	v_mfma_f32_16x16x32_bf16 v[122:125], v[154:157], v[162:165], v[122:125]
	v_mfma_f32_16x16x32_bf16 v[110:113], v[146:149], v[170:173], v[110:113]
	v_mfma_f32_16x16x32_bf16 v[106:109], v[154:157], v[170:173], v[106:109]
	v_mfma_f32_16x16x32_bf16 v[94:97], v[146:149], v[204:207], v[94:97]
	v_mfma_f32_16x16x32_bf16 v[90:93], v[154:157], v[204:207], v[90:93]
	v_mfma_f32_16x16x32_bf16 v[78:81], v[146:149], v[212:215], v[78:81]
	v_mfma_f32_16x16x32_bf16 v[74:77], v[154:157], v[212:215], v[74:77]
	s_barrier
	s_add_i32 s55, 0, 0x14000
	v_add_u32_e32 v174, s55, v131
	s_add_i32 s18, s33, s34
	ds_read_b128 v[216:219], v174
	ds_read_b128 v[220:223], v174 offset:1024
	ds_read_b128 v[224:227], v174 offset:2048
	ds_read_b128 v[228:231], v174 offset:3072
	v_lshl_add_u64 v[174:175], s[22:23], 0, v[134:135]
	s_mov_b32 m0, s18
	v_lshl_add_u64 v[182:183], s[22:23], 0, v[132:133]
	global_load_lds_dwordx4 v[174:175], off
	s_add_i32 m0, s18, 0x2000
	s_nop 0
	global_load_lds_dwordx4 v[182:183], off
	s_barrier
	s_waitcnt lgkmcnt(0)
	v_mfma_f32_16x16x32_bf16 v[118:121], v[216:219], v[158:161], v[118:121]
	v_mfma_f32_16x16x32_bf16 v[114:117], v[224:227], v[158:161], v[114:117]
	v_mfma_f32_16x16x32_bf16 v[102:105], v[216:219], v[166:169], v[102:105]
	v_mfma_f32_16x16x32_bf16 v[98:101], v[224:227], v[166:169], v[98:101]
	v_mfma_f32_16x16x32_bf16 v[86:89], v[216:219], v[200:203], v[86:89]
	v_mfma_f32_16x16x32_bf16 v[82:85], v[224:227], v[200:203], v[82:85]
	v_mfma_f32_16x16x32_bf16 v[70:73], v[216:219], v[208:211], v[70:73]
	v_mfma_f32_16x16x32_bf16 v[66:69], v[224:227], v[208:211], v[66:69]
	v_mfma_f32_16x16x32_bf16 v[118:121], v[220:223], v[162:165], v[118:121]
	v_mfma_f32_16x16x32_bf16 v[114:117], v[228:231], v[162:165], v[114:117]
	v_mfma_f32_16x16x32_bf16 v[102:105], v[220:223], v[170:173], v[102:105]
	v_mfma_f32_16x16x32_bf16 v[98:101], v[228:231], v[170:173], v[98:101]
	v_mfma_f32_16x16x32_bf16 v[86:89], v[220:223], v[204:207], v[86:89]
	v_mfma_f32_16x16x32_bf16 v[82:85], v[228:231], v[204:207], v[82:85]
	v_mfma_f32_16x16x32_bf16 v[70:73], v[220:223], v[212:215], v[70:73]
	v_mfma_f32_16x16x32_bf16 v[66:69], v[228:231], v[212:215], v[66:69]
	s_mov_b32 m0, s17
	v_lshl_add_u64 v[184:185], s[24:25], 0, v[134:135]
	s_barrier
	ds_read_b128 v[158:161], v145 offset:16384
	ds_read_b128 v[162:165], v145 offset:17408
	ds_read_b128 v[166:169], v145 offset:18432
	ds_read_b128 v[170:173], v145 offset:19456
	ds_read_b128 v[200:203], v145 offset:20480
	ds_read_b128 v[204:207], v145 offset:21504
	ds_read_b128 v[208:211], v145 offset:22528
	ds_read_b128 v[212:215], v145 offset:23552
	global_load_lds_dwordx4 v[184:185], off
	v_lshl_add_u64 v[232:233], s[24:25], 0, v[132:133]
	s_mov_b32 m0, s37
	s_nop 0
	global_load_lds_dwordx4 v[232:233], off
	s_barrier
	s_waitcnt lgkmcnt(0)
	v_mfma_f32_16x16x32_bf16 v[62:65], v[140:143], v[158:161], v[62:65]
	v_mfma_f32_16x16x32_bf16 v[58:61], v[150:153], v[158:161], v[58:61]
	v_mfma_f32_16x16x32_bf16 v[46:49], v[140:143], v[166:169], v[46:49]
	v_mfma_f32_16x16x32_bf16 v[42:45], v[150:153], v[166:169], v[42:45]
	v_mfma_f32_16x16x32_bf16 v[30:33], v[140:143], v[200:203], v[30:33]
	v_mfma_f32_16x16x32_bf16 v[26:29], v[150:153], v[200:203], v[26:29]
	v_mfma_f32_16x16x32_bf16 v[14:17], v[140:143], v[208:211], v[14:17]
	v_mfma_f32_16x16x32_bf16 v[10:13], v[150:153], v[208:211], v[10:13]
	v_mfma_f32_16x16x32_bf16 v[62:65], v[146:149], v[162:165], v[62:65]
	v_mfma_f32_16x16x32_bf16 v[58:61], v[154:157], v[162:165], v[58:61]
	v_mfma_f32_16x16x32_bf16 v[46:49], v[146:149], v[170:173], v[46:49]
	v_mfma_f32_16x16x32_bf16 v[42:45], v[154:157], v[170:173], v[42:45]
	v_mfma_f32_16x16x32_bf16 v[30:33], v[146:149], v[204:207], v[30:33]
	v_mfma_f32_16x16x32_bf16 v[26:29], v[154:157], v[204:207], v[26:29]
	v_mfma_f32_16x16x32_bf16 v[14:17], v[146:149], v[212:215], v[14:17]
	v_mfma_f32_16x16x32_bf16 v[10:13], v[154:157], v[212:215], v[10:13]
	s_barrier
; #define PG8_STAGE(bufoff, gbase, voff) do { _Pragma("unroll") for (int _i = 0; _i < 2; ++_i) \
;     __builtin_amdgcn_global_load_lds((const unsigned*)((const char*)(gbase) + (voff)[_i]), (PG8_LAS unsigned*)(lds + (bufoff) + ldsw + _i * 8192), 16, 0, 0); } while (0)
; #define PG8_LDA(dst, b, h) do { _Pragma("unroll") for (int m = 0; m < 4; ++m) _Pragma("unroll") for (int k = 0; k < 2; ++k) dst[m][k] = *(const PG8_LAS bf16x8*)(lds + PG8_SA(b, h) + aoff + m * 2048 + k * 1024); } while (0)
; #define PG8_LDB(dst, b, h) do { _Pragma("unroll") for (int n = 0; n < 2; ++n) _Pragma("unroll") for (int k = 0; k < 2; ++k) dst[n][k] = *(const PG8_LAS bf16x8*)(lds + PG8_SB(b, h) + boff + n * 2048 + k * 1024); } while (0)
; #define PG8_MMA(ai, bj, At, Bt) do { __builtin_amdgcn_s_setprio(1); _Pragma("unroll") for (int m = 0; m < 4; ++m) _Pragma("unroll") for (int n = 0; n < 2; ++n) _Pragma("unroll") for (int k = 0; k < 2; ++k) \
;     acc[ai][bj][m][n] = __builtin_amdgcn_mfma_f32_16x16x32_bf16(Bt[n][k], At[m][k], acc[ai][bj][m][n], 0, 0, 0); __builtin_amdgcn_s_setprio(0); } while (0)
; #define PG8_WAIT_V(n) asm volatile("s_waitcnt vmcnt(" #n ")" ::: "memory")
; #define PG8_WAIT_L(n) asm volatile("s_waitcnt lgkmcnt(" #n ")" ::: "memory")
; #define PG8_BAR __builtin_amdgcn_s_barrier()
; #define PG8_SCHED __builtin_amdgcn_sched_barrier(0)
; template <class Epi, class Sched>
; __device__ __forceinline__ void gemm_phase(PG8_LAS unsigned char* lds, const int lda, const int ldb, const Sched& S, const Epi& E) {
;     ...
;       PG8_STAGE(PG8_SB(0, 1), b2 + hstepB, voffB);
;       PG8_WAIT_V(6); PG8_BAR; PG8_MMA(1, 1, At, B1); PG8_BAR;
;       PG8_LDB(B0, 1, 0); PG8_SCHED; PG8_LDA(At, 1, 0); PG8_STAGE(PG8_SA(0, 1), a2 + hstepA, voffA);
;       PG8_WAIT_L(8); PG8_BAR; PG8_WAIT_L(0); PG8_MMA(0, 0, At, B0); PG8_BAR; PG8_SCHED;
;       PG8_LDB(B1, 1, 1); PG8_STAGE(PG8_SB(1, 0), b3, voffB);
;       PG8_BAR; PG8_WAIT_L(0); PG8_MMA(0, 1, At, B1); PG8_BAR;
;       PG8_LDA(At, 1, 1); PG8_STAGE(PG8_SA(1, 0), a3, voffA);
	s_add_u32 s18, s22, 0x40000
	s_addc_u32 s19, s23, 0
	s_add_i32 s33, s55, s34
	v_lshl_add_u64 v[140:141], s[18:19], 0, v[134:135]
	s_mov_b32 m0, s33
	s_nop 0
	global_load_lds_dwordx4 v[140:141], off
	v_lshl_add_u64 v[140:141], s[18:19], 0, v[132:133]
	s_add_i32 m0, s33, 0x2000
	s_nop 0
	global_load_lds_dwordx4 v[140:141], off
	s_waitcnt vmcnt(6)
	s_barrier
	v_mfma_f32_16x16x32_bf16 v[54:57], v[216:219], v[158:161], v[54:57]
	v_mfma_f32_16x16x32_bf16 v[50:53], v[224:227], v[158:161], v[50:53]
	v_mfma_f32_16x16x32_bf16 v[38:41], v[216:219], v[166:169], v[38:41]
	v_mfma_f32_16x16x32_bf16 v[34:37], v[224:227], v[166:169], v[34:37]
	v_mfma_f32_16x16x32_bf16 v[22:25], v[216:219], v[200:203], v[22:25]
	v_mfma_f32_16x16x32_bf16 v[18:21], v[224:227], v[200:203], v[18:21]
	v_mfma_f32_16x16x32_bf16 v[6:9], v[216:219], v[208:211], v[6:9]
	v_mfma_f32_16x16x32_bf16 v[2:5], v[224:227], v[208:211], v[2:5]
	v_mfma_f32_16x16x32_bf16 v[54:57], v[220:223], v[162:165], v[54:57]
	v_mfma_f32_16x16x32_bf16 v[50:53], v[228:231], v[162:165], v[50:53]
	v_mfma_f32_16x16x32_bf16 v[38:41], v[220:223], v[170:173], v[38:41]
	v_mfma_f32_16x16x32_bf16 v[34:37], v[228:231], v[170:173], v[34:37]
	v_mfma_f32_16x16x32_bf16 v[22:25], v[220:223], v[204:207], v[22:25]
	v_mfma_f32_16x16x32_bf16 v[18:21], v[228:231], v[204:207], v[18:21]
	v_mfma_f32_16x16x32_bf16 v[6:9], v[220:223], v[212:215], v[6:9]
	v_mfma_f32_16x16x32_bf16 v[2:5], v[228:231], v[212:215], v[2:5]
	s_add_i32 s33, 0, 0x18000
	v_add_u32_e32 v154, s33, v131
	s_barrier
	ds_read_b128 v[140:143], v154
	ds_read_b128 v[146:149], v154 offset:1024
	ds_read_b128 v[150:153], v154 offset:2048
	ds_read_b128 v[154:157], v154 offset:3072
	s_add_u32 s18, s24, 0x40000
	s_addc_u32 s19, s25, 0
	s_mov_b32 m0, s38
	v_lshl_add_u64 v[216:217], s[18:19], 0, v[134:135]
	ds_read_b128 v[158:161], v145 offset:32768
	ds_read_b128 v[162:165], v145 offset:33792
	ds_read_b128 v[166:169], v145 offset:34816
	ds_read_b128 v[170:173], v145 offset:35840
	ds_read_b128 v[200:203], v145 offset:36864
	ds_read_b128 v[204:207], v145 offset:37888
	ds_read_b128 v[208:211], v145 offset:38912
	ds_read_b128 v[212:215], v145 offset:39936
	global_load_lds_dwordx4 v[216:217], off
	v_lshl_add_u64 v[216:217], s[18:19], 0, v[132:133]
	s_mov_b32 m0, s39
	s_nop 0
	global_load_lds_dwordx4 v[216:217], off
	s_waitcnt lgkmcnt(8)
	s_barrier
	s_waitcnt lgkmcnt(0)
	v_mfma_f32_16x16x32_bf16 v[126:129], v[140:143], v[158:161], v[126:129]
	v_mfma_f32_16x16x32_bf16 v[122:125], v[150:153], v[158:161], v[122:125]
	v_mfma_f32_16x16x32_bf16 v[110:113], v[140:143], v[166:169], v[110:113]
	v_mfma_f32_16x16x32_bf16 v[106:109], v[150:153], v[166:169], v[106:109]
	v_mfma_f32_16x16x32_bf16 v[94:97], v[140:143], v[200:203], v[94:97]
	v_mfma_f32_16x16x32_bf16 v[90:93], v[150:153], v[200:203], v[90:93]
	v_mfma_f32_16x16x32_bf16 v[78:81], v[140:143], v[208:211], v[78:81]
	v_mfma_f32_16x16x32_bf16 v[74:77], v[150:153], v[208:211], v[74:77]
	v_mfma_f32_16x16x32_bf16 v[126:129], v[146:149], v[162:165], v[126:129]
	v_mfma_f32_16x16x32_bf16 v[122:125], v[154:157], v[162:165], v[122:125]
	v_mfma_f32_16x16x32_bf16 v[110:113], v[146:149], v[170:173], v[110:113]
	v_mfma_f32_16x16x32_bf16 v[106:109], v[154:157], v[170:173], v[106:109]
	v_mfma_f32_16x16x32_bf16 v[94:97], v[146:149], v[204:207], v[94:97]
	v_mfma_f32_16x16x32_bf16 v[90:93], v[154:157], v[204:207], v[90:93]
	v_mfma_f32_16x16x32_bf16 v[78:81], v[146:149], v[212:215], v[78:81]
	v_mfma_f32_16x16x32_bf16 v[74:77], v[154:157], v[212:215], v[74:77]
	s_barrier
	s_add_i32 s24, 0, 0x1c000
	s_add_i32 s18, s33, s34
	v_add_u32_e32 v228, s24, v131
	v_lshl_add_u64 v[174:175], v[174:175], 0, s[86:87]
	s_mov_b32 m0, s18
	ds_read_b128 v[216:219], v228
	ds_read_b128 v[220:223], v228 offset:1024
	ds_read_b128 v[224:227], v228 offset:2048
	ds_read_b128 v[228:231], v228 offset:3072
	global_load_lds_dwordx4 v[174:175], off
	v_lshl_add_u64 v[174:175], v[182:183], 0, s[86:87]
	s_add_i32 m0, s18, 0x2000
	s_nop 0
	global_load_lds_dwordx4 v[174:175], off
	s_barrier
; #define PG8_STAGE(bufoff, gbase, voff) do { _Pragma("unroll") for (int _i = 0; _i < 2; ++_i) \
;     __builtin_amdgcn_global_load_lds((const unsigned*)((const char*)(gbase) + (voff)[_i]), (PG8_LAS unsigned*)(lds + (bufoff) + ldsw + _i * 8192), 16, 0, 0); } while (0)
; #define PG8_MMA(ai, bj, At, Bt) do { __builtin_amdgcn_s_setprio(1); _Pragma("unroll") for (int m = 0; m < 4; ++m) _Pragma("unroll") for (int n = 0; n < 2; ++n) _Pragma("unroll") for (int k = 0; k < 2; ++k) \
;     acc[ai][bj][m][n] = __builtin_amdgcn_mfma_f32_16x16x32_bf16(Bt[n][k], At[m][k], acc[ai][bj][m][n], 0, 0, 0); __builtin_amdgcn_s_setprio(0); } while (0)
; #define PG8_WAIT_V(n) asm volatile("s_waitcnt vmcnt(" #n ")" ::: "memory")
; #define PG8_WAIT_L(n) asm volatile("s_waitcnt lgkmcnt(" #n ")" ::: "memory")
; #define PG8_BAR __builtin_amdgcn_s_barrier()
; #define PG8_SCHED __builtin_amdgcn_sched_barrier(0)
; template <class Epi, class Sched>
; __device__ __forceinline__ void gemm_phase(PG8_LAS unsigned char* lds, const int lda, const int ldb, const Sched& S, const Epi& E) {
;     ...
;       PG8_BAR; PG8_WAIT_L(0); PG8_MMA(1, 0, At, B0); PG8_BAR; PG8_SCHED;
;       PG8_STAGE(PG8_SB(1, 1), b3 + hstepB, voffB);
;       PG8_WAIT_V(6); PG8_BAR; PG8_MMA(1, 1, At, B1); PG8_BAR;
;     }
;   __device__ __forceinline__ void operator()(const f32x4 (&acc)[2][2][4][2], const Unit& u, int wr, int wc, int fr, int fq) const {
;     const int mr = (u.pm * 256 < ML) ? ((u.pm * 256) >> 11) : 32;
;     const float* gp = mod + (size_t)mr * 6144 + gate_off;
	s_waitcnt lgkmcnt(0)
	v_mfma_f32_16x16x32_bf16 v[118:121], v[216:219], v[158:161], v[118:121]
	v_mfma_f32_16x16x32_bf16 v[114:117], v[224:227], v[158:161], v[114:117]
	v_mfma_f32_16x16x32_bf16 v[102:105], v[216:219], v[166:169], v[102:105]
	v_mfma_f32_16x16x32_bf16 v[98:101], v[224:227], v[166:169], v[98:101]
	v_mfma_f32_16x16x32_bf16 v[86:89], v[216:219], v[200:203], v[86:89]
	v_mfma_f32_16x16x32_bf16 v[82:85], v[224:227], v[200:203], v[82:85]
	v_mfma_f32_16x16x32_bf16 v[70:73], v[216:219], v[208:211], v[70:73]
	v_mfma_f32_16x16x32_bf16 v[66:69], v[224:227], v[208:211], v[66:69]
	v_mfma_f32_16x16x32_bf16 v[118:121], v[220:223], v[162:165], v[118:121]
	v_mfma_f32_16x16x32_bf16 v[114:117], v[228:231], v[162:165], v[114:117]
	v_mfma_f32_16x16x32_bf16 v[102:105], v[220:223], v[170:173], v[102:105]
	v_mfma_f32_16x16x32_bf16 v[98:101], v[228:231], v[170:173], v[98:101]
	v_mfma_f32_16x16x32_bf16 v[86:89], v[220:223], v[204:207], v[86:89]
	v_mfma_f32_16x16x32_bf16 v[82:85], v[228:231], v[204:207], v[82:85]
	v_mfma_f32_16x16x32_bf16 v[70:73], v[220:223], v[212:215], v[70:73]
	v_mfma_f32_16x16x32_bf16 v[66:69], v[228:231], v[212:215], v[66:69]
	s_mov_b32 m0, s44
	v_lshl_add_u64 v[174:175], v[184:185], 0, s[86:87]
	s_barrier
	ds_read_b128 v[158:161], v145 offset:49152
	ds_read_b128 v[162:165], v145 offset:50176
	ds_read_b128 v[166:169], v145 offset:51200
	ds_read_b128 v[170:173], v145 offset:52224
	ds_read_b128 v[200:203], v145 offset:53248
	ds_read_b128 v[204:207], v145 offset:54272
	ds_read_b128 v[208:211], v145 offset:55296
	ds_read_b128 v[212:215], v145 offset:56320
	global_load_lds_dwordx4 v[174:175], off
	v_lshl_add_u64 v[174:175], v[232:233], 0, s[86:87]
	s_mov_b32 m0, s45
	s_nop 0
	global_load_lds_dwordx4 v[174:175], off
	s_barrier
	s_waitcnt lgkmcnt(0)
	v_mfma_f32_16x16x32_bf16 v[62:65], v[140:143], v[158:161], v[62:65]
	v_mfma_f32_16x16x32_bf16 v[58:61], v[150:153], v[158:161], v[58:61]
	v_mfma_f32_16x16x32_bf16 v[46:49], v[140:143], v[166:169], v[46:49]
	v_mfma_f32_16x16x32_bf16 v[42:45], v[150:153], v[166:169], v[42:45]
	v_mfma_f32_16x16x32_bf16 v[30:33], v[140:143], v[200:203], v[30:33]
	v_mfma_f32_16x16x32_bf16 v[26:29], v[150:153], v[200:203], v[26:29]
	v_mfma_f32_16x16x32_bf16 v[14:17], v[140:143], v[208:211], v[14:17]
	v_mfma_f32_16x16x32_bf16 v[10:13], v[150:153], v[208:211], v[10:13]
	v_mfma_f32_16x16x32_bf16 v[62:65], v[146:149], v[162:165], v[62:65]
	v_mfma_f32_16x16x32_bf16 v[58:61], v[154:157], v[162:165], v[58:61]
	v_mfma_f32_16x16x32_bf16 v[46:49], v[146:149], v[170:173], v[46:49]
	v_mfma_f32_16x16x32_bf16 v[42:45], v[154:157], v[170:173], v[42:45]
	v_mfma_f32_16x16x32_bf16 v[30:33], v[146:149], v[204:207], v[30:33]
	v_mfma_f32_16x16x32_bf16 v[26:29], v[154:157], v[204:207], v[26:29]
	v_mfma_f32_16x16x32_bf16 v[14:17], v[146:149], v[212:215], v[14:17]
	v_mfma_f32_16x16x32_bf16 v[10:13], v[154:157], v[212:215], v[10:13]
	s_barrier
	s_add_u32 s18, s22, 0x40080
	s_addc_u32 s19, s23, 0
	s_add_i32 s22, s24, s34
	v_lshl_add_u64 v[140:141], s[18:19], 0, v[134:135]
	s_mov_b32 m0, s22
	s_nop 0
	global_load_lds_dwordx4 v[140:141], off
	v_lshl_add_u64 v[140:141], s[18:19], 0, v[132:133]
	s_add_i32 m0, s22, 0x2000
	s_nop 0
	global_load_lds_dwordx4 v[140:141], off
	s_waitcnt vmcnt(6)
	s_barrier
	v_mfma_f32_16x16x32_bf16 v[54:57], v[216:219], v[158:161], v[54:57]
	v_mfma_f32_16x16x32_bf16 v[50:53], v[224:227], v[158:161], v[50:53]
	v_mfma_f32_16x16x32_bf16 v[38:41], v[216:219], v[166:169], v[38:41]
	v_mfma_f32_16x16x32_bf16 v[34:37], v[224:227], v[166:169], v[34:37]
	v_mfma_f32_16x16x32_bf16 v[22:25], v[216:219], v[200:203], v[22:25]
	v_mfma_f32_16x16x32_bf16 v[18:21], v[224:227], v[200:203], v[18:21]
	v_mfma_f32_16x16x32_bf16 v[6:9], v[216:219], v[208:211], v[6:9]
	v_mfma_f32_16x16x32_bf16 v[2:5], v[224:227], v[208:211], v[2:5]
	v_mfma_f32_16x16x32_bf16 v[54:57], v[220:223], v[162:165], v[54:57]
	v_mfma_f32_16x16x32_bf16 v[50:53], v[228:231], v[162:165], v[50:53]
	v_mfma_f32_16x16x32_bf16 v[38:41], v[220:223], v[170:173], v[38:41]
	v_mfma_f32_16x16x32_bf16 v[34:37], v[228:231], v[170:173], v[34:37]
	v_mfma_f32_16x16x32_bf16 v[22:25], v[220:223], v[204:207], v[22:25]
	v_mfma_f32_16x16x32_bf16 v[18:21], v[228:231], v[204:207], v[18:21]
	v_mfma_f32_16x16x32_bf16 v[6:9], v[220:223], v[212:215], v[6:9]
	v_mfma_f32_16x16x32_bf16 v[2:5], v[228:231], v[212:215], v[2:5]
	s_add_i32 s54, s54, 2
	s_add_u32 s52, s52, 0x100
	s_addc_u32 s53, s53, 0
	s_cmp_gt_u32 s54, 13
	s_mov_b64 s[18:19], s[20:21]
	s_barrier
	s_cbranch_scc0 .LBB0_1482
	s_cmpk_gt_i32 s16, 0xff
	s_mov_b64 s[18:19], 0x30000
	s_cbranch_scc1 .LBB0_1478
	s_ashr_i32 s1, s16, 3
	s_mul_hi_i32 s19, s1, 0x1800
	s_mul_i32 s18, s1, 0x1800
	s_branch .LBB0_1478

; #define PG8_STAGE(bufoff, gbase, voff) do { _Pragma("unroll") for (int _i = 0; _i < 2; ++_i) \
;     __builtin_amdgcn_global_load_lds((const unsigned*)((const char*)(gbase) + (voff)[_i]), (PG8_LAS unsigned*)(lds + (bufoff) + ldsw + _i * 8192), 16, 0, 0); } while (0)
; #define PG8_LDA(dst, b, h) do { _Pragma("unroll") for (int m = 0; m < 4; ++m) _Pragma("unroll") for (int k = 0; k < 2; ++k) dst[m][k] = *(const PG8_LAS bf16x8*)(lds + PG8_SA(b, h) + aoff + m * 2048 + k * 1024); } while (0)
; #define PG8_LDB(dst, b, h) do { _Pragma("unroll") for (int n = 0; n < 2; ++n) _Pragma("unroll") for (int k = 0; k < 2; ++k) dst[n][k] = *(const PG8_LAS bf16x8*)(lds + PG8_SB(b, h) + boff + n * 2048 + k * 1024); } while (0)
; #define PG8_MMA(ai, bj, At, Bt) do { __builtin_amdgcn_s_setprio(1); _Pragma("unroll") for (int m = 0; m < 4; ++m) _Pragma("unroll") for (int n = 0; n < 2; ++n) _Pragma("unroll") for (int k = 0; k < 2; ++k) \
;     acc[ai][bj][m][n] = __builtin_amdgcn_mfma_f32_16x16x32_bf16(Bt[n][k], At[m][k], acc[ai][bj][m][n], 0, 0, 0); __builtin_amdgcn_s_setprio(0); } while (0)
; #define PG8_WAIT_L(n) asm volatile("s_waitcnt lgkmcnt(" #n ")" ::: "memory")
; #define PG8_BAR __builtin_amdgcn_s_barrier()
; #define PG8_SCHED __builtin_amdgcn_sched_barrier(0)
; template <class Epi, class Sched>
; __device__ __forceinline__ void gemm_phase(PG8_LAS unsigned char* lds, const int lda, const int ldb, const Sched& S, const Epi& E) {
;     ...
;     for (int t = 0; t < nt; t += 2) {
;       const bool last = (t == nt - 2);
;       const char* a1 = cA + (size_t)(t + 1) * kstep;
;       const char* a2 = last ? nA : cA + (size_t)(t + 2) * kstep; const char* b2 = last ? nB : cB + (size_t)(t + 2) * kstep;
;       const char* a3 = a2 + kstep; const char* b3 = b2 + kstep;
;       PG8_LDB(B0, 0, 0); PG8_SCHED; PG8_LDA(At, 0, 0); PG8_STAGE(PG8_SA(1, 1), a1 + hstepA, voffA);
;       PG8_WAIT_L(8); PG8_BAR; PG8_WAIT_L(0); PG8_MMA(0, 0, At, B0); PG8_BAR; PG8_SCHED;
;       PG8_LDB(B1, 0, 1); PG8_STAGE(PG8_SB(0, 0), b2, voffB);
;       PG8_BAR; PG8_WAIT_L(0); PG8_MMA(0, 1, At, B1); PG8_BAR;
;       PG8_LDA(At, 0, 1); PG8_STAGE(PG8_SA(0, 0), a2, voffA);
;       PG8_BAR; PG8_WAIT_L(0); PG8_MMA(1, 0, At, B0); PG8_BAR; PG8_SCHED;
.LBB0_1604:
	s_add_u32 s20, s18, 0xfffc0080
	s_addc_u32 s21, s19, -1
	s_add_i32 s33, 0, 0x10000
	v_add_u32_e32 v154, s33, v131
	ds_read_b128 v[142:145], v154
	ds_read_b128 v[146:149], v154 offset:1024
	ds_read_b128 v[150:153], v154 offset:2048
	ds_read_b128 v[154:157], v154 offset:3072
	s_cmp_eq_u32 s46, 12
	s_cselect_b32 s23, s11, s21
	s_cselect_b32 s22, s42, s20
	s_cselect_b32 s21, s1, s45
	s_cselect_b32 s20, s43, s44
	v_lshl_add_u64 v[174:175], s[18:19], 0, v[136:137]
	s_add_i32 m0, s17, 0xc000
	ds_read_b128 v[158:161], v141
	ds_read_b128 v[162:165], v141 offset:1024
	ds_read_b128 v[166:169], v141 offset:2048
	ds_read_b128 v[170:173], v141 offset:3072
	ds_read_b128 v[200:203], v141 offset:4096
	ds_read_b128 v[204:207], v141 offset:5120
	ds_read_b128 v[208:211], v141 offset:6144
	ds_read_b128 v[212:215], v141 offset:7168
	global_load_lds_dwordx4 v[174:175], off
	v_lshl_add_u64 v[174:175], s[18:19], 0, v[138:139]
	s_add_i32 m0, s17, 0xe000
	s_nop 0
	global_load_lds_dwordx4 v[174:175], off
	s_waitcnt lgkmcnt(8)
	s_barrier
	s_waitcnt lgkmcnt(0)
	v_mfma_f32_16x16x32_bf16 v[126:129], v[142:145], v[158:161], v[126:129]
	v_mfma_f32_16x16x32_bf16 v[118:121], v[150:153], v[158:161], v[118:121]
	v_mfma_f32_16x16x32_bf16 v[110:113], v[142:145], v[166:169], v[110:113]
	v_mfma_f32_16x16x32_bf16 v[102:105], v[150:153], v[166:169], v[102:105]
	v_mfma_f32_16x16x32_bf16 v[94:97], v[142:145], v[200:203], v[94:97]
	v_mfma_f32_16x16x32_bf16 v[86:89], v[150:153], v[200:203], v[86:89]
	v_mfma_f32_16x16x32_bf16 v[78:81], v[142:145], v[208:211], v[78:81]
	v_mfma_f32_16x16x32_bf16 v[70:73], v[150:153], v[208:211], v[70:73]
	v_mfma_f32_16x16x32_bf16 v[126:129], v[146:149], v[162:165], v[126:129]
	v_mfma_f32_16x16x32_bf16 v[118:121], v[154:157], v[162:165], v[118:121]
	v_mfma_f32_16x16x32_bf16 v[110:113], v[146:149], v[170:173], v[110:113]
	v_mfma_f32_16x16x32_bf16 v[102:105], v[154:157], v[170:173], v[102:105]
	v_mfma_f32_16x16x32_bf16 v[94:97], v[146:149], v[204:207], v[94:97]
	v_mfma_f32_16x16x32_bf16 v[86:89], v[154:157], v[204:207], v[86:89]
	v_mfma_f32_16x16x32_bf16 v[78:81], v[146:149], v[212:215], v[78:81]
	v_mfma_f32_16x16x32_bf16 v[70:73], v[154:157], v[212:215], v[70:73]
	s_barrier
	s_add_i32 s47, 0, 0x14000
	v_add_u32_e32 v174, s47, v131
	s_add_i32 s33, s33, s30
	ds_read_b128 v[216:219], v174
	ds_read_b128 v[220:223], v174 offset:1024
	ds_read_b128 v[224:227], v174 offset:2048
	ds_read_b128 v[228:231], v174 offset:3072
	v_lshl_add_u64 v[174:175], s[20:21], 0, v[134:135]
	s_mov_b32 m0, s33
	v_lshl_add_u64 v[182:183], s[20:21], 0, v[132:133]
	global_load_lds_dwordx4 v[174:175], off
	s_add_i32 m0, s33, 0x2000
	s_nop 0
	global_load_lds_dwordx4 v[182:183], off
	s_barrier
	s_waitcnt lgkmcnt(0)
	v_mfma_f32_16x16x32_bf16 v[122:125], v[216:219], v[158:161], v[122:125]
	v_mfma_f32_16x16x32_bf16 v[114:117], v[224:227], v[158:161], v[114:117]
	v_mfma_f32_16x16x32_bf16 v[106:109], v[216:219], v[166:169], v[106:109]
	v_mfma_f32_16x16x32_bf16 v[98:101], v[224:227], v[166:169], v[98:101]
	v_mfma_f32_16x16x32_bf16 v[90:93], v[216:219], v[200:203], v[90:93]
	v_mfma_f32_16x16x32_bf16 v[82:85], v[224:227], v[200:203], v[82:85]
	v_mfma_f32_16x16x32_bf16 v[74:77], v[216:219], v[208:211], v[74:77]
	v_mfma_f32_16x16x32_bf16 v[66:69], v[224:227], v[208:211], v[66:69]
	v_mfma_f32_16x16x32_bf16 v[122:125], v[220:223], v[162:165], v[122:125]
	v_mfma_f32_16x16x32_bf16 v[114:117], v[228:231], v[162:165], v[114:117]
	v_mfma_f32_16x16x32_bf16 v[106:109], v[220:223], v[170:173], v[106:109]
	v_mfma_f32_16x16x32_bf16 v[98:101], v[228:231], v[170:173], v[98:101]
	v_mfma_f32_16x16x32_bf16 v[90:93], v[220:223], v[204:207], v[90:93]
	v_mfma_f32_16x16x32_bf16 v[82:85], v[228:231], v[204:207], v[82:85]
	v_mfma_f32_16x16x32_bf16 v[74:77], v[220:223], v[212:215], v[74:77]
	v_mfma_f32_16x16x32_bf16 v[66:69], v[228:231], v[212:215], v[66:69]
	s_mov_b32 m0, s17
	v_lshl_add_u64 v[184:185], s[22:23], 0, v[134:135]
	s_barrier
	ds_read_b128 v[158:161], v141 offset:16384
	ds_read_b128 v[162:165], v141 offset:17408
	ds_read_b128 v[166:169], v141 offset:18432
	ds_read_b128 v[170:173], v141 offset:19456
	ds_read_b128 v[200:203], v141 offset:20480
	ds_read_b128 v[204:207], v141 offset:21504
	ds_read_b128 v[208:211], v141 offset:22528
	ds_read_b128 v[212:215], v141 offset:23552
	global_load_lds_dwordx4 v[184:185], off
	v_lshl_add_u64 v[232:233], s[22:23], 0, v[132:133]
	s_mov_b32 m0, s35
	s_nop 0
	global_load_lds_dwordx4 v[232:233], off
	s_barrier
	s_waitcnt lgkmcnt(0)
	v_mfma_f32_16x16x32_bf16 v[62:65], v[142:145], v[158:161], v[62:65]
	v_mfma_f32_16x16x32_bf16 v[54:57], v[150:153], v[158:161], v[54:57]
	v_mfma_f32_16x16x32_bf16 v[46:49], v[142:145], v[166:169], v[46:49]
	v_mfma_f32_16x16x32_bf16 v[38:41], v[150:153], v[166:169], v[38:41]
	v_mfma_f32_16x16x32_bf16 v[30:33], v[142:145], v[200:203], v[30:33]
	v_mfma_f32_16x16x32_bf16 v[22:25], v[150:153], v[200:203], v[22:25]
	v_mfma_f32_16x16x32_bf16 v[14:17], v[142:145], v[208:211], v[14:17]
	v_mfma_f32_16x16x32_bf16 v[6:9], v[150:153], v[208:211], v[6:9]
	v_mfma_f32_16x16x32_bf16 v[62:65], v[146:149], v[162:165], v[62:65]
	v_mfma_f32_16x16x32_bf16 v[54:57], v[154:157], v[162:165], v[54:57]
	v_mfma_f32_16x16x32_bf16 v[46:49], v[146:149], v[170:173], v[46:49]
	v_mfma_f32_16x16x32_bf16 v[38:41], v[154:157], v[170:173], v[38:41]
	v_mfma_f32_16x16x32_bf16 v[30:33], v[146:149], v[204:207], v[30:33]
	v_mfma_f32_16x16x32_bf16 v[22:25], v[154:157], v[204:207], v[22:25]
	v_mfma_f32_16x16x32_bf16 v[14:17], v[146:149], v[212:215], v[14:17]
	v_mfma_f32_16x16x32_bf16 v[6:9], v[154:157], v[212:215], v[6:9]
	s_barrier
; #define PG8_STAGE(bufoff, gbase, voff) do { _Pragma("unroll") for (int _i = 0; _i < 2; ++_i) \
;     __builtin_amdgcn_global_load_lds((const unsigned*)((const char*)(gbase) + (voff)[_i]), (PG8_LAS unsigned*)(lds + (bufoff) + ldsw + _i * 8192), 16, 0, 0); } while (0)
; #define PG8_LDA(dst, b, h) do { _Pragma("unroll") for (int m = 0; m < 4; ++m) _Pragma("unroll") for (int k = 0; k < 2; ++k) dst[m][k] = *(const PG8_LAS bf16x8*)(lds + PG8_SA(b, h) + aoff + m * 2048 + k * 1024); } while (0)
; #define PG8_LDB(dst, b, h) do { _Pragma("unroll") for (int n = 0; n < 2; ++n) _Pragma("unroll") for (int k = 0; k < 2; ++k) dst[n][k] = *(const PG8_LAS bf16x8*)(lds + PG8_SB(b, h) + boff + n * 2048 + k * 1024); } while (0)
; #define PG8_MMA(ai, bj, At, Bt) do { __builtin_amdgcn_s_setprio(1); _Pragma("unroll") for (int m = 0; m < 4; ++m) _Pragma("unroll") for (int n = 0; n < 2; ++n) _Pragma("unroll") for (int k = 0; k < 2; ++k) \
;     acc[ai][bj][m][n] = __builtin_amdgcn_mfma_f32_16x16x32_bf16(Bt[n][k], At[m][k], acc[ai][bj][m][n], 0, 0, 0); __builtin_amdgcn_s_setprio(0); } while (0)
; #define PG8_WAIT_V(n) asm volatile("s_waitcnt vmcnt(" #n ")" ::: "memory")
; #define PG8_WAIT_L(n) asm volatile("s_waitcnt lgkmcnt(" #n ")" ::: "memory")
; #define PG8_BAR __builtin_amdgcn_s_barrier()
; #define PG8_SCHED __builtin_amdgcn_sched_barrier(0)
; template <class Epi, class Sched>
; __device__ __forceinline__ void gemm_phase(PG8_LAS unsigned char* lds, const int lda, const int ldb, const Sched& S, const Epi& E) {
;     ...
;       PG8_STAGE(PG8_SB(0, 1), b2 + hstepB, voffB);
;       PG8_WAIT_V(6); PG8_BAR; PG8_MMA(1, 1, At, B1); PG8_BAR;
;       PG8_LDB(B0, 1, 0); PG8_SCHED; PG8_LDA(At, 1, 0); PG8_STAGE(PG8_SA(0, 1), a2 + hstepA, voffA);
;       PG8_WAIT_L(8); PG8_BAR; PG8_WAIT_L(0); PG8_MMA(0, 0, At, B0); PG8_BAR; PG8_SCHED;
;       PG8_LDB(B1, 1, 1); PG8_STAGE(PG8_SB(1, 0), b3, voffB);
;       PG8_BAR; PG8_WAIT_L(0); PG8_MMA(0, 1, At, B1); PG8_BAR;
;       PG8_LDA(At, 1, 1); PG8_STAGE(PG8_SA(1, 0), a3, voffA);
;       PG8_BAR; PG8_WAIT_L(0); PG8_MMA(1, 0, At, B0); PG8_BAR; PG8_SCHED;
;       PG8_STAGE(PG8_SB(1, 1), b3 + hstepB, voffB);
	s_add_u32 s48, s20, 0x40000
	s_addc_u32 s49, s21, 0
	s_add_i32 s33, s47, s30
	v_lshl_add_u64 v[142:143], s[48:49], 0, v[134:135]
	s_mov_b32 m0, s33
	s_nop 0
	global_load_lds_dwordx4 v[142:143], off
	v_lshl_add_u64 v[142:143], s[48:49], 0, v[132:133]
	s_add_i32 m0, s33, 0x2000
	s_nop 0
	global_load_lds_dwordx4 v[142:143], off
	s_waitcnt vmcnt(6)
	s_barrier
	v_mfma_f32_16x16x32_bf16 v[58:61], v[216:219], v[158:161], v[58:61]
	v_mfma_f32_16x16x32_bf16 v[50:53], v[224:227], v[158:161], v[50:53]
	v_mfma_f32_16x16x32_bf16 v[42:45], v[216:219], v[166:169], v[42:45]
	v_mfma_f32_16x16x32_bf16 v[34:37], v[224:227], v[166:169], v[34:37]
	v_mfma_f32_16x16x32_bf16 v[26:29], v[216:219], v[200:203], v[26:29]
	v_mfma_f32_16x16x32_bf16 v[18:21], v[224:227], v[200:203], v[18:21]
	v_mfma_f32_16x16x32_bf16 v[10:13], v[216:219], v[208:211], v[10:13]
	v_mfma_f32_16x16x32_bf16 v[2:5], v[224:227], v[208:211], v[2:5]
	v_mfma_f32_16x16x32_bf16 v[58:61], v[220:223], v[162:165], v[58:61]
	v_mfma_f32_16x16x32_bf16 v[50:53], v[228:231], v[162:165], v[50:53]
	v_mfma_f32_16x16x32_bf16 v[42:45], v[220:223], v[170:173], v[42:45]
	v_mfma_f32_16x16x32_bf16 v[34:37], v[228:231], v[170:173], v[34:37]
	v_mfma_f32_16x16x32_bf16 v[26:29], v[220:223], v[204:207], v[26:29]
	v_mfma_f32_16x16x32_bf16 v[18:21], v[228:231], v[204:207], v[18:21]
	v_mfma_f32_16x16x32_bf16 v[10:13], v[220:223], v[212:215], v[10:13]
	v_mfma_f32_16x16x32_bf16 v[2:5], v[228:231], v[212:215], v[2:5]
	s_add_i32 s33, 0, 0x18000
	v_add_u32_e32 v154, s33, v131
	s_barrier
	ds_read_b128 v[142:145], v154
	ds_read_b128 v[146:149], v154 offset:1024
	ds_read_b128 v[150:153], v154 offset:2048
	ds_read_b128 v[154:157], v154 offset:3072
	s_add_u32 s22, s22, 0x40000
	s_addc_u32 s23, s23, 0
	s_mov_b32 m0, s36
	v_lshl_add_u64 v[216:217], s[22:23], 0, v[134:135]
	ds_read_b128 v[158:161], v141 offset:32768
	ds_read_b128 v[162:165], v141 offset:33792
	ds_read_b128 v[166:169], v141 offset:34816
	ds_read_b128 v[170:173], v141 offset:35840
	ds_read_b128 v[200:203], v141 offset:36864
	ds_read_b128 v[204:207], v141 offset:37888
	ds_read_b128 v[208:211], v141 offset:38912
	ds_read_b128 v[212:215], v141 offset:39936
	global_load_lds_dwordx4 v[216:217], off
	v_lshl_add_u64 v[216:217], s[22:23], 0, v[132:133]
	s_mov_b32 m0, s37
	s_nop 0
	global_load_lds_dwordx4 v[216:217], off
	s_waitcnt lgkmcnt(8)
	s_barrier
	s_waitcnt lgkmcnt(0)
	v_mfma_f32_16x16x32_bf16 v[126:129], v[142:145], v[158:161], v[126:129]
	v_mfma_f32_16x16x32_bf16 v[118:121], v[150:153], v[158:161], v[118:121]
	v_mfma_f32_16x16x32_bf16 v[110:113], v[142:145], v[166:169], v[110:113]
	v_mfma_f32_16x16x32_bf16 v[102:105], v[150:153], v[166:169], v[102:105]
	v_mfma_f32_16x16x32_bf16 v[94:97], v[142:145], v[200:203], v[94:97]
	v_mfma_f32_16x16x32_bf16 v[86:89], v[150:153], v[200:203], v[86:89]
	v_mfma_f32_16x16x32_bf16 v[78:81], v[142:145], v[208:211], v[78:81]
	v_mfma_f32_16x16x32_bf16 v[70:73], v[150:153], v[208:211], v[70:73]
	v_mfma_f32_16x16x32_bf16 v[126:129], v[146:149], v[162:165], v[126:129]
	v_mfma_f32_16x16x32_bf16 v[118:121], v[154:157], v[162:165], v[118:121]
	v_mfma_f32_16x16x32_bf16 v[110:113], v[146:149], v[170:173], v[110:113]
	v_mfma_f32_16x16x32_bf16 v[102:105], v[154:157], v[170:173], v[102:105]
	v_mfma_f32_16x16x32_bf16 v[94:97], v[146:149], v[204:207], v[94:97]
	v_mfma_f32_16x16x32_bf16 v[86:89], v[154:157], v[204:207], v[86:89]
	v_mfma_f32_16x16x32_bf16 v[78:81], v[146:149], v[212:215], v[78:81]
	v_mfma_f32_16x16x32_bf16 v[70:73], v[154:157], v[212:215], v[70:73]
	s_barrier
	s_add_i32 s22, 0, 0x1c000
	s_add_i32 s23, s33, s30
	v_add_u32_e32 v228, s22, v131
	v_lshl_add_u64 v[174:175], v[174:175], 0, s[86:87]
	s_mov_b32 m0, s23
	ds_read_b128 v[216:219], v228
	ds_read_b128 v[220:223], v228 offset:1024
	ds_read_b128 v[224:227], v228 offset:2048
	ds_read_b128 v[228:231], v228 offset:3072
	global_load_lds_dwordx4 v[174:175], off
	v_lshl_add_u64 v[174:175], v[182:183], 0, s[86:87]
	s_add_i32 m0, s23, 0x2000
	s_nop 0
	global_load_lds_dwordx4 v[174:175], off
	s_barrier
	s_waitcnt lgkmcnt(0)
	v_mfma_f32_16x16x32_bf16 v[122:125], v[216:219], v[158:161], v[122:125]
	v_mfma_f32_16x16x32_bf16 v[114:117], v[224:227], v[158:161], v[114:117]
	v_mfma_f32_16x16x32_bf16 v[106:109], v[216:219], v[166:169], v[106:109]
	v_mfma_f32_16x16x32_bf16 v[98:101], v[224:227], v[166:169], v[98:101]
	v_mfma_f32_16x16x32_bf16 v[90:93], v[216:219], v[200:203], v[90:93]
	v_mfma_f32_16x16x32_bf16 v[82:85], v[224:227], v[200:203], v[82:85]
	v_mfma_f32_16x16x32_bf16 v[74:77], v[216:219], v[208:211], v[74:77]
	v_mfma_f32_16x16x32_bf16 v[66:69], v[224:227], v[208:211], v[66:69]
	v_mfma_f32_16x16x32_bf16 v[122:125], v[220:223], v[162:165], v[122:125]
	v_mfma_f32_16x16x32_bf16 v[114:117], v[228:231], v[162:165], v[114:117]
	v_mfma_f32_16x16x32_bf16 v[106:109], v[220:223], v[170:173], v[106:109]
	v_mfma_f32_16x16x32_bf16 v[98:101], v[228:231], v[170:173], v[98:101]
	v_mfma_f32_16x16x32_bf16 v[90:93], v[220:223], v[204:207], v[90:93]
	v_mfma_f32_16x16x32_bf16 v[82:85], v[228:231], v[204:207], v[82:85]
	v_mfma_f32_16x16x32_bf16 v[74:77], v[220:223], v[212:215], v[74:77]
	v_mfma_f32_16x16x32_bf16 v[66:69], v[228:231], v[212:215], v[66:69]
	s_mov_b32 m0, s38
	v_lshl_add_u64 v[174:175], v[184:185], 0, s[86:87]
	s_barrier
	ds_read_b128 v[158:161], v141 offset:49152
	ds_read_b128 v[162:165], v141 offset:50176
	ds_read_b128 v[166:169], v141 offset:51200
	ds_read_b128 v[170:173], v141 offset:52224
	ds_read_b128 v[200:203], v141 offset:53248
	ds_read_b128 v[204:207], v141 offset:54272
	ds_read_b128 v[208:211], v141 offset:55296
	ds_read_b128 v[212:215], v141 offset:56320
	global_load_lds_dwordx4 v[174:175], off
	v_lshl_add_u64 v[174:175], v[232:233], 0, s[86:87]
	s_mov_b32 m0, s39
	s_nop 0
	global_load_lds_dwordx4 v[174:175], off
	s_barrier
; __device__ __forceinline__ float silu_f(float x) { return x * sigm(x); }
; #define PG8_MMA(ai, bj, At, Bt) do { __builtin_amdgcn_s_setprio(1); _Pragma("unroll") for (int m = 0; m < 4; ++m) _Pragma("unroll") for (int n = 0; n < 2; ++n) _Pragma("unroll") for (int k = 0; k < 2; ++k) \
;     acc[ai][bj][m][n] = __builtin_amdgcn_mfma_f32_16x16x32_bf16(Bt[n][k], At[m][k], acc[ai][bj][m][n], 0, 0, 0); __builtin_amdgcn_s_setprio(0); } while (0)
; #define PG8_WAIT_V(n) asm volatile("s_waitcnt vmcnt(" #n ")" ::: "memory")
; #define PG8_BAR __builtin_amdgcn_s_barrier()
; template <class Epi, class Sched>
; __device__ __forceinline__ void gemm_phase(PG8_LAS unsigned char* lds, const int lda, const int ldb, const Sched& S, const Epi& E) {
;     ...
;       PG8_WAIT_V(6); PG8_BAR; PG8_MMA(1, 1, At, B1); PG8_BAR;
;     }
;   __device__ __forceinline__ void operator()(const f32x4 (&acc)[2][2][4][2], const Unit& u, int wr, int wc, int fr, int fq) const {
; #pragma unroll
;     for (int ai = 0; ai < 2; ++ai)
; #pragma unroll
;       for (int m = 0; m < 4; ++m) {
;         const int r = u.pm * 256 + ai * 128 + wr * 64 + m * 16 + fr;
; #pragma unroll
;         for (int n = 0; n < 2; ++n) {
;           const f32x4 g = acc[ai][0][m][n], up = acc[ai][1][m][n];
;           const int c = u.pn * 128 + wc * 32 + n * 16 + 4 * fq;
;           uint2 w;
;           w.x = pack2(silu_f(g[0]) * up[0], silu_f(g[1]) * up[1]);
;           w.y = pack2(silu_f(g[2]) * up[2], silu_f(g[3]) * up[3]);
;           *reinterpret_cast<uint2*>(HID + (size_t)r * DFF + c) = w;
;         }
;       }
;   }
	s_waitcnt lgkmcnt(0)
	v_mfma_f32_16x16x32_bf16 v[62:65], v[142:145], v[158:161], v[62:65]
	v_mfma_f32_16x16x32_bf16 v[54:57], v[150:153], v[158:161], v[54:57]
	v_mfma_f32_16x16x32_bf16 v[46:49], v[142:145], v[166:169], v[46:49]
	v_mfma_f32_16x16x32_bf16 v[38:41], v[150:153], v[166:169], v[38:41]
	v_mfma_f32_16x16x32_bf16 v[30:33], v[142:145], v[200:203], v[30:33]
	v_mfma_f32_16x16x32_bf16 v[22:25], v[150:153], v[200:203], v[22:25]
	v_mfma_f32_16x16x32_bf16 v[14:17], v[142:145], v[208:211], v[14:17]
	v_mfma_f32_16x16x32_bf16 v[6:9], v[150:153], v[208:211], v[6:9]
	v_mfma_f32_16x16x32_bf16 v[62:65], v[146:149], v[162:165], v[62:65]
	v_mfma_f32_16x16x32_bf16 v[54:57], v[154:157], v[162:165], v[54:57]
	v_mfma_f32_16x16x32_bf16 v[46:49], v[146:149], v[170:173], v[46:49]
	v_mfma_f32_16x16x32_bf16 v[38:41], v[154:157], v[170:173], v[38:41]
	v_mfma_f32_16x16x32_bf16 v[30:33], v[146:149], v[204:207], v[30:33]
	v_mfma_f32_16x16x32_bf16 v[22:25], v[154:157], v[204:207], v[22:25]
	v_mfma_f32_16x16x32_bf16 v[14:17], v[146:149], v[212:215], v[14:17]
	v_mfma_f32_16x16x32_bf16 v[6:9], v[154:157], v[212:215], v[6:9]
	s_barrier
	s_add_u32 s20, s20, 0x40080
	s_addc_u32 s21, s21, 0
	s_add_i32 s22, s22, s30
	v_lshl_add_u64 v[142:143], s[20:21], 0, v[134:135]
	s_mov_b32 m0, s22
	s_nop 0
	global_load_lds_dwordx4 v[142:143], off
	v_lshl_add_u64 v[142:143], s[20:21], 0, v[132:133]
	s_add_i32 m0, s22, 0x2000
	s_nop 0
	global_load_lds_dwordx4 v[142:143], off
	s_waitcnt vmcnt(6)
	s_barrier
	v_mfma_f32_16x16x32_bf16 v[58:61], v[216:219], v[158:161], v[58:61]
	v_mfma_f32_16x16x32_bf16 v[50:53], v[224:227], v[158:161], v[50:53]
	v_mfma_f32_16x16x32_bf16 v[42:45], v[216:219], v[166:169], v[42:45]
	v_mfma_f32_16x16x32_bf16 v[34:37], v[224:227], v[166:169], v[34:37]
	v_mfma_f32_16x16x32_bf16 v[26:29], v[216:219], v[200:203], v[26:29]
	v_mfma_f32_16x16x32_bf16 v[18:21], v[224:227], v[200:203], v[18:21]
	v_mfma_f32_16x16x32_bf16 v[10:13], v[216:219], v[208:211], v[10:13]
	v_mfma_f32_16x16x32_bf16 v[2:5], v[224:227], v[208:211], v[2:5]
	v_mfma_f32_16x16x32_bf16 v[58:61], v[220:223], v[162:165], v[58:61]
	v_mfma_f32_16x16x32_bf16 v[50:53], v[228:231], v[162:165], v[50:53]
	v_mfma_f32_16x16x32_bf16 v[42:45], v[220:223], v[170:173], v[42:45]
	v_mfma_f32_16x16x32_bf16 v[34:37], v[228:231], v[170:173], v[34:37]
	v_mfma_f32_16x16x32_bf16 v[26:29], v[220:223], v[204:207], v[26:29]
	v_mfma_f32_16x16x32_bf16 v[18:21], v[228:231], v[204:207], v[18:21]
	v_mfma_f32_16x16x32_bf16 v[10:13], v[220:223], v[212:215], v[10:13]
	v_mfma_f32_16x16x32_bf16 v[2:5], v[228:231], v[212:215], v[2:5]
	s_add_i32 s46, s46, 2
	s_add_u32 s18, s18, 0x100
	s_addc_u32 s19, s19, 0
	s_add_u32 s44, s44, 0x100
	s_addc_u32 s45, s45, 0
	s_cmp_gt_u32 s46, 13
	s_barrier
	s_cbranch_scc0 .LBB0_1604
	v_mul_f32_e32 v143, 0xbfb8aa3b, v126
	v_exp_f32_e32 v143, v143
	v_lshl_or_b32 v144, s41, 7, v140
	v_lshl_add_u32 v142, s16, 8, v1
	v_ashrrev_i32_e32 v145, 31, v144
	v_add_f32_e32 v143, 1.0, v143
	v_rcp_f32_e32 v146, v143
	v_mul_f32_e32 v143, 0xbfb8aa3b, v127
	v_exp_f32_e32 v143, v143
	s_and_b64 vcc, exec, s[6:7]
	s_mov_b32 s41, s0
	s_mov_b32 s16, s10
	v_add_f32_e32 v143, 1.0, v143
	v_rcp_f32_e32 v147, v143
	s_mov_b64 s[20:21], s[14:15]
	v_pk_mul_f32 v[126:127], v[126:127], v[146:147]
	s_nop 0
	v_pk_mul_f32 v[122:123], v[126:127], v[122:123]
	s_nop 0
	v_cvt_pk_bf16_f32 v126, v122, v123
	v_mul_f32_e32 v122, 0xbfb8aa3b, v128
	v_mul_f32_e32 v123, 0xbfb8aa3b, v129
	v_exp_f32_e32 v122, v122
	v_exp_f32_e32 v123, v123
	v_add_f32_e32 v122, 1.0, v122
	v_add_f32_e32 v123, 1.0, v123
	v_rcp_f32_e32 v122, v122
	v_rcp_f32_e32 v123, v123
	s_nop 0
	v_pk_mul_f32 v[122:123], v[128:129], v[122:123]
	s_nop 0
	v_pk_mul_f32 v[122:123], v[122:123], v[124:125]
	v_lshlrev_b64 v[124:125], 1, v[144:145]
	v_cvt_pk_bf16_f32 v127, v122, v123
	v_mov_b64_e32 v[122:123], s[84:85]
	v_mad_i64_i32 v[128:129], s[18:19], v142, s50, v[122:123]
	v_lshl_add_u64 v[128:129], v[128:129], 0, v[124:125]
	global_store_dwordx2 v[128:129], v[126:127], off
	v_mul_f32_e32 v126, 0xbfb8aa3b, v118
	v_mul_f32_e32 v127, 0xbfb8aa3b, v119
	v_exp_f32_e32 v126, v126
	v_exp_f32_e32 v127, v127
	v_add_f32_e32 v126, 1.0, v126
	v_add_f32_e32 v127, 1.0, v127
	v_rcp_f32_e32 v126, v126
	v_rcp_f32_e32 v127, v127
	s_nop 0
	v_pk_mul_f32 v[118:119], v[118:119], v[126:127]
	s_nop 0
	v_pk_mul_f32 v[114:115], v[118:119], v[114:115]
	s_nop 0
	v_cvt_pk_bf16_f32 v114, v114, v115
	v_mul_f32_e32 v115, 0xbfb8aa3b, v120
	v_exp_f32_e32 v115, v115
	s_nop 0
	v_add_f32_e32 v115, 1.0, v115
	v_rcp_f32_e32 v118, v115
	v_mul_f32_e32 v115, 0xbfb8aa3b, v121
	v_exp_f32_e32 v115, v115
	s_nop 0
	v_add_f32_e32 v115, 1.0, v115
	v_rcp_f32_e32 v119, v115
	s_nop 0
	v_pk_mul_f32 v[118:119], v[120:121], v[118:119]
	s_nop 0
	v_pk_mul_f32 v[116:117], v[118:119], v[116:117]
	s_nop 0
	v_cvt_pk_bf16_f32 v115, v116, v117
	global_store_dwordx2 v[128:129], v[114:115], off offset:32
	v_mul_f32_e32 v114, 0xbfb8aa3b, v110
	v_mul_f32_e32 v115, 0xbfb8aa3b, v111
	v_exp_f32_e32 v114, v114
	v_exp_f32_e32 v115, v115
	v_or_b32_e32 v116, 16, v142
	v_add_f32_e32 v114, 1.0, v114
	v_add_f32_e32 v115, 1.0, v115
	v_rcp_f32_e32 v114, v114
	v_rcp_f32_e32 v115, v115
	s_nop 0
	v_pk_mul_f32 v[110:111], v[110:111], v[114:115]
	s_nop 0
	v_pk_mul_f32 v[106:107], v[110:111], v[106:107]
	s_nop 0
	v_cvt_pk_bf16_f32 v106, v106, v107
	v_mul_f32_e32 v107, 0xbfb8aa3b, v112
	v_exp_f32_e32 v107, v107
	s_nop 0
	v_add_f32_e32 v107, 1.0, v107
	v_rcp_f32_e32 v110, v107
	v_mul_f32_e32 v107, 0xbfb8aa3b, v113
	v_exp_f32_e32 v107, v107
	s_nop 0
	v_add_f32_e32 v107, 1.0, v107
	v_rcp_f32_e32 v111, v107
	s_nop 0
	v_pk_mul_f32 v[110:111], v[112:113], v[110:111]
	s_nop 0
; __device__ __forceinline__ float silu_f(float x) { return x * sigm(x); }
;   __device__ __forceinline__ void operator()(const f32x4 (&acc)[2][2][4][2], const Unit& u, int wr, int wc, int fr, int fq) const {
; #pragma unroll
;     for (int ai = 0; ai < 2; ++ai)
; #pragma unroll
;       for (int m = 0; m < 4; ++m) {
;         const int r = u.pm * 256 + ai * 128 + wr * 64 + m * 16 + fr;
; #pragma unroll
;         for (int n = 0; n < 2; ++n) {
;           const f32x4 g = acc[ai][0][m][n], up = acc[ai][1][m][n];
;           const int c = u.pn * 128 + wc * 32 + n * 16 + 4 * fq;
;           uint2 w;
;           w.x = pack2(silu_f(g[0]) * up[0], silu_f(g[1]) * up[1]);
;           w.y = pack2(silu_f(g[2]) * up[2], silu_f(g[3]) * up[3]);
;           *reinterpret_cast<uint2*>(HID + (size_t)r * DFF + c) = w;
;         }
;       }
;   }
	v_pk_mul_f32 v[108:109], v[110:111], v[108:109]
	s_nop 0
	v_cvt_pk_bf16_f32 v107, v108, v109
	v_mad_i64_i32 v[108:109], s[18:19], v116, s50, v[122:123]
	v_lshl_add_u64 v[108:109], v[108:109], 0, v[124:125]
	global_store_dwordx2 v[108:109], v[106:107], off
	v_mul_f32_e32 v106, 0xbfb8aa3b, v102
	v_mul_f32_e32 v107, 0xbfb8aa3b, v103
	v_exp_f32_e32 v106, v106
	v_exp_f32_e32 v107, v107
	v_add_f32_e32 v106, 1.0, v106
	v_add_f32_e32 v107, 1.0, v107
	v_rcp_f32_e32 v106, v106
	v_rcp_f32_e32 v107, v107
	s_nop 0
	v_pk_mul_f32 v[102:103], v[102:103], v[106:107]
	s_nop 0
	v_pk_mul_f32 v[98:99], v[102:103], v[98:99]
	s_nop 0
	v_cvt_pk_bf16_f32 v98, v98, v99
	v_mul_f32_e32 v99, 0xbfb8aa3b, v104
	v_exp_f32_e32 v99, v99
	s_nop 0
	v_add_f32_e32 v99, 1.0, v99
	v_rcp_f32_e32 v102, v99
	v_mul_f32_e32 v99, 0xbfb8aa3b, v105
	v_exp_f32_e32 v99, v99
	s_nop 0
	v_add_f32_e32 v99, 1.0, v99
	v_rcp_f32_e32 v103, v99
	s_nop 0
	v_pk_mul_f32 v[102:103], v[104:105], v[102:103]
	s_nop 0
	v_pk_mul_f32 v[100:101], v[102:103], v[100:101]
	s_nop 0
	v_cvt_pk_bf16_f32 v99, v100, v101
	global_store_dwordx2 v[108:109], v[98:99], off offset:32
	v_mul_f32_e32 v98, 0xbfb8aa3b, v94
	v_mul_f32_e32 v99, 0xbfb8aa3b, v95
	v_exp_f32_e32 v98, v98
	v_exp_f32_e32 v99, v99
	v_or_b32_e32 v100, 32, v142
	v_add_f32_e32 v98, 1.0, v98
	v_add_f32_e32 v99, 1.0, v99
	v_rcp_f32_e32 v98, v98
	v_rcp_f32_e32 v99, v99
	s_nop 0
	v_pk_mul_f32 v[94:95], v[94:95], v[98:99]
	s_nop 0
	v_pk_mul_f32 v[90:91], v[94:95], v[90:91]
	s_nop 0
	v_cvt_pk_bf16_f32 v90, v90, v91
	v_mul_f32_e32 v91, 0xbfb8aa3b, v96
	v_exp_f32_e32 v91, v91
	s_nop 0
	v_add_f32_e32 v91, 1.0, v91
	v_rcp_f32_e32 v94, v91
	v_mul_f32_e32 v91, 0xbfb8aa3b, v97
	v_exp_f32_e32 v91, v91
	s_nop 0
	v_add_f32_e32 v91, 1.0, v91
	v_rcp_f32_e32 v95, v91
	s_nop 0
	v_pk_mul_f32 v[94:95], v[96:97], v[94:95]
	s_nop 0
	v_pk_mul_f32 v[92:93], v[94:95], v[92:93]
	s_nop 0
	v_cvt_pk_bf16_f32 v91, v92, v93
	v_mad_i64_i32 v[92:93], s[18:19], v100, s50, v[122:123]
	v_lshl_add_u64 v[92:93], v[92:93], 0, v[124:125]
	global_store_dwordx2 v[92:93], v[90:91], off
	v_mul_f32_e32 v90, 0xbfb8aa3b, v86
	v_mul_f32_e32 v91, 0xbfb8aa3b, v87
	v_exp_f32_e32 v90, v90
	v_exp_f32_e32 v91, v91
	v_add_f32_e32 v90, 1.0, v90
	v_add_f32_e32 v91, 1.0, v91
	v_rcp_f32_e32 v90, v90
	v_rcp_f32_e32 v91, v91
	s_nop 0
	v_pk_mul_f32 v[86:87], v[86:87], v[90:91]
	s_nop 0
	v_pk_mul_f32 v[82:83], v[86:87], v[82:83]
	s_nop 0
	v_cvt_pk_bf16_f32 v82, v82, v83
	v_mul_f32_e32 v83, 0xbfb8aa3b, v88
	v_exp_f32_e32 v83, v83
	s_nop 0
	v_add_f32_e32 v83, 1.0, v83
	v_rcp_f32_e32 v86, v83
	v_mul_f32_e32 v83, 0xbfb8aa3b, v89
	v_exp_f32_e32 v83, v83
	s_nop 0
	v_add_f32_e32 v83, 1.0, v83
	v_rcp_f32_e32 v87, v83
	s_nop 0
	v_pk_mul_f32 v[86:87], v[88:89], v[86:87]
	s_nop 0
	v_pk_mul_f32 v[84:85], v[86:87], v[84:85]
	s_nop 0
	v_cvt_pk_bf16_f32 v83, v84, v85
	global_store_dwordx2 v[92:93], v[82:83], off offset:32
	v_mul_f32_e32 v82, 0xbfb8aa3b, v78
	v_mul_f32_e32 v83, 0xbfb8aa3b, v79
	v_exp_f32_e32 v82, v82
	v_exp_f32_e32 v83, v83
	v_or_b32_e32 v84, 48, v142
	v_add_f32_e32 v82, 1.0, v82
	v_add_f32_e32 v83, 1.0, v83
	v_rcp_f32_e32 v82, v82
	v_rcp_f32_e32 v83, v83
	s_nop 0
	v_pk_mul_f32 v[78:79], v[78:79], v[82:83]
	s_nop 0
	v_pk_mul_f32 v[74:75], v[78:79], v[74:75]
	s_nop 0
	v_cvt_pk_bf16_f32 v74, v74, v75
	v_mul_f32_e32 v75, 0xbfb8aa3b, v80
	v_exp_f32_e32 v75, v75
	s_nop 0
	v_add_f32_e32 v75, 1.0, v75
	v_rcp_f32_e32 v78, v75
	v_mul_f32_e32 v75, 0xbfb8aa3b, v81
	v_exp_f32_e32 v75, v75
	s_nop 0
	v_add_f32_e32 v75, 1.0, v75
	v_rcp_f32_e32 v79, v75
	s_nop 0
	v_pk_mul_f32 v[78:79], v[80:81], v[78:79]
	s_nop 0
	v_pk_mul_f32 v[76:77], v[78:79], v[76:77]
	s_nop 0
	v_cvt_pk_bf16_f32 v75, v76, v77
	v_mad_i64_i32 v[76:77], s[18:19], v84, s50, v[122:123]
	v_lshl_add_u64 v[76:77], v[76:77], 0, v[124:125]
	global_store_dwordx2 v[76:77], v[74:75], off
	v_mul_f32_e32 v74, 0xbfb8aa3b, v70
	v_mul_f32_e32 v75, 0xbfb8aa3b, v71
	v_exp_f32_e32 v74, v74
	v_exp_f32_e32 v75, v75
	v_add_f32_e32 v74, 1.0, v74
	v_add_f32_e32 v75, 1.0, v75
	v_rcp_f32_e32 v74, v74
	v_rcp_f32_e32 v75, v75
	s_nop 0
	v_pk_mul_f32 v[70:71], v[70:71], v[74:75]
	s_nop 0
	v_pk_mul_f32 v[66:67], v[70:71], v[66:67]
	s_nop 0
	v_cvt_pk_bf16_f32 v66, v66, v67
	v_mul_f32_e32 v67, 0xbfb8aa3b, v72
	v_exp_f32_e32 v67, v67
	s_nop 0
	v_add_f32_e32 v67, 1.0, v67
	v_rcp_f32_e32 v70, v67
	v_mul_f32_e32 v67, 0xbfb8aa3b, v73
	v_exp_f32_e32 v67, v67
	s_nop 0
	v_add_f32_e32 v67, 1.0, v67
	v_rcp_f32_e32 v71, v67
	s_nop 0
	v_pk_mul_f32 v[70:71], v[72:73], v[70:71]
	s_nop 0
	v_pk_mul_f32 v[68:69], v[70:71], v[68:69]
	s_nop 0
	v_cvt_pk_bf16_f32 v67, v68, v69
	global_store_dwordx2 v[76:77], v[66:67], off offset:32
	v_mul_f32_e32 v66, 0xbfb8aa3b, v62
	v_mul_f32_e32 v67, 0xbfb8aa3b, v63
	v_exp_f32_e32 v66, v66
	v_exp_f32_e32 v67, v67
	v_add_u32_e32 v68, 0x80, v142
	v_add_f32_e32 v66, 1.0, v66
	v_add_f32_e32 v67, 1.0, v67
	v_rcp_f32_e32 v66, v66
	v_rcp_f32_e32 v67, v67
	s_nop 0
	v_pk_mul_f32 v[62:63], v[62:63], v[66:67]
	s_nop 0
	v_pk_mul_f32 v[58:59], v[62:63], v[58:59]
	s_nop 0
	v_cvt_pk_bf16_f32 v58, v58, v59
	v_mul_f32_e32 v59, 0xbfb8aa3b, v64
	v_exp_f32_e32 v59, v59
	s_nop 0
	v_add_f32_e32 v59, 1.0, v59
	v_rcp_f32_e32 v62, v59
	v_mul_f32_e32 v59, 0xbfb8aa3b, v65
	v_exp_f32_e32 v59, v59
	s_nop 0
	v_add_f32_e32 v59, 1.0, v59
	v_rcp_f32_e32 v63, v59
	s_nop 0
	v_pk_mul_f32 v[62:63], v[64:65], v[62:63]
	s_nop 0
	v_pk_mul_f32 v[60:61], v[62:63], v[60:61]
	s_nop 0
	v_cvt_pk_bf16_f32 v59, v60, v61
	v_mad_i64_i32 v[60:61], s[18:19], v68, s50, v[122:123]
	v_lshl_add_u64 v[60:61], v[60:61], 0, v[124:125]
	global_store_dwordx2 v[60:61], v[58:59], off
	v_mul_f32_e32 v58, 0xbfb8aa3b, v54
; __device__ __forceinline__ float silu_f(float x) { return x * sigm(x); }
; #define PG8_WAIT_V(n) asm volatile("s_waitcnt vmcnt(" #n ")" ::: "memory")
; #define PG8_BAR __builtin_amdgcn_s_barrier()
;   __device__ __forceinline__ int kt(const Unit& u) const { return ((u.pn & 7) < 4) ? 4 : 16; }
; template <class Epi, class Sched>
; __device__ __forceinline__ void gemm_phase(PG8_LAS unsigned char* lds, const int lda, const int ldb, const Sched& S, const Epi& E) {
;     ...
;     E(acc, cur, wr, wc, fr, fq);
;     if (!has_next) break;
; #pragma unroll
;     for (int a = 0; a < 2; ++a)
; #pragma unroll
;       for (int b = 0; b < 2; ++b)
; #pragma unroll
;         for (int m = 0; m < 4; ++m)
; #pragma unroll
;           for (int n = 0; n < 2; ++n) acc[a][b][m][n] = (f32x4){0.f, 0.f, 0.f, 0.f};
;     cur = nxt; cA = nA; cB = nB; ++ui;
;     nt = S.kt(cur);
;   }
;   PG8_WAIT_V(0);
;   if (wr == 0) PG8_BAR;
;   PG8_BAR;
;   __device__ __forceinline__ void operator()(const f32x4 (&acc)[2][2][4][2], const Unit& u, int wr, int wc, int fr, int fq) const {
; #pragma unroll
;     for (int ai = 0; ai < 2; ++ai)
; #pragma unroll
;       for (int m = 0; m < 4; ++m) {
;         const int r = u.pm * 256 + ai * 128 + wr * 64 + m * 16 + fr;
; #pragma unroll
;         for (int n = 0; n < 2; ++n) {
;           const f32x4 g = acc[ai][0][m][n], up = acc[ai][1][m][n];
;           const int c = u.pn * 128 + wc * 32 + n * 16 + 4 * fq;
;           uint2 w;
;           w.x = pack2(silu_f(g[0]) * up[0], silu_f(g[1]) * up[1]);
;           w.y = pack2(silu_f(g[2]) * up[2], silu_f(g[3]) * up[3]);
;           *reinterpret_cast<uint2*>(HID + (size_t)r * DFF + c) = w;
;         }
;       }
;   }
	v_mul_f32_e32 v59, 0xbfb8aa3b, v55
	v_exp_f32_e32 v58, v58
	v_exp_f32_e32 v59, v59
	v_add_f32_e32 v58, 1.0, v58
	v_add_f32_e32 v59, 1.0, v59
	v_rcp_f32_e32 v58, v58
	v_rcp_f32_e32 v59, v59
	s_nop 0
	v_pk_mul_f32 v[54:55], v[54:55], v[58:59]
	s_nop 0
	v_pk_mul_f32 v[50:51], v[54:55], v[50:51]
	s_nop 0
	v_cvt_pk_bf16_f32 v50, v50, v51
	v_mul_f32_e32 v51, 0xbfb8aa3b, v56
	v_exp_f32_e32 v51, v51
	s_nop 0
	v_add_f32_e32 v51, 1.0, v51
	v_rcp_f32_e32 v54, v51
	v_mul_f32_e32 v51, 0xbfb8aa3b, v57
	v_exp_f32_e32 v51, v51
	s_nop 0
	v_add_f32_e32 v51, 1.0, v51
	v_rcp_f32_e32 v55, v51
	s_nop 0
	v_pk_mul_f32 v[54:55], v[56:57], v[54:55]
	s_nop 0
	v_pk_mul_f32 v[52:53], v[54:55], v[52:53]
	s_nop 0
	v_cvt_pk_bf16_f32 v51, v52, v53
	global_store_dwordx2 v[60:61], v[50:51], off offset:32
	v_mul_f32_e32 v50, 0xbfb8aa3b, v46
	v_mul_f32_e32 v51, 0xbfb8aa3b, v47
	v_exp_f32_e32 v50, v50
	v_exp_f32_e32 v51, v51
	v_add_u32_e32 v52, 0x90, v142
	v_add_f32_e32 v50, 1.0, v50
	v_add_f32_e32 v51, 1.0, v51
	v_rcp_f32_e32 v50, v50
	v_rcp_f32_e32 v51, v51
	s_nop 0
	v_pk_mul_f32 v[46:47], v[46:47], v[50:51]
	s_nop 0
	v_pk_mul_f32 v[42:43], v[46:47], v[42:43]
	s_nop 0
	v_cvt_pk_bf16_f32 v42, v42, v43
	v_mul_f32_e32 v43, 0xbfb8aa3b, v48
	v_exp_f32_e32 v43, v43
	s_nop 0
	v_add_f32_e32 v43, 1.0, v43
	v_rcp_f32_e32 v46, v43
	v_mul_f32_e32 v43, 0xbfb8aa3b, v49
	v_exp_f32_e32 v43, v43
	s_nop 0
	v_add_f32_e32 v43, 1.0, v43
	v_rcp_f32_e32 v47, v43
	s_nop 0
	v_pk_mul_f32 v[46:47], v[48:49], v[46:47]
	s_nop 0
	v_pk_mul_f32 v[44:45], v[46:47], v[44:45]
	s_nop 0
	v_cvt_pk_bf16_f32 v43, v44, v45
	v_mad_i64_i32 v[44:45], s[18:19], v52, s50, v[122:123]
	v_lshl_add_u64 v[44:45], v[44:45], 0, v[124:125]
	global_store_dwordx2 v[44:45], v[42:43], off
	v_mul_f32_e32 v42, 0xbfb8aa3b, v38
	v_mul_f32_e32 v43, 0xbfb8aa3b, v39
	v_exp_f32_e32 v42, v42
	v_exp_f32_e32 v43, v43
	v_add_f32_e32 v42, 1.0, v42
	v_add_f32_e32 v43, 1.0, v43
	v_rcp_f32_e32 v42, v42
	v_rcp_f32_e32 v43, v43
	s_nop 0
	v_pk_mul_f32 v[38:39], v[38:39], v[42:43]
	s_nop 0
	v_pk_mul_f32 v[34:35], v[38:39], v[34:35]
	s_nop 0
	v_cvt_pk_bf16_f32 v34, v34, v35
	v_mul_f32_e32 v35, 0xbfb8aa3b, v40
	v_exp_f32_e32 v35, v35
	s_nop 0
	v_add_f32_e32 v35, 1.0, v35
	v_rcp_f32_e32 v38, v35
	v_mul_f32_e32 v35, 0xbfb8aa3b, v41
	v_exp_f32_e32 v35, v35
	s_nop 0
	v_add_f32_e32 v35, 1.0, v35
	v_rcp_f32_e32 v39, v35
	s_nop 0
	v_pk_mul_f32 v[38:39], v[40:41], v[38:39]
	s_nop 0
	v_pk_mul_f32 v[36:37], v[38:39], v[36:37]
	s_nop 0
	v_cvt_pk_bf16_f32 v35, v36, v37
	global_store_dwordx2 v[44:45], v[34:35], off offset:32
	v_mul_f32_e32 v34, 0xbfb8aa3b, v30
	v_mul_f32_e32 v35, 0xbfb8aa3b, v31
	v_exp_f32_e32 v34, v34
	v_exp_f32_e32 v35, v35
	v_add_u32_e32 v36, 0xa0, v142
	v_add_f32_e32 v34, 1.0, v34
	v_add_f32_e32 v35, 1.0, v35
	v_rcp_f32_e32 v34, v34
	v_rcp_f32_e32 v35, v35
	s_nop 0
	v_pk_mul_f32 v[30:31], v[30:31], v[34:35]
	s_nop 0
	v_pk_mul_f32 v[26:27], v[30:31], v[26:27]
	s_nop 0
	v_cvt_pk_bf16_f32 v26, v26, v27
	v_mul_f32_e32 v27, 0xbfb8aa3b, v32
	v_exp_f32_e32 v27, v27
	s_nop 0
	v_add_f32_e32 v27, 1.0, v27
	v_rcp_f32_e32 v30, v27
	v_mul_f32_e32 v27, 0xbfb8aa3b, v33
	v_exp_f32_e32 v27, v27
	s_nop 0
	v_add_f32_e32 v27, 1.0, v27
	v_rcp_f32_e32 v31, v27
	s_nop 0
	v_pk_mul_f32 v[30:31], v[32:33], v[30:31]
	s_nop 0
	v_pk_mul_f32 v[28:29], v[30:31], v[28:29]
	s_nop 0
	v_cvt_pk_bf16_f32 v27, v28, v29
	v_mad_i64_i32 v[28:29], s[18:19], v36, s50, v[122:123]
	v_lshl_add_u64 v[28:29], v[28:29], 0, v[124:125]
	global_store_dwordx2 v[28:29], v[26:27], off
	v_mul_f32_e32 v26, 0xbfb8aa3b, v22
	v_mul_f32_e32 v27, 0xbfb8aa3b, v23
	v_exp_f32_e32 v26, v26
	v_exp_f32_e32 v27, v27
	v_add_f32_e32 v26, 1.0, v26
	v_add_f32_e32 v27, 1.0, v27
	v_rcp_f32_e32 v26, v26
	v_rcp_f32_e32 v27, v27
	s_nop 0
	v_pk_mul_f32 v[22:23], v[22:23], v[26:27]
	s_nop 0
	v_pk_mul_f32 v[18:19], v[22:23], v[18:19]
	s_nop 0
	v_cvt_pk_bf16_f32 v18, v18, v19
	v_mul_f32_e32 v19, 0xbfb8aa3b, v24
	v_exp_f32_e32 v19, v19
	s_nop 0
	v_add_f32_e32 v19, 1.0, v19
	v_rcp_f32_e32 v22, v19
	v_mul_f32_e32 v19, 0xbfb8aa3b, v25
	v_exp_f32_e32 v19, v19
	s_nop 0
	v_add_f32_e32 v19, 1.0, v19
	v_rcp_f32_e32 v23, v19
	s_nop 0
	v_pk_mul_f32 v[22:23], v[24:25], v[22:23]
	s_nop 0
	v_pk_mul_f32 v[20:21], v[22:23], v[20:21]
	s_nop 0
	v_cvt_pk_bf16_f32 v19, v20, v21
	global_store_dwordx2 v[28:29], v[18:19], off offset:32
	v_mul_f32_e32 v18, 0xbfb8aa3b, v14
	v_mul_f32_e32 v19, 0xbfb8aa3b, v15
	v_exp_f32_e32 v18, v18
	v_exp_f32_e32 v19, v19
	v_add_u32_e32 v20, 0xb0, v142
	v_add_f32_e32 v18, 1.0, v18
	v_add_f32_e32 v19, 1.0, v19
	v_rcp_f32_e32 v18, v18
	v_rcp_f32_e32 v19, v19
	s_nop 0
	v_pk_mul_f32 v[14:15], v[14:15], v[18:19]
	s_nop 0
	v_pk_mul_f32 v[10:11], v[14:15], v[10:11]
	s_nop 0
	v_cvt_pk_bf16_f32 v10, v10, v11
	v_mul_f32_e32 v11, 0xbfb8aa3b, v16
	v_exp_f32_e32 v11, v11
	s_nop 0
	v_add_f32_e32 v11, 1.0, v11
	v_rcp_f32_e32 v14, v11
	v_mul_f32_e32 v11, 0xbfb8aa3b, v17
	v_exp_f32_e32 v11, v11
	s_nop 0
	v_add_f32_e32 v11, 1.0, v11
	v_rcp_f32_e32 v15, v11
	s_nop 0
	v_pk_mul_f32 v[14:15], v[16:17], v[14:15]
	s_nop 0
	v_pk_mul_f32 v[12:13], v[14:15], v[12:13]
	s_nop 0
	v_cvt_pk_bf16_f32 v11, v12, v13
	v_mad_i64_i32 v[12:13], s[18:19], v20, s50, v[122:123]
	v_lshl_add_u64 v[12:13], v[12:13], 0, v[124:125]
	global_store_dwordx2 v[12:13], v[10:11], off
	v_mul_f32_e32 v10, 0xbfb8aa3b, v6
	v_mul_f32_e32 v11, 0xbfb8aa3b, v7
	v_exp_f32_e32 v10, v10
	v_exp_f32_e32 v11, v11
	s_mov_b64 s[18:19], s[12:13]
	v_add_f32_e32 v10, 1.0, v10
	v_add_f32_e32 v11, 1.0, v11
	v_rcp_f32_e32 v10, v10
	v_rcp_f32_e32 v11, v11
	s_nop 0
	v_pk_mul_f32 v[6:7], v[6:7], v[10:11]
	s_nop 0
	v_pk_mul_f32 v[2:3], v[6:7], v[2:3]
	s_nop 0
	v_cvt_pk_bf16_f32 v2, v2, v3
	v_mul_f32_e32 v3, 0xbfb8aa3b, v8
	v_exp_f32_e32 v3, v3
	s_nop 0
	v_add_f32_e32 v3, 1.0, v3
	v_rcp_f32_e32 v6, v3
	v_mul_f32_e32 v3, 0xbfb8aa3b, v9
	v_exp_f32_e32 v3, v3
	s_nop 0
	v_add_f32_e32 v3, 1.0, v3
	v_rcp_f32_e32 v7, v3
	s_nop 0
	v_pk_mul_f32 v[6:7], v[8:9], v[6:7]
	s_nop 0
	v_pk_mul_f32 v[4:5], v[6:7], v[4:5]
	s_nop 0
	v_cvt_pk_bf16_f32 v3, v4, v5
	global_store_dwordx2 v[12:13], v[2:3], off offset:32
	s_cbranch_vccz .LBB0_1601
	s_waitcnt vmcnt(0)
	v_readlane_b32 s40, v253, 12
	s_cmpk_gt_u32 s9, 0xff
	v_readlane_b32 s41, v253, 13
	v_readlane_b32 s44, v253, 16
	v_readlane_b32 s45, v253, 17
	v_readlane_b32 s52, v253, 24
	v_readlane_b32 s53, v253, 25
	v_readlane_b32 s54, v253, 26
	v_readlane_b32 s55, v253, 27
	v_readlane_b32 s38, v255, 23
	v_readlane_b32 s42, v253, 14
	v_readlane_b32 s43, v253, 15
	v_readlane_b32 s46, v253, 18
	v_readlane_b32 s47, v253, 19
	v_readlane_b32 s48, v253, 20
	v_readlane_b32 s49, v253, 21
	v_readlane_b32 s50, v253, 22
	v_readlane_b32 s51, v253, 23
	v_readlane_b32 s39, v255, 24
	s_cbranch_scc1 .LBB0_1608
	s_barrier

; #define PG8_STAGE(bufoff, gbase, voff) do { _Pragma("unroll") for (int _i = 0; _i < 2; ++_i) \
;     __builtin_amdgcn_global_load_lds((const unsigned*)((const char*)(gbase) + (voff)[_i]), (PG8_LAS unsigned*)(lds + (bufoff) + ldsw + _i * 8192), 16, 0, 0); } while (0)
; #define PG8_LDA(dst, b, h) do { _Pragma("unroll") for (int m = 0; m < 4; ++m) _Pragma("unroll") for (int k = 0; k < 2; ++k) dst[m][k] = *(const PG8_LAS bf16x8*)(lds + PG8_SA(b, h) + aoff + m * 2048 + k * 1024); } while (0)
; #define PG8_LDB(dst, b, h) do { _Pragma("unroll") for (int n = 0; n < 2; ++n) _Pragma("unroll") for (int k = 0; k < 2; ++k) dst[n][k] = *(const PG8_LAS bf16x8*)(lds + PG8_SB(b, h) + boff + n * 2048 + k * 1024); } while (0)
; #define PG8_MMA(ai, bj, At, Bt) do { __builtin_amdgcn_s_setprio(1); _Pragma("unroll") for (int m = 0; m < 4; ++m) _Pragma("unroll") for (int n = 0; n < 2; ++n) _Pragma("unroll") for (int k = 0; k < 2; ++k) \
;     acc[ai][bj][m][n] = __builtin_amdgcn_mfma_f32_16x16x32_bf16(Bt[n][k], At[m][k], acc[ai][bj][m][n], 0, 0, 0); __builtin_amdgcn_s_setprio(0); } while (0)
; #define PG8_WAIT_L(n) asm volatile("s_waitcnt lgkmcnt(" #n ")" ::: "memory")
; #define PG8_BAR __builtin_amdgcn_s_barrier()
; #define PG8_SCHED __builtin_amdgcn_sched_barrier(0)
; template <class Epi, class Sched>
; __device__ __forceinline__ void gemm_phase(PG8_LAS unsigned char* lds, const int lda, const int ldb, const Sched& S, const Epi& E) {
;     ...
;     for (int t = 0; t < nt; t += 2) {
;       const bool last = (t == nt - 2);
;       const char* a1 = cA + (size_t)(t + 1) * kstep;
;       const char* a2 = last ? nA : cA + (size_t)(t + 2) * kstep; const char* b2 = last ? nB : cB + (size_t)(t + 2) * kstep;
;       const char* a3 = a2 + kstep; const char* b3 = b2 + kstep;
;       PG8_LDB(B0, 0, 0); PG8_SCHED; PG8_LDA(At, 0, 0); PG8_STAGE(PG8_SA(1, 1), a1 + hstepA, voffA);
;       PG8_WAIT_L(8); PG8_BAR; PG8_WAIT_L(0); PG8_MMA(0, 0, At, B0); PG8_BAR; PG8_SCHED;
;       PG8_LDB(B1, 0, 1); PG8_STAGE(PG8_SB(0, 0), b2, voffB);
;       PG8_BAR; PG8_WAIT_L(0); PG8_MMA(0, 1, At, B1); PG8_BAR;
;       PG8_LDA(At, 0, 1); PG8_STAGE(PG8_SA(0, 0), a2, voffA);
;       PG8_BAR; PG8_WAIT_L(0); PG8_MMA(1, 0, At, B0); PG8_BAR; PG8_SCHED;
.LBB0_1673:
	s_add_u32 s12, s10, 0x100
	s_addc_u32 s13, s11, 0
	s_add_i32 s33, 0, 0x10000
	v_add_u32_e32 v154, s33, v131
	ds_read_b128 v[140:143], v154
	ds_read_b128 v[146:149], v154 offset:1024
	ds_read_b128 v[150:153], v154 offset:2048
	ds_read_b128 v[154:157], v154 offset:3072
	s_cmp_eq_u32 s41, 40
	s_cselect_b32 s17, s7, s13
	s_cselect_b32 s16, s6, s12
	s_cselect_b32 s15, s1, s40
	s_cselect_b32 s14, s0, s39
	v_lshl_add_u64 v[174:175], s[10:11], 0, v[136:137]
	s_add_i32 m0, s23, 0xc000
	ds_read_b128 v[158:161], v145
	ds_read_b128 v[162:165], v145 offset:1024
	ds_read_b128 v[166:169], v145 offset:2048
	ds_read_b128 v[170:173], v145 offset:3072
	ds_read_b128 v[200:203], v145 offset:4096
	ds_read_b128 v[204:207], v145 offset:5120
	ds_read_b128 v[208:211], v145 offset:6144
	ds_read_b128 v[212:215], v145 offset:7168
	global_load_lds_dwordx4 v[174:175], off
	v_lshl_add_u64 v[174:175], s[10:11], 0, v[138:139]
	s_add_i32 m0, s23, 0xe000
	s_nop 0
	global_load_lds_dwordx4 v[174:175], off
	s_waitcnt lgkmcnt(8)
	s_barrier
	s_waitcnt lgkmcnt(0)
	v_mfma_f32_16x16x32_bf16 v[126:129], v[140:143], v[158:161], v[126:129]
	v_mfma_f32_16x16x32_bf16 v[122:125], v[150:153], v[158:161], v[122:125]
	v_mfma_f32_16x16x32_bf16 v[110:113], v[140:143], v[166:169], v[110:113]
	v_mfma_f32_16x16x32_bf16 v[106:109], v[150:153], v[166:169], v[106:109]
	v_mfma_f32_16x16x32_bf16 v[94:97], v[140:143], v[200:203], v[94:97]
	v_mfma_f32_16x16x32_bf16 v[90:93], v[150:153], v[200:203], v[90:93]
	v_mfma_f32_16x16x32_bf16 v[78:81], v[140:143], v[208:211], v[78:81]
	v_mfma_f32_16x16x32_bf16 v[74:77], v[150:153], v[208:211], v[74:77]
	v_mfma_f32_16x16x32_bf16 v[126:129], v[146:149], v[162:165], v[126:129]
	v_mfma_f32_16x16x32_bf16 v[122:125], v[154:157], v[162:165], v[122:125]
	v_mfma_f32_16x16x32_bf16 v[110:113], v[146:149], v[170:173], v[110:113]
	v_mfma_f32_16x16x32_bf16 v[106:109], v[154:157], v[170:173], v[106:109]
	v_mfma_f32_16x16x32_bf16 v[94:97], v[146:149], v[204:207], v[94:97]
	v_mfma_f32_16x16x32_bf16 v[90:93], v[154:157], v[204:207], v[90:93]
	v_mfma_f32_16x16x32_bf16 v[78:81], v[146:149], v[212:215], v[78:81]
	v_mfma_f32_16x16x32_bf16 v[74:77], v[154:157], v[212:215], v[74:77]
	s_barrier
	s_add_i32 s42, 0, 0x14000
	v_add_u32_e32 v174, s42, v131
	s_add_i32 s10, s33, s20
	ds_read_b128 v[216:219], v174
	ds_read_b128 v[220:223], v174 offset:1024
	ds_read_b128 v[224:227], v174 offset:2048
	ds_read_b128 v[228:231], v174 offset:3072
	v_lshl_add_u64 v[174:175], s[14:15], 0, v[134:135]
	s_mov_b32 m0, s10
	v_lshl_add_u64 v[182:183], s[14:15], 0, v[132:133]
	global_load_lds_dwordx4 v[174:175], off
	s_add_i32 m0, s10, 0x2000
	s_nop 0
	global_load_lds_dwordx4 v[182:183], off
	s_barrier
	s_waitcnt lgkmcnt(0)
	v_mfma_f32_16x16x32_bf16 v[118:121], v[216:219], v[158:161], v[118:121]
	v_mfma_f32_16x16x32_bf16 v[114:117], v[224:227], v[158:161], v[114:117]
	v_mfma_f32_16x16x32_bf16 v[102:105], v[216:219], v[166:169], v[102:105]
	v_mfma_f32_16x16x32_bf16 v[98:101], v[224:227], v[166:169], v[98:101]
	v_mfma_f32_16x16x32_bf16 v[86:89], v[216:219], v[200:203], v[86:89]
	v_mfma_f32_16x16x32_bf16 v[82:85], v[224:227], v[200:203], v[82:85]
	v_mfma_f32_16x16x32_bf16 v[70:73], v[216:219], v[208:211], v[70:73]
	v_mfma_f32_16x16x32_bf16 v[66:69], v[224:227], v[208:211], v[66:69]
	v_mfma_f32_16x16x32_bf16 v[118:121], v[220:223], v[162:165], v[118:121]
	v_mfma_f32_16x16x32_bf16 v[114:117], v[228:231], v[162:165], v[114:117]
	v_mfma_f32_16x16x32_bf16 v[102:105], v[220:223], v[170:173], v[102:105]
	v_mfma_f32_16x16x32_bf16 v[98:101], v[228:231], v[170:173], v[98:101]
	v_mfma_f32_16x16x32_bf16 v[86:89], v[220:223], v[204:207], v[86:89]
	v_mfma_f32_16x16x32_bf16 v[82:85], v[228:231], v[204:207], v[82:85]
	v_mfma_f32_16x16x32_bf16 v[70:73], v[220:223], v[212:215], v[70:73]
	v_mfma_f32_16x16x32_bf16 v[66:69], v[228:231], v[212:215], v[66:69]
	s_mov_b32 m0, s23
	v_lshl_add_u64 v[184:185], s[16:17], 0, v[134:135]
	s_barrier
	ds_read_b128 v[158:161], v145 offset:16384
	ds_read_b128 v[162:165], v145 offset:17408
	ds_read_b128 v[166:169], v145 offset:18432
	ds_read_b128 v[170:173], v145 offset:19456
	ds_read_b128 v[200:203], v145 offset:20480
	ds_read_b128 v[204:207], v145 offset:21504
	ds_read_b128 v[208:211], v145 offset:22528
	ds_read_b128 v[212:215], v145 offset:23552
	global_load_lds_dwordx4 v[184:185], off
	v_lshl_add_u64 v[232:233], s[16:17], 0, v[132:133]
	s_mov_b32 m0, s24
	s_nop 0
	global_load_lds_dwordx4 v[232:233], off
	s_barrier
	s_waitcnt lgkmcnt(0)
	v_mfma_f32_16x16x32_bf16 v[62:65], v[140:143], v[158:161], v[62:65]
	v_mfma_f32_16x16x32_bf16 v[58:61], v[150:153], v[158:161], v[58:61]
	v_mfma_f32_16x16x32_bf16 v[46:49], v[140:143], v[166:169], v[46:49]
	v_mfma_f32_16x16x32_bf16 v[42:45], v[150:153], v[166:169], v[42:45]
	v_mfma_f32_16x16x32_bf16 v[30:33], v[140:143], v[200:203], v[30:33]
	v_mfma_f32_16x16x32_bf16 v[26:29], v[150:153], v[200:203], v[26:29]
	v_mfma_f32_16x16x32_bf16 v[14:17], v[140:143], v[208:211], v[14:17]
	v_mfma_f32_16x16x32_bf16 v[10:13], v[150:153], v[208:211], v[10:13]
	v_mfma_f32_16x16x32_bf16 v[62:65], v[146:149], v[162:165], v[62:65]
	v_mfma_f32_16x16x32_bf16 v[58:61], v[154:157], v[162:165], v[58:61]
	v_mfma_f32_16x16x32_bf16 v[46:49], v[146:149], v[170:173], v[46:49]
	v_mfma_f32_16x16x32_bf16 v[42:45], v[154:157], v[170:173], v[42:45]
	v_mfma_f32_16x16x32_bf16 v[30:33], v[146:149], v[204:207], v[30:33]
	v_mfma_f32_16x16x32_bf16 v[26:29], v[154:157], v[204:207], v[26:29]
	v_mfma_f32_16x16x32_bf16 v[14:17], v[146:149], v[212:215], v[14:17]
	v_mfma_f32_16x16x32_bf16 v[10:13], v[154:157], v[212:215], v[10:13]
	s_barrier
; #define PG8_STAGE(bufoff, gbase, voff) do { _Pragma("unroll") for (int _i = 0; _i < 2; ++_i) \
;     __builtin_amdgcn_global_load_lds((const unsigned*)((const char*)(gbase) + (voff)[_i]), (PG8_LAS unsigned*)(lds + (bufoff) + ldsw + _i * 8192), 16, 0, 0); } while (0)
; #define PG8_LDA(dst, b, h) do { _Pragma("unroll") for (int m = 0; m < 4; ++m) _Pragma("unroll") for (int k = 0; k < 2; ++k) dst[m][k] = *(const PG8_LAS bf16x8*)(lds + PG8_SA(b, h) + aoff + m * 2048 + k * 1024); } while (0)
; #define PG8_LDB(dst, b, h) do { _Pragma("unroll") for (int n = 0; n < 2; ++n) _Pragma("unroll") for (int k = 0; k < 2; ++k) dst[n][k] = *(const PG8_LAS bf16x8*)(lds + PG8_SB(b, h) + boff + n * 2048 + k * 1024); } while (0)
; #define PG8_MMA(ai, bj, At, Bt) do { __builtin_amdgcn_s_setprio(1); _Pragma("unroll") for (int m = 0; m < 4; ++m) _Pragma("unroll") for (int n = 0; n < 2; ++n) _Pragma("unroll") for (int k = 0; k < 2; ++k) \
;     acc[ai][bj][m][n] = __builtin_amdgcn_mfma_f32_16x16x32_bf16(Bt[n][k], At[m][k], acc[ai][bj][m][n], 0, 0, 0); __builtin_amdgcn_s_setprio(0); } while (0)
; #define PG8_WAIT_V(n) asm volatile("s_waitcnt vmcnt(" #n ")" ::: "memory")
; #define PG8_WAIT_L(n) asm volatile("s_waitcnt lgkmcnt(" #n ")" ::: "memory")
; #define PG8_BAR __builtin_amdgcn_s_barrier()
; #define PG8_SCHED __builtin_amdgcn_sched_barrier(0)
; template <class Epi, class Sched>
; __device__ __forceinline__ void gemm_phase(PG8_LAS unsigned char* lds, const int lda, const int ldb, const Sched& S, const Epi& E) {
;     ...
;       PG8_STAGE(PG8_SB(0, 1), b2 + hstepB, voffB);
;       PG8_WAIT_V(6); PG8_BAR; PG8_MMA(1, 1, At, B1); PG8_BAR;
;       PG8_LDB(B0, 1, 0); PG8_SCHED; PG8_LDA(At, 1, 0); PG8_STAGE(PG8_SA(0, 1), a2 + hstepA, voffA);
;       PG8_WAIT_L(8); PG8_BAR; PG8_WAIT_L(0); PG8_MMA(0, 0, At, B0); PG8_BAR; PG8_SCHED;
;       PG8_LDB(B1, 1, 1); PG8_STAGE(PG8_SB(1, 0), b3, voffB);
;       PG8_BAR; PG8_WAIT_L(0); PG8_MMA(0, 1, At, B1); PG8_BAR;
;       PG8_LDA(At, 1, 1); PG8_STAGE(PG8_SA(1, 0), a3, voffA);
	s_add_u32 s10, s14, 0xb0000
	s_addc_u32 s11, s15, 0
	s_add_i32 s33, s42, s20
	v_lshl_add_u64 v[140:141], s[10:11], 0, v[134:135]
	s_mov_b32 m0, s33
	s_nop 0
	global_load_lds_dwordx4 v[140:141], off
	v_lshl_add_u64 v[140:141], s[10:11], 0, v[132:133]
	s_add_i32 m0, s33, 0x2000
	s_nop 0
	global_load_lds_dwordx4 v[140:141], off
	s_waitcnt vmcnt(6)
	s_barrier
	v_mfma_f32_16x16x32_bf16 v[54:57], v[216:219], v[158:161], v[54:57]
	v_mfma_f32_16x16x32_bf16 v[50:53], v[224:227], v[158:161], v[50:53]
	v_mfma_f32_16x16x32_bf16 v[38:41], v[216:219], v[166:169], v[38:41]
	v_mfma_f32_16x16x32_bf16 v[34:37], v[224:227], v[166:169], v[34:37]
	v_mfma_f32_16x16x32_bf16 v[22:25], v[216:219], v[200:203], v[22:25]
	v_mfma_f32_16x16x32_bf16 v[18:21], v[224:227], v[200:203], v[18:21]
	v_mfma_f32_16x16x32_bf16 v[6:9], v[216:219], v[208:211], v[6:9]
	v_mfma_f32_16x16x32_bf16 v[2:5], v[224:227], v[208:211], v[2:5]
	v_mfma_f32_16x16x32_bf16 v[54:57], v[220:223], v[162:165], v[54:57]
	v_mfma_f32_16x16x32_bf16 v[50:53], v[228:231], v[162:165], v[50:53]
	v_mfma_f32_16x16x32_bf16 v[38:41], v[220:223], v[170:173], v[38:41]
	v_mfma_f32_16x16x32_bf16 v[34:37], v[228:231], v[170:173], v[34:37]
	v_mfma_f32_16x16x32_bf16 v[22:25], v[220:223], v[204:207], v[22:25]
	v_mfma_f32_16x16x32_bf16 v[18:21], v[228:231], v[204:207], v[18:21]
	v_mfma_f32_16x16x32_bf16 v[6:9], v[220:223], v[212:215], v[6:9]
	v_mfma_f32_16x16x32_bf16 v[2:5], v[228:231], v[212:215], v[2:5]
	s_add_i32 s33, 0, 0x18000
	v_add_u32_e32 v154, s33, v131
	s_barrier
	ds_read_b128 v[140:143], v154
	ds_read_b128 v[146:149], v154 offset:1024
	ds_read_b128 v[150:153], v154 offset:2048
	ds_read_b128 v[154:157], v154 offset:3072
	s_add_u32 s10, s16, 0xb0000
	s_addc_u32 s11, s17, 0
	s_mov_b32 m0, s25
	v_lshl_add_u64 v[216:217], s[10:11], 0, v[134:135]
	ds_read_b128 v[158:161], v145 offset:32768
	ds_read_b128 v[162:165], v145 offset:33792
	ds_read_b128 v[166:169], v145 offset:34816
	ds_read_b128 v[170:173], v145 offset:35840
	ds_read_b128 v[200:203], v145 offset:36864
	ds_read_b128 v[204:207], v145 offset:37888
	ds_read_b128 v[208:211], v145 offset:38912
	ds_read_b128 v[212:215], v145 offset:39936
	global_load_lds_dwordx4 v[216:217], off
	v_lshl_add_u64 v[216:217], s[10:11], 0, v[132:133]
	s_mov_b32 m0, s26
	s_nop 0
	global_load_lds_dwordx4 v[216:217], off
	s_waitcnt lgkmcnt(8)
	s_barrier
	s_waitcnt lgkmcnt(0)
	v_mfma_f32_16x16x32_bf16 v[126:129], v[140:143], v[158:161], v[126:129]
	v_mfma_f32_16x16x32_bf16 v[122:125], v[150:153], v[158:161], v[122:125]
	v_mfma_f32_16x16x32_bf16 v[110:113], v[140:143], v[166:169], v[110:113]
	v_mfma_f32_16x16x32_bf16 v[106:109], v[150:153], v[166:169], v[106:109]
	v_mfma_f32_16x16x32_bf16 v[94:97], v[140:143], v[200:203], v[94:97]
	v_mfma_f32_16x16x32_bf16 v[90:93], v[150:153], v[200:203], v[90:93]
	v_mfma_f32_16x16x32_bf16 v[78:81], v[140:143], v[208:211], v[78:81]
	v_mfma_f32_16x16x32_bf16 v[74:77], v[150:153], v[208:211], v[74:77]
	v_mfma_f32_16x16x32_bf16 v[126:129], v[146:149], v[162:165], v[126:129]
	v_mfma_f32_16x16x32_bf16 v[122:125], v[154:157], v[162:165], v[122:125]
	v_mfma_f32_16x16x32_bf16 v[110:113], v[146:149], v[170:173], v[110:113]
	v_mfma_f32_16x16x32_bf16 v[106:109], v[154:157], v[170:173], v[106:109]
	v_mfma_f32_16x16x32_bf16 v[94:97], v[146:149], v[204:207], v[94:97]
	v_mfma_f32_16x16x32_bf16 v[90:93], v[154:157], v[204:207], v[90:93]
	v_mfma_f32_16x16x32_bf16 v[78:81], v[146:149], v[212:215], v[78:81]
	v_mfma_f32_16x16x32_bf16 v[74:77], v[154:157], v[212:215], v[74:77]
	s_barrier
	s_add_i32 s16, 0, 0x1c000
	s_add_i32 s10, s33, s20
	v_add_u32_e32 v228, s16, v131
	v_lshl_add_u64 v[174:175], v[174:175], 0, s[86:87]
	s_mov_b32 m0, s10
	ds_read_b128 v[216:219], v228
	ds_read_b128 v[220:223], v228 offset:1024
	ds_read_b128 v[224:227], v228 offset:2048
	ds_read_b128 v[228:231], v228 offset:3072
	global_load_lds_dwordx4 v[174:175], off
	v_lshl_add_u64 v[174:175], v[182:183], 0, s[86:87]
	s_add_i32 m0, s10, 0x2000
	s_nop 0
	global_load_lds_dwordx4 v[174:175], off
	s_barrier
; #define PG8_STAGE(bufoff, gbase, voff) do { _Pragma("unroll") for (int _i = 0; _i < 2; ++_i) \
;     __builtin_amdgcn_global_load_lds((const unsigned*)((const char*)(gbase) + (voff)[_i]), (PG8_LAS unsigned*)(lds + (bufoff) + ldsw + _i * 8192), 16, 0, 0); } while (0)
; #define PG8_MMA(ai, bj, At, Bt) do { __builtin_amdgcn_s_setprio(1); _Pragma("unroll") for (int m = 0; m < 4; ++m) _Pragma("unroll") for (int n = 0; n < 2; ++n) _Pragma("unroll") for (int k = 0; k < 2; ++k) \
;     acc[ai][bj][m][n] = __builtin_amdgcn_mfma_f32_16x16x32_bf16(Bt[n][k], At[m][k], acc[ai][bj][m][n], 0, 0, 0); __builtin_amdgcn_s_setprio(0); } while (0)
; #define PG8_WAIT_V(n) asm volatile("s_waitcnt vmcnt(" #n ")" ::: "memory")
; #define PG8_WAIT_L(n) asm volatile("s_waitcnt lgkmcnt(" #n ")" ::: "memory")
; #define PG8_BAR __builtin_amdgcn_s_barrier()
; #define PG8_SCHED __builtin_amdgcn_sched_barrier(0)
; template <class Epi, class Sched>
; __device__ __forceinline__ void gemm_phase(PG8_LAS unsigned char* lds, const int lda, const int ldb, const Sched& S, const Epi& E) {
;     ...
;       PG8_BAR; PG8_WAIT_L(0); PG8_MMA(1, 0, At, B0); PG8_BAR; PG8_SCHED;
;       PG8_STAGE(PG8_SB(1, 1), b3 + hstepB, voffB);
;       PG8_WAIT_V(6); PG8_BAR; PG8_MMA(1, 1, At, B1); PG8_BAR;
;     }
;   __device__ __forceinline__ void operator()(const f32x4 (&acc)[2][2][4][2], const Unit& u, int wr, int wc, int fr, int fq) const {
;     const int mr = (u.pm * 256 < ML) ? ((u.pm * 256) >> 11) : 32;
;     const float* gp = mod + (size_t)mr * 6144 + gate_off;
	s_waitcnt lgkmcnt(0)
	v_mfma_f32_16x16x32_bf16 v[118:121], v[216:219], v[158:161], v[118:121]
	v_mfma_f32_16x16x32_bf16 v[114:117], v[224:227], v[158:161], v[114:117]
	v_mfma_f32_16x16x32_bf16 v[102:105], v[216:219], v[166:169], v[102:105]
	v_mfma_f32_16x16x32_bf16 v[98:101], v[224:227], v[166:169], v[98:101]
	v_mfma_f32_16x16x32_bf16 v[86:89], v[216:219], v[200:203], v[86:89]
	v_mfma_f32_16x16x32_bf16 v[82:85], v[224:227], v[200:203], v[82:85]
	v_mfma_f32_16x16x32_bf16 v[70:73], v[216:219], v[208:211], v[70:73]
	v_mfma_f32_16x16x32_bf16 v[66:69], v[224:227], v[208:211], v[66:69]
	v_mfma_f32_16x16x32_bf16 v[118:121], v[220:223], v[162:165], v[118:121]
	v_mfma_f32_16x16x32_bf16 v[114:117], v[228:231], v[162:165], v[114:117]
	v_mfma_f32_16x16x32_bf16 v[102:105], v[220:223], v[170:173], v[102:105]
	v_mfma_f32_16x16x32_bf16 v[98:101], v[228:231], v[170:173], v[98:101]
	v_mfma_f32_16x16x32_bf16 v[86:89], v[220:223], v[204:207], v[86:89]
	v_mfma_f32_16x16x32_bf16 v[82:85], v[228:231], v[204:207], v[82:85]
	v_mfma_f32_16x16x32_bf16 v[70:73], v[220:223], v[212:215], v[70:73]
	v_mfma_f32_16x16x32_bf16 v[66:69], v[228:231], v[212:215], v[66:69]
	s_mov_b32 m0, s28
	v_lshl_add_u64 v[174:175], v[184:185], 0, s[86:87]
	s_barrier
	ds_read_b128 v[158:161], v145 offset:49152
	ds_read_b128 v[162:165], v145 offset:50176
	ds_read_b128 v[166:169], v145 offset:51200
	ds_read_b128 v[170:173], v145 offset:52224
	ds_read_b128 v[200:203], v145 offset:53248
	ds_read_b128 v[204:207], v145 offset:54272
	ds_read_b128 v[208:211], v145 offset:55296
	ds_read_b128 v[212:215], v145 offset:56320
	global_load_lds_dwordx4 v[174:175], off
	v_lshl_add_u64 v[174:175], v[232:233], 0, s[86:87]
	s_mov_b32 m0, s29
	s_nop 0
	global_load_lds_dwordx4 v[174:175], off
	s_barrier
	s_waitcnt lgkmcnt(0)
	v_mfma_f32_16x16x32_bf16 v[62:65], v[140:143], v[158:161], v[62:65]
	v_mfma_f32_16x16x32_bf16 v[58:61], v[150:153], v[158:161], v[58:61]
	v_mfma_f32_16x16x32_bf16 v[46:49], v[140:143], v[166:169], v[46:49]
	v_mfma_f32_16x16x32_bf16 v[42:45], v[150:153], v[166:169], v[42:45]
	v_mfma_f32_16x16x32_bf16 v[30:33], v[140:143], v[200:203], v[30:33]
	v_mfma_f32_16x16x32_bf16 v[26:29], v[150:153], v[200:203], v[26:29]
	v_mfma_f32_16x16x32_bf16 v[14:17], v[140:143], v[208:211], v[14:17]
	v_mfma_f32_16x16x32_bf16 v[10:13], v[150:153], v[208:211], v[10:13]
	v_mfma_f32_16x16x32_bf16 v[62:65], v[146:149], v[162:165], v[62:65]
	v_mfma_f32_16x16x32_bf16 v[58:61], v[154:157], v[162:165], v[58:61]
	v_mfma_f32_16x16x32_bf16 v[46:49], v[146:149], v[170:173], v[46:49]
	v_mfma_f32_16x16x32_bf16 v[42:45], v[154:157], v[170:173], v[42:45]
	v_mfma_f32_16x16x32_bf16 v[30:33], v[146:149], v[204:207], v[30:33]
	v_mfma_f32_16x16x32_bf16 v[26:29], v[154:157], v[204:207], v[26:29]
	v_mfma_f32_16x16x32_bf16 v[14:17], v[146:149], v[212:215], v[14:17]
	v_mfma_f32_16x16x32_bf16 v[10:13], v[154:157], v[212:215], v[10:13]
	s_barrier
	s_add_u32 s10, s14, 0xb0080
	s_addc_u32 s11, s15, 0
	s_add_i32 s14, s16, s20
	v_lshl_add_u64 v[140:141], s[10:11], 0, v[134:135]
	s_mov_b32 m0, s14
	s_nop 0
	global_load_lds_dwordx4 v[140:141], off
	v_lshl_add_u64 v[140:141], s[10:11], 0, v[132:133]
	s_add_i32 m0, s14, 0x2000
	s_nop 0
	global_load_lds_dwordx4 v[140:141], off
	s_waitcnt vmcnt(6)
	s_barrier
	v_mfma_f32_16x16x32_bf16 v[54:57], v[216:219], v[158:161], v[54:57]
	v_mfma_f32_16x16x32_bf16 v[50:53], v[224:227], v[158:161], v[50:53]
	v_mfma_f32_16x16x32_bf16 v[38:41], v[216:219], v[166:169], v[38:41]
	v_mfma_f32_16x16x32_bf16 v[34:37], v[224:227], v[166:169], v[34:37]
	v_mfma_f32_16x16x32_bf16 v[22:25], v[216:219], v[200:203], v[22:25]
	v_mfma_f32_16x16x32_bf16 v[18:21], v[224:227], v[200:203], v[18:21]
	v_mfma_f32_16x16x32_bf16 v[6:9], v[216:219], v[208:211], v[6:9]
	v_mfma_f32_16x16x32_bf16 v[2:5], v[224:227], v[208:211], v[2:5]
	v_mfma_f32_16x16x32_bf16 v[54:57], v[220:223], v[162:165], v[54:57]
	v_mfma_f32_16x16x32_bf16 v[50:53], v[228:231], v[162:165], v[50:53]
	v_mfma_f32_16x16x32_bf16 v[38:41], v[220:223], v[170:173], v[38:41]
	v_mfma_f32_16x16x32_bf16 v[34:37], v[228:231], v[170:173], v[34:37]
	v_mfma_f32_16x16x32_bf16 v[22:25], v[220:223], v[204:207], v[22:25]
	v_mfma_f32_16x16x32_bf16 v[18:21], v[228:231], v[204:207], v[18:21]
	v_mfma_f32_16x16x32_bf16 v[6:9], v[220:223], v[212:215], v[6:9]
	v_mfma_f32_16x16x32_bf16 v[2:5], v[228:231], v[212:215], v[2:5]
	s_add_i32 s41, s41, 2
	s_add_u32 s39, s39, 0x100
	s_addc_u32 s40, s40, 0
	s_cmp_gt_u32 s41, 41
	s_mov_b64 s[10:11], s[12:13]
	s_barrier
	s_cbranch_scc0 .LBB0_1673
	s_cmpk_gt_i32 s37, 0xff
	s_mov_b64 s[10:11], 0x30000
	s_cbranch_scc1 .LBB0_1665
	s_ashr_i32 s10, s37, 3
	s_mul_hi_i32 s11, s10, 0x1800
	s_mulk_i32 s10, 0x1800
	s_branch .LBB0_1665
